# static-priority lever A/B: the per-phase s_setprio 1/0 flips in all GEMM K-loops replaced by s_nop (no user priority in GEMM phases); raise-per-half variants were slower
# speedup vs baseline: 1.0120x; 1.0005x over previous
; #define PG8_STAGE(bufoff, gbase, voff) do { _Pragma("unroll") for (int _i = 0; _i < 2; ++_i) \
;         __builtin_amdgcn_global_load_lds((const unsigned*)((const char*)(gbase) + (voff)[_i]), (PG8_LAS unsigned*)(lds + (bufoff) + ldsw + _i * 8192), 16, 0, 0); } while (0)
; #define PG8_LDA(dst, b, h) do { _Pragma("unroll") for (int m = 0; m < 4; ++m) _Pragma("unroll") for (int k = 0; k < 2; ++k) dst[m][k] = *(const PG8_LAS bf16x8*)(lds + PG8_SA(b, h) + aoff + m * 2048 + k * 1024); } while (0)
; #define PG8_LDB(dst, b, h) do { _Pragma("unroll") for (int n = 0; n < 2; ++n) _Pragma("unroll") for (int k = 0; k < 2; ++k) dst[n][k] = *(const PG8_LAS bf16x8*)(lds + PG8_SB(b, h) + boff + n * 2048 + k * 1024); } while (0)
; #define PG8_MMA(ai, bj, At, Bt) do { __builtin_amdgcn_s_setprio(1); _Pragma("unroll") for (int m = 0; m < 4; ++m) _Pragma("unroll") for (int n = 0; n < 2; ++n) _Pragma("unroll") for (int k = 0; k < 2; ++k) \
;         acc[ai][bj][m][n] = __builtin_amdgcn_mfma_f32_16x16x32_bf16(Bt[n][k], At[m][k], acc[ai][bj][m][n], 0, 0, 0); __builtin_amdgcn_s_setprio(0); } while (0)
; #define PG8_BAR __builtin_amdgcn_s_barrier()
; template <class Epi, class Sched, bool ALIGN_EPI = false, bool SP2 = false>
; __device__ __forceinline__ void gemm_phase(PG8_LAS unsigned char* lds, const Gemm g, const Sched& S, const Epi& E, const int wave_s) {
;     ...
;             PG8_LDB(B0, 0, 0); PG8_LDB(B1, 0, 1); PG8_SCHED; PG8_LDA(At, 0, 0); PG8_STAGE(PG8_SA(1, 1), a1 + hstepA, voffA);
;             PG8_WAIT_V(8); PG8_WAIT_L(0); PG8_BAR; PG8_MMA(0, 0, At, B0); PG8_MMA(0, 1, At, B1); PG8_BAR; PG8_SCHED;
;             PG8_LDA(At, 0, 1); PG8_STAGE(PG8_SB(0, 0), b2, voffB); PG8_STAGE(PG8_SB(0, 1), b2 + hstepB, voffB); PG8_STAGE(PG8_SA(0, 0), a2, voffA);
;             PG8_WAIT_V(8); PG8_WAIT_L(0); PG8_BAR; PG8_MMA(1, 0, At, B0); PG8_MMA(1, 1, At, B1); PG8_BAR; PG8_SCHED;
;             PG8_LDB(B0, 1, 0); PG8_LDB(B1, 1, 1); PG8_SCHED; PG8_LDA(At, 1, 0); PG8_STAGE(PG8_SA(0, 1), a2 + hstepA, voffA);
;             PG8_WAIT_V(8); PG8_WAIT_L(0); PG8_BAR; PG8_MMA(0, 0, At, B0); PG8_MMA(0, 1, At, B1); PG8_BAR; PG8_SCHED;
;             PG8_LDA(At, 1, 1); PG8_STAGE(PG8_SB(1, 0), b3, voffB); PG8_STAGE(PG8_SB(1, 1), b3 + hstepB, voffB); PG8_STAGE(PG8_SA(1, 0), a3, voffA);
;             PG8_WAIT_V(8); PG8_WAIT_L(0); PG8_BAR; PG8_MMA(1, 0, At, B0); PG8_MMA(1, 1, At, B1); PG8_BAR; PG8_SCHED;
.LBB0_422:
	s_add_u32 s4, s8, 0xfffc0800
	s_addc_u32 s5, s9, -1
	s_add_i32 s19, 0, 0x10000
	s_cmp_eq_u32 s18, 12
	s_cselect_b32 s15, s2, s5
	s_cselect_b32 s14, s3, s4
	v_add_u32_e32 v0, s19, v17
	s_cselect_b32 s5, s11, s17
	s_cselect_b32 s4, s13, s16
	s_add_i32 s35, 0, 0x14000
	ds_read_b128 v[86:89], v0
	ds_read_b128 v[90:93], v0 offset:1024
	ds_read_b128 v[152:155], v0 offset:2048
	ds_read_b128 v[156:159], v0 offset:3072
	v_add_u32_e32 v0, s35, v17
	ds_read_b128 v[160:163], v0
	ds_read_b128 v[164:167], v0 offset:1024
	ds_read_b128 v[168:171], v0 offset:2048
	ds_read_b128 v[172:175], v0 offset:3072
	v_lshl_add_u64 v[176:177], s[8:9], 0, v[150:151]
	s_add_i32 m0, s90, 0xc000
	ds_read_b128 v[194:197], v200
	ds_read_b128 v[202:205], v200 offset:1024
	ds_read_b128 v[206:209], v200 offset:2048
	ds_read_b128 v[210:213], v200 offset:3072
	ds_read_b128 v[214:217], v200 offset:4096
	ds_read_b128 v[228:231], v200 offset:5120
	ds_read_b128 v[232:235], v200 offset:6144
	ds_read_b128 v[236:239], v200 offset:7168
	global_load_lds_dwordx4 v[176:177], off
	v_lshl_add_u64 v[176:177], s[8:9], 0, v[148:149]
	s_add_i32 m0, s90, 0xe000
	s_nop 0
	global_load_lds_dwordx4 v[176:177], off
	s_waitcnt vmcnt(8)
	s_waitcnt lgkmcnt(0)
	s_barrier
	s_nop 0
	s_waitcnt lgkmcnt(0)
	v_mfma_f32_16x16x32_bf16 v[138:141], v[86:89], v[194:197], v[138:141]
	v_mfma_f32_16x16x32_bf16 v[134:137], v[152:155], v[194:197], v[134:137]
	v_mfma_f32_16x16x32_bf16 v[130:133], v[86:89], v[206:209], v[130:133]
	v_mfma_f32_16x16x32_bf16 v[126:129], v[152:155], v[206:209], v[126:129]
	v_mfma_f32_16x16x32_bf16 v[122:125], v[86:89], v[214:217], v[122:125]
	v_mfma_f32_16x16x32_bf16 v[118:121], v[152:155], v[214:217], v[118:121]
	v_mfma_f32_16x16x32_bf16 v[114:117], v[86:89], v[232:235], v[114:117]
	v_mfma_f32_16x16x32_bf16 v[110:113], v[152:155], v[232:235], v[110:113]
	v_mfma_f32_16x16x32_bf16 v[138:141], v[90:93], v[202:205], v[138:141]
	v_mfma_f32_16x16x32_bf16 v[134:137], v[156:159], v[202:205], v[134:137]
	v_mfma_f32_16x16x32_bf16 v[130:133], v[90:93], v[210:213], v[130:133]
	v_mfma_f32_16x16x32_bf16 v[126:129], v[156:159], v[210:213], v[126:129]
	v_mfma_f32_16x16x32_bf16 v[122:125], v[90:93], v[228:231], v[122:125]
	v_mfma_f32_16x16x32_bf16 v[118:121], v[156:159], v[228:231], v[118:121]
	v_mfma_f32_16x16x32_bf16 v[114:117], v[90:93], v[236:239], v[114:117]
	v_mfma_f32_16x16x32_bf16 v[110:113], v[156:159], v[236:239], v[110:113]
	s_nop 0
	s_nop 0
	v_mfma_f32_16x16x32_bf16 v[66:69], v[160:163], v[194:197], v[66:69]
	v_mfma_f32_16x16x32_bf16 v[62:65], v[168:171], v[194:197], v[62:65]
	v_mfma_f32_16x16x32_bf16 v[58:61], v[160:163], v[206:209], v[58:61]
	v_mfma_f32_16x16x32_bf16 v[54:57], v[168:171], v[206:209], v[54:57]
	v_mfma_f32_16x16x32_bf16 v[50:53], v[160:163], v[214:217], v[50:53]
	v_mfma_f32_16x16x32_bf16 v[46:49], v[168:171], v[214:217], v[46:49]
	v_mfma_f32_16x16x32_bf16 v[42:45], v[160:163], v[232:235], v[42:45]
	v_mfma_f32_16x16x32_bf16 v[38:41], v[168:171], v[232:235], v[38:41]
	v_mfma_f32_16x16x32_bf16 v[66:69], v[164:167], v[202:205], v[66:69]
	v_mfma_f32_16x16x32_bf16 v[62:65], v[172:175], v[202:205], v[62:65]
	v_mfma_f32_16x16x32_bf16 v[58:61], v[164:167], v[210:213], v[58:61]
	v_mfma_f32_16x16x32_bf16 v[54:57], v[172:175], v[210:213], v[54:57]
	v_mfma_f32_16x16x32_bf16 v[50:53], v[164:167], v[228:231], v[50:53]
	v_mfma_f32_16x16x32_bf16 v[46:49], v[172:175], v[228:231], v[46:49]
	v_mfma_f32_16x16x32_bf16 v[42:45], v[164:167], v[236:239], v[42:45]
	v_mfma_f32_16x16x32_bf16 v[38:41], v[172:175], v[236:239], v[38:41]
	s_nop 0
	s_barrier
	s_add_i32 s19, s19, s52
	v_lshl_add_u64 v[176:177], s[4:5], 0, v[142:143]
	s_mov_b32 m0, s19
	ds_read_b128 v[194:197], v200 offset:16384
	ds_read_b128 v[202:205], v200 offset:17408
	ds_read_b128 v[206:209], v200 offset:18432
	ds_read_b128 v[210:213], v200 offset:19456
	ds_read_b128 v[214:217], v200 offset:20480
	ds_read_b128 v[228:231], v200 offset:21504
	ds_read_b128 v[232:235], v200 offset:22528
	ds_read_b128 v[236:239], v200 offset:23552
	global_load_lds_dwordx4 v[176:177], off
	s_add_i32 m0, s19, 0x2000
	s_add_u32 s40, s4, 0x40000
	v_lshl_add_u64 v[178:179], s[4:5], 0, v[146:147]
	s_addc_u32 s41, s5, 0
	s_add_i32 s19, s35, s52
	global_load_lds_dwordx4 v[178:179], off
	v_lshl_add_u64 v[180:181], s[40:41], 0, v[142:143]
	s_mov_b32 m0, s19
	v_lshl_add_u64 v[182:183], s[14:15], 0, v[144:145]
	global_load_lds_dwordx4 v[180:181], off
	v_lshl_add_u64 v[180:181], s[40:41], 0, v[146:147]
	s_add_i32 m0, s19, 0x2000
	s_nop 0
	global_load_lds_dwordx4 v[180:181], off
	v_lshl_add_u64 v[180:181], s[14:15], 0, v[14:15]
	s_mov_b32 m0, s90
	s_nop 0
	global_load_lds_dwordx4 v[180:181], off
	s_mov_b32 m0, s91
	s_nop 0
	global_load_lds_dwordx4 v[182:183], off
	s_waitcnt vmcnt(8)
	s_waitcnt lgkmcnt(0)
	s_barrier
; #define PG8_STAGE(bufoff, gbase, voff) do { _Pragma("unroll") for (int _i = 0; _i < 2; ++_i) \
;         __builtin_amdgcn_global_load_lds((const unsigned*)((const char*)(gbase) + (voff)[_i]), (PG8_LAS unsigned*)(lds + (bufoff) + ldsw + _i * 8192), 16, 0, 0); } while (0)
; #define PG8_LDA(dst, b, h) do { _Pragma("unroll") for (int m = 0; m < 4; ++m) _Pragma("unroll") for (int k = 0; k < 2; ++k) dst[m][k] = *(const PG8_LAS bf16x8*)(lds + PG8_SA(b, h) + aoff + m * 2048 + k * 1024); } while (0)
; #define PG8_LDB(dst, b, h) do { _Pragma("unroll") for (int n = 0; n < 2; ++n) _Pragma("unroll") for (int k = 0; k < 2; ++k) dst[n][k] = *(const PG8_LAS bf16x8*)(lds + PG8_SB(b, h) + boff + n * 2048 + k * 1024); } while (0)
; #define PG8_MMA(ai, bj, At, Bt) do { __builtin_amdgcn_s_setprio(1); _Pragma("unroll") for (int m = 0; m < 4; ++m) _Pragma("unroll") for (int n = 0; n < 2; ++n) _Pragma("unroll") for (int k = 0; k < 2; ++k) \
;         acc[ai][bj][m][n] = __builtin_amdgcn_mfma_f32_16x16x32_bf16(Bt[n][k], At[m][k], acc[ai][bj][m][n], 0, 0, 0); __builtin_amdgcn_s_setprio(0); } while (0)
; #define PG8_BAR __builtin_amdgcn_s_barrier()
; template <class Epi, class Sched, bool ALIGN_EPI = false, bool SP2 = false>
; __device__ __forceinline__ void gemm_phase(PG8_LAS unsigned char* lds, const Gemm g, const Sched& S, const Epi& E, const int wave_s) {
;     ...
;             PG8_LDB(B0, 0, 0); PG8_LDB(B1, 0, 1); PG8_SCHED; PG8_LDA(At, 0, 0); PG8_STAGE(PG8_SA(1, 1), a1 + hstepA, voffA);
;             PG8_WAIT_V(8); PG8_WAIT_L(0); PG8_BAR; PG8_MMA(0, 0, At, B0); PG8_MMA(0, 1, At, B1); PG8_BAR; PG8_SCHED;
;             PG8_LDA(At, 0, 1); PG8_STAGE(PG8_SB(0, 0), b2, voffB); PG8_STAGE(PG8_SB(0, 1), b2 + hstepB, voffB); PG8_STAGE(PG8_SA(0, 0), a2, voffA);
;             PG8_WAIT_V(8); PG8_WAIT_L(0); PG8_BAR; PG8_MMA(1, 0, At, B0); PG8_MMA(1, 1, At, B1); PG8_BAR; PG8_SCHED;
;             PG8_LDB(B0, 1, 0); PG8_LDB(B1, 1, 1); PG8_SCHED; PG8_LDA(At, 1, 0); PG8_STAGE(PG8_SA(0, 1), a2 + hstepA, voffA);
;             PG8_WAIT_V(8); PG8_WAIT_L(0); PG8_BAR; PG8_MMA(0, 0, At, B0); PG8_MMA(0, 1, At, B1); PG8_BAR; PG8_SCHED;
;             PG8_LDA(At, 1, 1); PG8_STAGE(PG8_SB(1, 0), b3, voffB); PG8_STAGE(PG8_SB(1, 1), b3 + hstepB, voffB); PG8_STAGE(PG8_SA(1, 0), a3, voffA);
;             PG8_WAIT_V(8); PG8_WAIT_L(0); PG8_BAR; PG8_MMA(1, 0, At, B0); PG8_MMA(1, 1, At, B1); PG8_BAR; PG8_SCHED;
	s_nop 0
	s_waitcnt lgkmcnt(0)
	v_mfma_f32_16x16x32_bf16 v[106:109], v[86:89], v[194:197], v[106:109]
	v_mfma_f32_16x16x32_bf16 v[102:105], v[152:155], v[194:197], v[102:105]
	v_mfma_f32_16x16x32_bf16 v[98:101], v[86:89], v[206:209], v[98:101]
	v_mfma_f32_16x16x32_bf16 v[94:97], v[152:155], v[206:209], v[94:97]
	v_mfma_f32_16x16x32_bf16 v[82:85], v[86:89], v[214:217], v[82:85]
	v_mfma_f32_16x16x32_bf16 v[78:81], v[152:155], v[214:217], v[78:81]
	v_mfma_f32_16x16x32_bf16 v[74:77], v[86:89], v[232:235], v[74:77]
	v_mfma_f32_16x16x32_bf16 v[70:73], v[152:155], v[232:235], v[70:73]
	v_mfma_f32_16x16x32_bf16 v[106:109], v[90:93], v[202:205], v[106:109]
	v_mfma_f32_16x16x32_bf16 v[102:105], v[156:159], v[202:205], v[102:105]
	v_mfma_f32_16x16x32_bf16 v[98:101], v[90:93], v[210:213], v[98:101]
	v_mfma_f32_16x16x32_bf16 v[94:97], v[156:159], v[210:213], v[94:97]
	v_mfma_f32_16x16x32_bf16 v[82:85], v[90:93], v[228:231], v[82:85]
	v_mfma_f32_16x16x32_bf16 v[78:81], v[156:159], v[228:231], v[78:81]
	v_mfma_f32_16x16x32_bf16 v[74:77], v[90:93], v[236:239], v[74:77]
	v_mfma_f32_16x16x32_bf16 v[70:73], v[156:159], v[236:239], v[70:73]
	s_nop 0
	s_nop 0
	v_mfma_f32_16x16x32_bf16 v[34:37], v[160:163], v[194:197], v[34:37]
	v_mfma_f32_16x16x32_bf16 v[30:33], v[168:171], v[194:197], v[30:33]
	v_mfma_f32_16x16x32_bf16 v[26:29], v[160:163], v[206:209], v[26:29]
	v_mfma_f32_16x16x32_bf16 v[22:25], v[168:171], v[206:209], v[22:25]
	v_mfma_f32_16x16x32_bf16 v[18:21], v[160:163], v[214:217], v[18:21]
	v_mfma_f32_16x16x32_bf16 v[10:13], v[168:171], v[214:217], v[10:13]
	v_mfma_f32_16x16x32_bf16 v[6:9], v[160:163], v[232:235], v[6:9]
	v_mfma_f32_16x16x32_bf16 v[2:5], v[168:171], v[232:235], v[2:5]
	v_mfma_f32_16x16x32_bf16 v[34:37], v[164:167], v[202:205], v[34:37]
	v_mfma_f32_16x16x32_bf16 v[30:33], v[172:175], v[202:205], v[30:33]
	v_mfma_f32_16x16x32_bf16 v[26:29], v[164:167], v[210:213], v[26:29]
	v_mfma_f32_16x16x32_bf16 v[22:25], v[172:175], v[210:213], v[22:25]
	v_mfma_f32_16x16x32_bf16 v[18:21], v[164:167], v[228:231], v[18:21]
	v_mfma_f32_16x16x32_bf16 v[10:13], v[172:175], v[228:231], v[10:13]
	v_mfma_f32_16x16x32_bf16 v[6:9], v[164:167], v[236:239], v[6:9]
	v_mfma_f32_16x16x32_bf16 v[2:5], v[172:175], v[236:239], v[2:5]
	s_nop 0
	s_barrier
	s_add_i32 s19, 0, 0x18000
	v_add_u32_e32 v0, s19, v17
	s_add_i32 s35, 0, 0x1c000
	ds_read_b128 v[86:89], v0
	ds_read_b128 v[90:93], v0 offset:1024
	ds_read_b128 v[152:155], v0 offset:2048
	ds_read_b128 v[156:159], v0 offset:3072
	v_add_u32_e32 v0, s35, v17
	ds_read_b128 v[160:163], v0
	ds_read_b128 v[164:167], v0 offset:1024
	ds_read_b128 v[168:171], v0 offset:2048
	ds_read_b128 v[172:175], v0 offset:3072
	s_add_u32 s14, s14, 0x40000
	s_addc_u32 s15, s15, 0
	s_mov_b32 m0, s92
	v_lshl_add_u64 v[184:185], s[14:15], 0, v[14:15]
	ds_read_b128 v[194:197], v200 offset:32768
	ds_read_b128 v[202:205], v200 offset:33792
	ds_read_b128 v[206:209], v200 offset:34816
	ds_read_b128 v[210:213], v200 offset:35840
	ds_read_b128 v[214:217], v200 offset:36864
	ds_read_b128 v[228:231], v200 offset:37888
	ds_read_b128 v[232:235], v200 offset:38912
	ds_read_b128 v[236:239], v200 offset:39936
	global_load_lds_dwordx4 v[184:185], off
	v_lshl_add_u64 v[184:185], s[14:15], 0, v[144:145]
	s_mov_b32 m0, s93
	s_nop 0
	global_load_lds_dwordx4 v[184:185], off
	s_waitcnt vmcnt(8)
	s_waitcnt lgkmcnt(0)
	s_barrier
	s_nop 0
	s_waitcnt lgkmcnt(0)
	v_mfma_f32_16x16x32_bf16 v[138:141], v[86:89], v[194:197], v[138:141]
	v_mfma_f32_16x16x32_bf16 v[134:137], v[152:155], v[194:197], v[134:137]
	v_mfma_f32_16x16x32_bf16 v[130:133], v[86:89], v[206:209], v[130:133]
	v_mfma_f32_16x16x32_bf16 v[126:129], v[152:155], v[206:209], v[126:129]
	v_mfma_f32_16x16x32_bf16 v[122:125], v[86:89], v[214:217], v[122:125]
	v_mfma_f32_16x16x32_bf16 v[118:121], v[152:155], v[214:217], v[118:121]
	v_mfma_f32_16x16x32_bf16 v[114:117], v[86:89], v[232:235], v[114:117]
	v_mfma_f32_16x16x32_bf16 v[110:113], v[152:155], v[232:235], v[110:113]
	v_mfma_f32_16x16x32_bf16 v[138:141], v[90:93], v[202:205], v[138:141]
	v_mfma_f32_16x16x32_bf16 v[134:137], v[156:159], v[202:205], v[134:137]
	v_mfma_f32_16x16x32_bf16 v[130:133], v[90:93], v[210:213], v[130:133]
	v_mfma_f32_16x16x32_bf16 v[126:129], v[156:159], v[210:213], v[126:129]
	v_mfma_f32_16x16x32_bf16 v[122:125], v[90:93], v[228:231], v[122:125]
	v_mfma_f32_16x16x32_bf16 v[118:121], v[156:159], v[228:231], v[118:121]
	v_mfma_f32_16x16x32_bf16 v[114:117], v[90:93], v[236:239], v[114:117]
	v_mfma_f32_16x16x32_bf16 v[110:113], v[156:159], v[236:239], v[110:113]
	s_nop 0
	s_nop 0
	v_mfma_f32_16x16x32_bf16 v[66:69], v[160:163], v[194:197], v[66:69]
	v_mfma_f32_16x16x32_bf16 v[62:65], v[168:171], v[194:197], v[62:65]
	v_mfma_f32_16x16x32_bf16 v[58:61], v[160:163], v[206:209], v[58:61]
	v_mfma_f32_16x16x32_bf16 v[54:57], v[168:171], v[206:209], v[54:57]
	v_mfma_f32_16x16x32_bf16 v[50:53], v[160:163], v[214:217], v[50:53]
	v_mfma_f32_16x16x32_bf16 v[46:49], v[168:171], v[214:217], v[46:49]
	v_mfma_f32_16x16x32_bf16 v[42:45], v[160:163], v[232:235], v[42:45]
	v_mfma_f32_16x16x32_bf16 v[38:41], v[168:171], v[232:235], v[38:41]
	v_mfma_f32_16x16x32_bf16 v[66:69], v[164:167], v[202:205], v[66:69]
	v_mfma_f32_16x16x32_bf16 v[62:65], v[172:175], v[202:205], v[62:65]
	v_mfma_f32_16x16x32_bf16 v[58:61], v[164:167], v[210:213], v[58:61]
	v_mfma_f32_16x16x32_bf16 v[54:57], v[172:175], v[210:213], v[54:57]
	v_mfma_f32_16x16x32_bf16 v[50:53], v[164:167], v[228:231], v[50:53]
	v_mfma_f32_16x16x32_bf16 v[46:49], v[172:175], v[228:231], v[46:49]
	v_mfma_f32_16x16x32_bf16 v[42:45], v[164:167], v[236:239], v[42:45]
	v_mfma_f32_16x16x32_bf16 v[38:41], v[172:175], v[236:239], v[38:41]
	s_nop 0
	s_barrier
; #define PG8_STAGE(bufoff, gbase, voff) do { _Pragma("unroll") for (int _i = 0; _i < 2; ++_i) \
;         __builtin_amdgcn_global_load_lds((const unsigned*)((const char*)(gbase) + (voff)[_i]), (PG8_LAS unsigned*)(lds + (bufoff) + ldsw + _i * 8192), 16, 0, 0); } while (0)
; #define PG8_LDA(dst, b, h) do { _Pragma("unroll") for (int m = 0; m < 4; ++m) _Pragma("unroll") for (int k = 0; k < 2; ++k) dst[m][k] = *(const PG8_LAS bf16x8*)(lds + PG8_SA(b, h) + aoff + m * 2048 + k * 1024); } while (0)
; #define PG8_LDB(dst, b, h) do { _Pragma("unroll") for (int n = 0; n < 2; ++n) _Pragma("unroll") for (int k = 0; k < 2; ++k) dst[n][k] = *(const PG8_LAS bf16x8*)(lds + PG8_SB(b, h) + boff + n * 2048 + k * 1024); } while (0)
; #define PG8_MMA(ai, bj, At, Bt) do { __builtin_amdgcn_s_setprio(1); _Pragma("unroll") for (int m = 0; m < 4; ++m) _Pragma("unroll") for (int n = 0; n < 2; ++n) _Pragma("unroll") for (int k = 0; k < 2; ++k) \
;         acc[ai][bj][m][n] = __builtin_amdgcn_mfma_f32_16x16x32_bf16(Bt[n][k], At[m][k], acc[ai][bj][m][n], 0, 0, 0); __builtin_amdgcn_s_setprio(0); } while (0)
; #define PG8_BAR __builtin_amdgcn_s_barrier()
; template <class Epi, class Sched, bool ALIGN_EPI = false, bool SP2 = false>
; __device__ __forceinline__ void gemm_phase(PG8_LAS unsigned char* lds, const Gemm g, const Sched& S, const Epi& E, const int wave_s) {
;     ...
;             PG8_LDB(B0, 0, 0); PG8_LDB(B1, 0, 1); PG8_SCHED; PG8_LDA(At, 0, 0); PG8_STAGE(PG8_SA(1, 1), a1 + hstepA, voffA);
;             PG8_WAIT_V(8); PG8_WAIT_L(0); PG8_BAR; PG8_MMA(0, 0, At, B0); PG8_MMA(0, 1, At, B1); PG8_BAR; PG8_SCHED;
;             PG8_LDA(At, 0, 1); PG8_STAGE(PG8_SB(0, 0), b2, voffB); PG8_STAGE(PG8_SB(0, 1), b2 + hstepB, voffB); PG8_STAGE(PG8_SA(0, 0), a2, voffA);
;             PG8_WAIT_V(8); PG8_WAIT_L(0); PG8_BAR; PG8_MMA(1, 0, At, B0); PG8_MMA(1, 1, At, B1); PG8_BAR; PG8_SCHED;
;             PG8_LDB(B0, 1, 0); PG8_LDB(B1, 1, 1); PG8_SCHED; PG8_LDA(At, 1, 0); PG8_STAGE(PG8_SA(0, 1), a2 + hstepA, voffA);
;             PG8_WAIT_V(8); PG8_WAIT_L(0); PG8_BAR; PG8_MMA(0, 0, At, B0); PG8_MMA(0, 1, At, B1); PG8_BAR; PG8_SCHED;
;             PG8_LDA(At, 1, 1); PG8_STAGE(PG8_SB(1, 0), b3, voffB); PG8_STAGE(PG8_SB(1, 1), b3 + hstepB, voffB); PG8_STAGE(PG8_SA(1, 0), a3, voffA);
;             PG8_WAIT_V(8); PG8_WAIT_L(0); PG8_BAR; PG8_MMA(1, 0, At, B0); PG8_MMA(1, 1, At, B1); PG8_BAR; PG8_SCHED;
	s_add_i32 s14, s19, s52
	v_lshl_add_u64 v[176:177], v[176:177], 0, s[58:59]
	s_mov_b32 m0, s14
	ds_read_b128 v[194:197], v200 offset:49152
	ds_read_b128 v[202:205], v200 offset:50176
	ds_read_b128 v[206:209], v200 offset:51200
	ds_read_b128 v[210:213], v200 offset:52224
	ds_read_b128 v[214:217], v200 offset:53248
	ds_read_b128 v[228:231], v200 offset:54272
	ds_read_b128 v[232:235], v200 offset:55296
	ds_read_b128 v[236:239], v200 offset:56320
	global_load_lds_dwordx4 v[176:177], off
	s_add_i32 m0, s14, 0x2000
	s_add_u32 s4, s4, 0x40080
	v_lshl_add_u64 v[176:177], v[178:179], 0, s[58:59]
	s_addc_u32 s5, s5, 0
	s_add_i32 s14, s35, s52
	global_load_lds_dwordx4 v[176:177], off
	v_lshl_add_u64 v[176:177], s[4:5], 0, v[142:143]
	s_mov_b32 m0, s14
	s_nop 0
	global_load_lds_dwordx4 v[176:177], off
	v_lshl_add_u64 v[176:177], s[4:5], 0, v[146:147]
	s_add_i32 m0, s14, 0x2000
	s_nop 0
	global_load_lds_dwordx4 v[176:177], off
	v_lshl_add_u64 v[176:177], v[180:181], 0, v[248:249]
	s_mov_b32 m0, s20
	s_nop 0
	global_load_lds_dwordx4 v[176:177], off
	v_lshl_add_u64 v[176:177], v[182:183], 0, v[248:249]
	s_mov_b32 m0, s21
	s_nop 0
	global_load_lds_dwordx4 v[176:177], off
	s_waitcnt vmcnt(8)
	s_waitcnt lgkmcnt(0)
	s_barrier
	s_nop 0
	s_waitcnt lgkmcnt(0)
	v_mfma_f32_16x16x32_bf16 v[106:109], v[86:89], v[194:197], v[106:109]
	v_mfma_f32_16x16x32_bf16 v[102:105], v[152:155], v[194:197], v[102:105]
	v_mfma_f32_16x16x32_bf16 v[98:101], v[86:89], v[206:209], v[98:101]
	v_mfma_f32_16x16x32_bf16 v[94:97], v[152:155], v[206:209], v[94:97]
	v_mfma_f32_16x16x32_bf16 v[82:85], v[86:89], v[214:217], v[82:85]
	v_mfma_f32_16x16x32_bf16 v[78:81], v[152:155], v[214:217], v[78:81]
	v_mfma_f32_16x16x32_bf16 v[74:77], v[86:89], v[232:235], v[74:77]
	v_mfma_f32_16x16x32_bf16 v[70:73], v[152:155], v[232:235], v[70:73]
	v_mfma_f32_16x16x32_bf16 v[106:109], v[90:93], v[202:205], v[106:109]
	v_mfma_f32_16x16x32_bf16 v[102:105], v[156:159], v[202:205], v[102:105]
	v_mfma_f32_16x16x32_bf16 v[98:101], v[90:93], v[210:213], v[98:101]
	v_mfma_f32_16x16x32_bf16 v[94:97], v[156:159], v[210:213], v[94:97]
	v_mfma_f32_16x16x32_bf16 v[82:85], v[90:93], v[228:231], v[82:85]
	v_mfma_f32_16x16x32_bf16 v[78:81], v[156:159], v[228:231], v[78:81]
	v_mfma_f32_16x16x32_bf16 v[74:77], v[90:93], v[236:239], v[74:77]
	v_mfma_f32_16x16x32_bf16 v[70:73], v[156:159], v[236:239], v[70:73]
	s_nop 0
	s_nop 0
	v_mfma_f32_16x16x32_bf16 v[34:37], v[160:163], v[194:197], v[34:37]
	v_mfma_f32_16x16x32_bf16 v[30:33], v[168:171], v[194:197], v[30:33]
	v_mfma_f32_16x16x32_bf16 v[26:29], v[160:163], v[206:209], v[26:29]
	v_mfma_f32_16x16x32_bf16 v[22:25], v[168:171], v[206:209], v[22:25]
	v_mfma_f32_16x16x32_bf16 v[18:21], v[160:163], v[214:217], v[18:21]
	v_mfma_f32_16x16x32_bf16 v[10:13], v[168:171], v[214:217], v[10:13]
	v_mfma_f32_16x16x32_bf16 v[6:9], v[160:163], v[232:235], v[6:9]
	v_mfma_f32_16x16x32_bf16 v[2:5], v[168:171], v[232:235], v[2:5]
	v_mfma_f32_16x16x32_bf16 v[34:37], v[164:167], v[202:205], v[34:37]
	v_mfma_f32_16x16x32_bf16 v[30:33], v[172:175], v[202:205], v[30:33]
	v_mfma_f32_16x16x32_bf16 v[26:29], v[164:167], v[210:213], v[26:29]
	v_mfma_f32_16x16x32_bf16 v[22:25], v[172:175], v[210:213], v[22:25]
	v_mfma_f32_16x16x32_bf16 v[18:21], v[164:167], v[228:231], v[18:21]
	v_mfma_f32_16x16x32_bf16 v[10:13], v[172:175], v[228:231], v[10:13]
	v_mfma_f32_16x16x32_bf16 v[6:9], v[164:167], v[236:239], v[6:9]
	v_mfma_f32_16x16x32_bf16 v[2:5], v[172:175], v[236:239], v[2:5]
	s_nop 0
	s_barrier
	s_add_i32 s18, s18, 2
	s_add_u32 s16, s16, 0x100
	s_addc_u32 s17, s17, 0
	s_add_u32 s8, s8, 0x1000
	s_addc_u32 s9, s9, 0
	s_cmp_gt_u32 s18, 13
	s_cbranch_scc0 .LBB0_422
	s_and_b64 vcc, exec, s[30:31]
	s_cbranch_vccz .LBB0_425
	s_barrier

; #define PG8_STAGE(bufoff, gbase, voff) do { _Pragma("unroll") for (int _i = 0; _i < 2; ++_i) \
;         __builtin_amdgcn_global_load_lds((const unsigned*)((const char*)(gbase) + (voff)[_i]), (PG8_LAS unsigned*)(lds + (bufoff) + ldsw + _i * 8192), 16, 0, 0); } while (0)
; #define PG8_LDA(dst, b, h) do { _Pragma("unroll") for (int m = 0; m < 4; ++m) _Pragma("unroll") for (int k = 0; k < 2; ++k) dst[m][k] = *(const PG8_LAS bf16x8*)(lds + PG8_SA(b, h) + aoff + m * 2048 + k * 1024); } while (0)
; #define PG8_LDB(dst, b, h) do { _Pragma("unroll") for (int n = 0; n < 2; ++n) _Pragma("unroll") for (int k = 0; k < 2; ++k) dst[n][k] = *(const PG8_LAS bf16x8*)(lds + PG8_SB(b, h) + boff + n * 2048 + k * 1024); } while (0)
; #define PG8_MMA(ai, bj, At, Bt) do { __builtin_amdgcn_s_setprio(1); _Pragma("unroll") for (int m = 0; m < 4; ++m) _Pragma("unroll") for (int n = 0; n < 2; ++n) _Pragma("unroll") for (int k = 0; k < 2; ++k) \
;         acc[ai][bj][m][n] = __builtin_amdgcn_mfma_f32_16x16x32_bf16(Bt[n][k], At[m][k], acc[ai][bj][m][n], 0, 0, 0); __builtin_amdgcn_s_setprio(0); } while (0)
; #define PG8_BAR __builtin_amdgcn_s_barrier()
; template <class Epi, class Sched, bool ALIGN_EPI = false, bool SP2 = false>
; __device__ __forceinline__ void gemm_phase(PG8_LAS unsigned char* lds, const Gemm g, const Sched& S, const Epi& E, const int wave_s) {
;     ...
;             PG8_LDB(B0, 0, 0); PG8_LDB(B1, 0, 1); PG8_SCHED; PG8_LDA(At, 0, 0); PG8_STAGE(PG8_SA(1, 1), a1 + hstepA, voffA);
;             PG8_WAIT_V(8); PG8_WAIT_L(0); PG8_BAR; PG8_MMA(0, 0, At, B0); PG8_MMA(0, 1, At, B1); PG8_BAR; PG8_SCHED;
;             PG8_LDA(At, 0, 1); PG8_STAGE(PG8_SB(0, 0), b2, voffB); PG8_STAGE(PG8_SB(0, 1), b2 + hstepB, voffB); PG8_STAGE(PG8_SA(0, 0), a2, voffA);
;             PG8_WAIT_V(8); PG8_WAIT_L(0); PG8_BAR; PG8_MMA(1, 0, At, B0); PG8_MMA(1, 1, At, B1); PG8_BAR; PG8_SCHED;
;             PG8_LDB(B0, 1, 0); PG8_LDB(B1, 1, 1); PG8_SCHED; PG8_LDA(At, 1, 0); PG8_STAGE(PG8_SA(0, 1), a2 + hstepA, voffA);
;             PG8_WAIT_V(8); PG8_WAIT_L(0); PG8_BAR; PG8_MMA(0, 0, At, B0); PG8_MMA(0, 1, At, B1); PG8_BAR; PG8_SCHED;
;             PG8_LDA(At, 1, 1); PG8_STAGE(PG8_SB(1, 0), b3, voffB); PG8_STAGE(PG8_SB(1, 1), b3 + hstepB, voffB); PG8_STAGE(PG8_SA(1, 0), a3, voffA);
;             PG8_WAIT_V(8); PG8_WAIT_L(0); PG8_BAR; PG8_MMA(1, 0, At, B0); PG8_MMA(1, 1, At, B1); PG8_BAR; PG8_SCHED;
.LBB0_711:
	s_add_i32 s49, 0, 0x10000
	s_add_i32 s8, 0, 0x14000
	v_add_u32_e32 v0, s49, v17
	v_add_u32_e32 v10, s8, v17
	ds_read_b128 v[18:21], v0
	ds_read_b128 v[22:25], v0 offset:1024
	ds_read_b128 v[26:29], v0 offset:2048
	ds_read_b128 v[30:33], v0 offset:3072
	ds_read_b128 v[34:37], v10
	ds_read_b128 v[38:41], v10 offset:1024
	ds_read_b128 v[42:45], v10 offset:2048
	ds_read_b128 v[46:49], v10 offset:3072
	s_add_u32 s2, s10, 0x84080
	s_addc_u32 s3, s11, 0
	s_add_i32 s52, s41, 0xc000
	v_lshl_add_u64 v[12:13], s[2:3], 0, v[14:15]
	s_mov_b32 m0, s52
	ds_read_b128 v[2:5], v164
	ds_read_b128 v[6:9], v164 offset:1024
	ds_read_b128 v[50:53], v164 offset:2048
	ds_read_b128 v[54:57], v164 offset:3072
	ds_read_b128 v[58:61], v164 offset:4096
	ds_read_b128 v[62:65], v164 offset:5120
	ds_read_b128 v[66:69], v164 offset:6144
	ds_read_b128 v[70:73], v164 offset:7168
	global_load_lds_dwordx4 v[12:13], off
	v_lshl_add_u64 v[12:13], s[2:3], 0, v[136:137]
	s_add_i32 s2, s41, 0xe000
	s_mov_b32 m0, s2
	s_nop 0
	global_load_lds_dwordx4 v[12:13], off
	s_waitcnt vmcnt(8)
	s_waitcnt lgkmcnt(0)
	s_barrier
	s_nop 0
	s_waitcnt lgkmcnt(0)
	v_mfma_f32_16x16x32_bf16 v[74:77], v[18:21], v[2:5], 0
	v_mfma_f32_16x16x32_bf16 v[78:81], v[26:29], v[2:5], 0
	v_mfma_f32_16x16x32_bf16 v[82:85], v[18:21], v[50:53], 0
	v_mfma_f32_16x16x32_bf16 v[86:89], v[26:29], v[50:53], 0
	v_mfma_f32_16x16x32_bf16 v[90:93], v[18:21], v[58:61], 0
	v_mfma_f32_16x16x32_bf16 v[94:97], v[26:29], v[58:61], 0
	v_mfma_f32_16x16x32_bf16 v[98:101], v[18:21], v[66:69], 0
	v_mfma_f32_16x16x32_bf16 v[102:105], v[26:29], v[66:69], 0
	v_mfma_f32_16x16x32_bf16 v[74:77], v[22:25], v[6:9], v[74:77]
	v_mfma_f32_16x16x32_bf16 v[78:81], v[30:33], v[6:9], v[78:81]
	v_mfma_f32_16x16x32_bf16 v[82:85], v[22:25], v[54:57], v[82:85]
	v_mfma_f32_16x16x32_bf16 v[86:89], v[30:33], v[54:57], v[86:89]
	v_mfma_f32_16x16x32_bf16 v[90:93], v[22:25], v[62:65], v[90:93]
	v_mfma_f32_16x16x32_bf16 v[94:97], v[30:33], v[62:65], v[94:97]
	v_mfma_f32_16x16x32_bf16 v[98:101], v[22:25], v[70:73], v[98:101]
	v_mfma_f32_16x16x32_bf16 v[102:105], v[30:33], v[70:73], v[102:105]
	s_nop 0
	s_nop 0
	v_mfma_f32_16x16x32_bf16 v[106:109], v[34:37], v[2:5], 0
	v_mfma_f32_16x16x32_bf16 v[2:5], v[42:45], v[2:5], 0
	v_mfma_f32_16x16x32_bf16 v[110:113], v[46:49], v[6:9], v[2:5]
	v_mfma_f32_16x16x32_bf16 v[2:5], v[34:37], v[50:53], 0
	v_mfma_f32_16x16x32_bf16 v[114:117], v[38:41], v[54:57], v[2:5]
	v_mfma_f32_16x16x32_bf16 v[2:5], v[42:45], v[50:53], 0
	v_mfma_f32_16x16x32_bf16 v[50:53], v[46:49], v[54:57], v[2:5]
	v_mfma_f32_16x16x32_bf16 v[2:5], v[34:37], v[58:61], 0
	v_mfma_f32_16x16x32_bf16 v[54:57], v[38:41], v[62:65], v[2:5]
	v_mfma_f32_16x16x32_bf16 v[2:5], v[42:45], v[58:61], 0
	v_mfma_f32_16x16x32_bf16 v[58:61], v[46:49], v[62:65], v[2:5]
	v_mfma_f32_16x16x32_bf16 v[2:5], v[34:37], v[66:69], 0
	v_mfma_f32_16x16x32_bf16 v[62:65], v[38:41], v[70:73], v[2:5]
	v_mfma_f32_16x16x32_bf16 v[2:5], v[42:45], v[66:69], 0
	v_mfma_f32_16x16x32_bf16 v[106:109], v[38:41], v[6:9], v[106:109]
	v_mfma_f32_16x16x32_bf16 v[66:69], v[46:49], v[70:73], v[2:5]
	s_nop 0
	s_barrier
	s_nop 3
	v_lshl_add_u64 v[2:3], s[12:13], 0, v[134:135]
	s_add_i32 s49, s49, s40
	v_lshl_add_u64 v[4:5], v[2:3], 0, s[60:61]
	s_mov_b32 m0, s49
	s_add_i32 s3, s49, 0x2000
	ds_read_b128 v[70:73], v164 offset:16384
	ds_read_b128 v[118:121], v164 offset:17408
	ds_read_b128 v[122:125], v164 offset:18432
	ds_read_b128 v[126:129], v164 offset:19456
	ds_read_b128 v[130:133], v164 offset:20480
	ds_read_b128 v[140:143], v164 offset:21504
	ds_read_b128 v[144:147], v164 offset:22528
	ds_read_b128 v[148:151], v164 offset:23552
	global_load_lds_dwordx4 v[4:5], off
	v_lshl_add_u64 v[4:5], s[12:13], 0, v[138:139]
	s_add_u32 s50, s12, 0x18100
	v_lshl_add_u64 v[6:7], v[4:5], 0, s[60:61]
	s_mov_b32 m0, s3
	s_addc_u32 s51, s13, 0
	s_add_i32 s8, s8, s40
	global_load_lds_dwordx4 v[6:7], off
	v_lshl_add_u64 v[6:7], s[50:51], 0, v[134:135]
	s_mov_b32 m0, s8
	s_add_i32 s9, s8, 0x2000
	global_load_lds_dwordx4 v[6:7], off
	v_lshl_add_u64 v[6:7], s[50:51], 0, v[138:139]
	s_mov_b32 m0, s9
	s_nop 0
	global_load_lds_dwordx4 v[6:7], off
	v_lshl_add_u64 v[6:7], s[10:11], 0, v[14:15]
	v_lshl_add_u64 v[8:9], v[6:7], 0, s[60:61]
	s_mov_b32 m0, s41
	s_nop 0
	global_load_lds_dwordx4 v[8:9], off
	v_lshl_add_u64 v[8:9], s[10:11], 0, v[136:137]
	v_lshl_add_u64 v[12:13], v[8:9], 0, s[60:61]
	s_mov_b32 m0, s42
	s_nop 0
	global_load_lds_dwordx4 v[12:13], off
	s_waitcnt vmcnt(8)
	s_waitcnt lgkmcnt(0)
	s_barrier
	s_nop 0
	s_waitcnt lgkmcnt(0)
	v_mfma_f32_16x16x32_bf16 v[152:155], v[18:21], v[70:73], 0
	v_mfma_f32_16x16x32_bf16 v[160:163], v[18:21], v[122:125], 0
	v_mfma_f32_16x16x32_bf16 v[170:173], v[18:21], v[130:133], 0
	v_mfma_f32_16x16x32_bf16 v[18:21], v[18:21], v[144:147], 0
	v_mfma_f32_16x16x32_bf16 v[152:155], v[22:25], v[118:121], v[152:155]
	v_mfma_f32_16x16x32_bf16 v[160:163], v[22:25], v[126:129], v[160:163]
	v_mfma_f32_16x16x32_bf16 v[170:173], v[22:25], v[140:143], v[170:173]
	v_mfma_f32_16x16x32_bf16 v[18:21], v[22:25], v[148:151], v[18:21]
	v_mfma_f32_16x16x32_bf16 v[22:25], v[26:29], v[144:147], 0
	v_mfma_f32_16x16x32_bf16 v[156:159], v[26:29], v[70:73], 0
	v_mfma_f32_16x16x32_bf16 v[166:169], v[26:29], v[122:125], 0
	v_mfma_f32_16x16x32_bf16 v[174:177], v[26:29], v[130:133], 0
	v_mfma_f32_16x16x32_bf16 v[22:25], v[30:33], v[148:151], v[22:25]
	v_mfma_f32_16x16x32_bf16 v[156:159], v[30:33], v[118:121], v[156:159]
	v_mfma_f32_16x16x32_bf16 v[166:169], v[30:33], v[126:129], v[166:169]
	v_mfma_f32_16x16x32_bf16 v[174:177], v[30:33], v[140:143], v[174:177]
	s_nop 0
	s_nop 0
	v_mfma_f32_16x16x32_bf16 v[26:29], v[34:37], v[70:73], 0
	v_mfma_f32_16x16x32_bf16 v[30:33], v[42:45], v[70:73], 0
	v_mfma_f32_16x16x32_bf16 v[26:29], v[38:41], v[118:121], v[26:29]
	v_mfma_f32_16x16x32_bf16 v[30:33], v[46:49], v[118:121], v[30:33]
	v_mfma_f32_16x16x32_bf16 v[70:73], v[34:37], v[122:125], 0
	v_mfma_f32_16x16x32_bf16 v[118:121], v[42:45], v[122:125], 0
	v_mfma_f32_16x16x32_bf16 v[122:125], v[34:37], v[130:133], 0
	v_mfma_f32_16x16x32_bf16 v[34:37], v[34:37], v[144:147], 0
	v_mfma_f32_16x16x32_bf16 v[70:73], v[38:41], v[126:129], v[70:73]
	v_mfma_f32_16x16x32_bf16 v[118:121], v[46:49], v[126:129], v[118:121]
	v_mfma_f32_16x16x32_bf16 v[122:125], v[38:41], v[140:143], v[122:125]
	v_mfma_f32_16x16x32_bf16 v[126:129], v[42:45], v[130:133], 0
	v_mfma_f32_16x16x32_bf16 v[34:37], v[38:41], v[148:151], v[34:37]
	v_mfma_f32_16x16x32_bf16 v[38:41], v[42:45], v[144:147], 0
	v_mfma_f32_16x16x32_bf16 v[126:129], v[46:49], v[140:143], v[126:129]
	v_mfma_f32_16x16x32_bf16 v[38:41], v[46:49], v[148:151], v[38:41]
	s_nop 0
	s_barrier
; #define PG8_STAGE(bufoff, gbase, voff) do { _Pragma("unroll") for (int _i = 0; _i < 2; ++_i) \
;         __builtin_amdgcn_global_load_lds((const unsigned*)((const char*)(gbase) + (voff)[_i]), (PG8_LAS unsigned*)(lds + (bufoff) + ldsw + _i * 8192), 16, 0, 0); } while (0)
; #define PG8_LDA(dst, b, h) do { _Pragma("unroll") for (int m = 0; m < 4; ++m) _Pragma("unroll") for (int k = 0; k < 2; ++k) dst[m][k] = *(const PG8_LAS bf16x8*)(lds + PG8_SA(b, h) + aoff + m * 2048 + k * 1024); } while (0)
; #define PG8_LDB(dst, b, h) do { _Pragma("unroll") for (int n = 0; n < 2; ++n) _Pragma("unroll") for (int k = 0; k < 2; ++k) dst[n][k] = *(const PG8_LAS bf16x8*)(lds + PG8_SB(b, h) + boff + n * 2048 + k * 1024); } while (0)
; #define PG8_MMA(ai, bj, At, Bt) do { __builtin_amdgcn_s_setprio(1); _Pragma("unroll") for (int m = 0; m < 4; ++m) _Pragma("unroll") for (int n = 0; n < 2; ++n) _Pragma("unroll") for (int k = 0; k < 2; ++k) \
;         acc[ai][bj][m][n] = __builtin_amdgcn_mfma_f32_16x16x32_bf16(Bt[n][k], At[m][k], acc[ai][bj][m][n], 0, 0, 0); __builtin_amdgcn_s_setprio(0); } while (0)
; #define PG8_BAR __builtin_amdgcn_s_barrier()
; template <class Epi, class Sched, bool ALIGN_EPI = false, bool SP2 = false>
; __device__ __forceinline__ void gemm_phase(PG8_LAS unsigned char* lds, const Gemm g, const Sched& S, const Epi& E, const int wave_s) {
;     ...
;             PG8_LDB(B0, 0, 0); PG8_LDB(B1, 0, 1); PG8_SCHED; PG8_LDA(At, 0, 0); PG8_STAGE(PG8_SA(1, 1), a1 + hstepA, voffA);
;             PG8_WAIT_V(8); PG8_WAIT_L(0); PG8_BAR; PG8_MMA(0, 0, At, B0); PG8_MMA(0, 1, At, B1); PG8_BAR; PG8_SCHED;
;             PG8_LDA(At, 0, 1); PG8_STAGE(PG8_SB(0, 0), b2, voffB); PG8_STAGE(PG8_SB(0, 1), b2 + hstepB, voffB); PG8_STAGE(PG8_SA(0, 0), a2, voffA);
;             PG8_WAIT_V(8); PG8_WAIT_L(0); PG8_BAR; PG8_MMA(1, 0, At, B0); PG8_MMA(1, 1, At, B1); PG8_BAR; PG8_SCHED;
;             PG8_LDB(B0, 1, 0); PG8_LDB(B1, 1, 1); PG8_SCHED; PG8_LDA(At, 1, 0); PG8_STAGE(PG8_SA(0, 1), a2 + hstepA, voffA);
;             PG8_WAIT_V(8); PG8_WAIT_L(0); PG8_BAR; PG8_MMA(0, 0, At, B0); PG8_MMA(0, 1, At, B1); PG8_BAR; PG8_SCHED;
;             PG8_LDA(At, 1, 1); PG8_STAGE(PG8_SB(1, 0), b3, voffB); PG8_STAGE(PG8_SB(1, 1), b3 + hstepB, voffB); PG8_STAGE(PG8_SA(1, 0), a3, voffA);
;             PG8_WAIT_V(8); PG8_WAIT_L(0); PG8_BAR; PG8_MMA(1, 0, At, B0); PG8_MMA(1, 1, At, B1); PG8_BAR; PG8_SCHED;
	s_add_i32 s55, 0, 0x18000
	s_add_i32 s54, 0, 0x1c000
	v_add_u32_e32 v11, s55, v17
	v_add_u32_e32 v12, s54, v17
	ds_read_b128 v[42:45], v11
	ds_read_b128 v[46:49], v11 offset:1024
	ds_read_b128 v[130:133], v11 offset:2048
	ds_read_b128 v[140:143], v11 offset:3072
	ds_read_b128 v[144:147], v12
	ds_read_b128 v[148:151], v12 offset:1024
	ds_read_b128 v[194:197], v12 offset:2048
	ds_read_b128 v[198:201], v12 offset:3072
	s_add_u32 s50, s10, 0x84100
	s_addc_u32 s51, s11, 0
	s_mov_b32 m0, s43
	v_lshl_add_u64 v[178:179], s[50:51], 0, v[14:15]
	ds_read_b128 v[202:205], v164 offset:32768
	ds_read_b128 v[206:209], v164 offset:33792
	ds_read_b128 v[210:213], v164 offset:34816
	ds_read_b128 v[214:217], v164 offset:35840
	ds_read_b128 v[228:231], v164 offset:36864
	ds_read_b128 v[232:235], v164 offset:37888
	ds_read_b128 v[236:239], v164 offset:38912
	ds_read_b128 v[240:243], v164 offset:39936
	global_load_lds_dwordx4 v[178:179], off
	v_lshl_add_u64 v[178:179], s[50:51], 0, v[136:137]
	s_mov_b32 m0, s44
	s_nop 0
	global_load_lds_dwordx4 v[178:179], off
	s_waitcnt vmcnt(8)
	s_waitcnt lgkmcnt(0)
	s_barrier
	s_nop 0
	s_waitcnt lgkmcnt(0)
	v_mfma_f32_16x16x32_bf16 v[74:77], v[42:45], v[202:205], v[74:77]
	v_mfma_f32_16x16x32_bf16 v[78:81], v[130:133], v[202:205], v[78:81]
	v_mfma_f32_16x16x32_bf16 v[82:85], v[42:45], v[210:213], v[82:85]
	v_mfma_f32_16x16x32_bf16 v[86:89], v[130:133], v[210:213], v[86:89]
	v_mfma_f32_16x16x32_bf16 v[90:93], v[42:45], v[228:231], v[90:93]
	v_mfma_f32_16x16x32_bf16 v[94:97], v[130:133], v[228:231], v[94:97]
	v_mfma_f32_16x16x32_bf16 v[98:101], v[42:45], v[236:239], v[98:101]
	v_mfma_f32_16x16x32_bf16 v[102:105], v[130:133], v[236:239], v[102:105]
	v_mfma_f32_16x16x32_bf16 v[74:77], v[46:49], v[206:209], v[74:77]
	v_mfma_f32_16x16x32_bf16 v[78:81], v[140:143], v[206:209], v[78:81]
	v_mfma_f32_16x16x32_bf16 v[82:85], v[46:49], v[214:217], v[82:85]
	v_mfma_f32_16x16x32_bf16 v[86:89], v[140:143], v[214:217], v[86:89]
	v_mfma_f32_16x16x32_bf16 v[90:93], v[46:49], v[232:235], v[90:93]
	v_mfma_f32_16x16x32_bf16 v[94:97], v[140:143], v[232:235], v[94:97]
	v_mfma_f32_16x16x32_bf16 v[98:101], v[46:49], v[240:243], v[98:101]
	v_mfma_f32_16x16x32_bf16 v[102:105], v[140:143], v[240:243], v[102:105]
	s_nop 0
	s_nop 0
	v_mfma_f32_16x16x32_bf16 v[106:109], v[144:147], v[202:205], v[106:109]
	v_mfma_f32_16x16x32_bf16 v[110:113], v[194:197], v[202:205], v[110:113]
	v_mfma_f32_16x16x32_bf16 v[114:117], v[144:147], v[210:213], v[114:117]
	v_mfma_f32_16x16x32_bf16 v[50:53], v[194:197], v[210:213], v[50:53]
	v_mfma_f32_16x16x32_bf16 v[54:57], v[144:147], v[228:231], v[54:57]
	v_mfma_f32_16x16x32_bf16 v[58:61], v[194:197], v[228:231], v[58:61]
	v_mfma_f32_16x16x32_bf16 v[62:65], v[144:147], v[236:239], v[62:65]
	v_mfma_f32_16x16x32_bf16 v[66:69], v[194:197], v[236:239], v[66:69]
	v_mfma_f32_16x16x32_bf16 v[106:109], v[148:151], v[206:209], v[106:109]
	v_mfma_f32_16x16x32_bf16 v[110:113], v[198:201], v[206:209], v[110:113]
	v_mfma_f32_16x16x32_bf16 v[114:117], v[148:151], v[214:217], v[114:117]
	v_mfma_f32_16x16x32_bf16 v[50:53], v[198:201], v[214:217], v[50:53]
	v_mfma_f32_16x16x32_bf16 v[54:57], v[148:151], v[232:235], v[54:57]
	v_mfma_f32_16x16x32_bf16 v[58:61], v[198:201], v[232:235], v[58:61]
	v_mfma_f32_16x16x32_bf16 v[62:65], v[148:151], v[240:243], v[62:65]
	v_mfma_f32_16x16x32_bf16 v[66:69], v[198:201], v[240:243], v[66:69]
	s_nop 0
	s_barrier
	s_add_i32 s55, s55, s40
	s_add_i32 s50, s55, 0x2000
	v_lshl_add_u64 v[178:179], v[2:3], 0, s[78:79]
	s_mov_b32 m0, s55
	s_add_u32 s56, s12, 0x18180
	ds_read_b128 v[202:205], v164 offset:49152
	ds_read_b128 v[206:209], v164 offset:50176
	ds_read_b128 v[210:213], v164 offset:51200
	ds_read_b128 v[214:217], v164 offset:52224
	ds_read_b128 v[228:231], v164 offset:53248
	ds_read_b128 v[232:235], v164 offset:54272
	ds_read_b128 v[236:239], v164 offset:55296
	ds_read_b128 v[240:243], v164 offset:56320
	global_load_lds_dwordx4 v[178:179], off
	v_lshl_add_u64 v[178:179], v[4:5], 0, s[78:79]
	s_mov_b32 m0, s50
	s_addc_u32 s57, s13, 0
	s_add_i32 s51, s54, s40
	global_load_lds_dwordx4 v[178:179], off
	v_lshl_add_u64 v[178:179], s[56:57], 0, v[134:135]
	s_mov_b32 m0, s51
	s_add_i32 s54, s51, 0x2000
	global_load_lds_dwordx4 v[178:179], off
	v_lshl_add_u64 v[178:179], s[56:57], 0, v[138:139]
	s_mov_b32 m0, s54
	s_nop 0
	global_load_lds_dwordx4 v[178:179], off
	v_lshl_add_u64 v[178:179], v[6:7], 0, s[78:79]
	s_mov_b32 m0, s45
	s_nop 0
	global_load_lds_dwordx4 v[178:179], off
	v_lshl_add_u64 v[178:179], v[8:9], 0, s[78:79]
	s_mov_b32 m0, s46
	s_nop 0
	global_load_lds_dwordx4 v[178:179], off
	s_waitcnt vmcnt(8)
	s_waitcnt lgkmcnt(0)
	s_barrier
; #define PG8_STAGE(bufoff, gbase, voff) do { _Pragma("unroll") for (int _i = 0; _i < 2; ++_i) \
;         __builtin_amdgcn_global_load_lds((const unsigned*)((const char*)(gbase) + (voff)[_i]), (PG8_LAS unsigned*)(lds + (bufoff) + ldsw + _i * 8192), 16, 0, 0); } while (0)
; #define PG8_LDA(dst, b, h) do { _Pragma("unroll") for (int m = 0; m < 4; ++m) _Pragma("unroll") for (int k = 0; k < 2; ++k) dst[m][k] = *(const PG8_LAS bf16x8*)(lds + PG8_SA(b, h) + aoff + m * 2048 + k * 1024); } while (0)
; #define PG8_LDB(dst, b, h) do { _Pragma("unroll") for (int n = 0; n < 2; ++n) _Pragma("unroll") for (int k = 0; k < 2; ++k) dst[n][k] = *(const PG8_LAS bf16x8*)(lds + PG8_SB(b, h) + boff + n * 2048 + k * 1024); } while (0)
; #define PG8_MMA(ai, bj, At, Bt) do { __builtin_amdgcn_s_setprio(1); _Pragma("unroll") for (int m = 0; m < 4; ++m) _Pragma("unroll") for (int n = 0; n < 2; ++n) _Pragma("unroll") for (int k = 0; k < 2; ++k) \
;         acc[ai][bj][m][n] = __builtin_amdgcn_mfma_f32_16x16x32_bf16(Bt[n][k], At[m][k], acc[ai][bj][m][n], 0, 0, 0); __builtin_amdgcn_s_setprio(0); } while (0)
; #define PG8_BAR __builtin_amdgcn_s_barrier()
; template <class Epi, class Sched, bool ALIGN_EPI = false, bool SP2 = false>
; __device__ __forceinline__ void gemm_phase(PG8_LAS unsigned char* lds, const Gemm g, const Sched& S, const Epi& E, const int wave_s) {
;     ...
;             PG8_LDB(B0, 0, 0); PG8_LDB(B1, 0, 1); PG8_SCHED; PG8_LDA(At, 0, 0); PG8_STAGE(PG8_SA(1, 1), a1 + hstepA, voffA);
;             PG8_WAIT_V(8); PG8_WAIT_L(0); PG8_BAR; PG8_MMA(0, 0, At, B0); PG8_MMA(0, 1, At, B1); PG8_BAR; PG8_SCHED;
;             PG8_LDA(At, 0, 1); PG8_STAGE(PG8_SB(0, 0), b2, voffB); PG8_STAGE(PG8_SB(0, 1), b2 + hstepB, voffB); PG8_STAGE(PG8_SA(0, 0), a2, voffA);
;             PG8_WAIT_V(8); PG8_WAIT_L(0); PG8_BAR; PG8_MMA(1, 0, At, B0); PG8_MMA(1, 1, At, B1); PG8_BAR; PG8_SCHED;
;             PG8_LDB(B0, 1, 0); PG8_LDB(B1, 1, 1); PG8_SCHED; PG8_LDA(At, 1, 0); PG8_STAGE(PG8_SA(0, 1), a2 + hstepA, voffA);
;             PG8_WAIT_V(8); PG8_WAIT_L(0); PG8_BAR; PG8_MMA(0, 0, At, B0); PG8_MMA(0, 1, At, B1); PG8_BAR; PG8_SCHED;
;             PG8_LDA(At, 1, 1); PG8_STAGE(PG8_SB(1, 0), b3, voffB); PG8_STAGE(PG8_SB(1, 1), b3 + hstepB, voffB); PG8_STAGE(PG8_SA(1, 0), a3, voffA);
;             PG8_WAIT_V(8); PG8_WAIT_L(0); PG8_BAR; PG8_MMA(1, 0, At, B0); PG8_MMA(1, 1, At, B1); PG8_BAR; PG8_SCHED;
	s_nop 0
	s_waitcnt lgkmcnt(0)
	v_mfma_f32_16x16x32_bf16 v[18:21], v[42:45], v[236:239], v[18:21]
	v_mfma_f32_16x16x32_bf16 v[22:25], v[130:133], v[236:239], v[22:25]
	v_mfma_f32_16x16x32_bf16 v[152:155], v[42:45], v[202:205], v[152:155]
	v_mfma_f32_16x16x32_bf16 v[156:159], v[130:133], v[202:205], v[156:159]
	v_mfma_f32_16x16x32_bf16 v[160:163], v[42:45], v[210:213], v[160:163]
	v_mfma_f32_16x16x32_bf16 v[166:169], v[130:133], v[210:213], v[166:169]
	v_mfma_f32_16x16x32_bf16 v[170:173], v[42:45], v[228:231], v[170:173]
	v_mfma_f32_16x16x32_bf16 v[174:177], v[130:133], v[228:231], v[174:177]
	v_mfma_f32_16x16x32_bf16 v[18:21], v[46:49], v[240:243], v[18:21]
	v_mfma_f32_16x16x32_bf16 v[22:25], v[140:143], v[240:243], v[22:25]
	v_mfma_f32_16x16x32_bf16 v[152:155], v[46:49], v[206:209], v[152:155]
	v_mfma_f32_16x16x32_bf16 v[156:159], v[140:143], v[206:209], v[156:159]
	v_mfma_f32_16x16x32_bf16 v[160:163], v[46:49], v[214:217], v[160:163]
	v_mfma_f32_16x16x32_bf16 v[166:169], v[140:143], v[214:217], v[166:169]
	v_mfma_f32_16x16x32_bf16 v[170:173], v[46:49], v[232:235], v[170:173]
	v_mfma_f32_16x16x32_bf16 v[174:177], v[140:143], v[232:235], v[174:177]
	s_nop 0
	s_nop 0
	v_mfma_f32_16x16x32_bf16 v[26:29], v[144:147], v[202:205], v[26:29]
	v_mfma_f32_16x16x32_bf16 v[30:33], v[194:197], v[202:205], v[30:33]
	v_mfma_f32_16x16x32_bf16 v[42:45], v[144:147], v[210:213], v[70:73]
	v_mfma_f32_16x16x32_bf16 v[46:49], v[194:197], v[210:213], v[118:121]
	v_mfma_f32_16x16x32_bf16 v[70:73], v[144:147], v[228:231], v[122:125]
	v_mfma_f32_16x16x32_bf16 v[118:121], v[194:197], v[228:231], v[126:129]
	v_mfma_f32_16x16x32_bf16 v[34:37], v[144:147], v[236:239], v[34:37]
	v_mfma_f32_16x16x32_bf16 v[38:41], v[194:197], v[236:239], v[38:41]
	v_mfma_f32_16x16x32_bf16 v[26:29], v[148:151], v[206:209], v[26:29]
	v_mfma_f32_16x16x32_bf16 v[30:33], v[198:201], v[206:209], v[30:33]
	v_mfma_f32_16x16x32_bf16 v[42:45], v[148:151], v[214:217], v[42:45]
	v_mfma_f32_16x16x32_bf16 v[46:49], v[198:201], v[214:217], v[46:49]
	v_mfma_f32_16x16x32_bf16 v[70:73], v[148:151], v[232:235], v[70:73]
	v_mfma_f32_16x16x32_bf16 v[118:121], v[198:201], v[232:235], v[118:121]
	v_mfma_f32_16x16x32_bf16 v[34:37], v[148:151], v[240:243], v[34:37]
	v_mfma_f32_16x16x32_bf16 v[38:41], v[198:201], v[240:243], v[38:41]
	s_nop 0
	s_barrier
	ds_read_b128 v[122:125], v0
	ds_read_b128 v[126:129], v0 offset:1024
	ds_read_b128 v[130:133], v0 offset:2048
	ds_read_b128 v[140:143], v0 offset:3072
	ds_read_b128 v[144:147], v10
	ds_read_b128 v[148:151], v10 offset:1024
	ds_read_b128 v[194:197], v10 offset:2048
	ds_read_b128 v[198:201], v10 offset:3072
	s_add_u32 s56, s10, 0x84180
	s_addc_u32 s57, s11, 0
	s_mov_b32 m0, s52
	v_lshl_add_u64 v[178:179], s[56:57], 0, v[14:15]
	ds_read_b128 v[202:205], v164
	ds_read_b128 v[206:209], v164 offset:1024
	ds_read_b128 v[210:213], v164 offset:2048
	ds_read_b128 v[214:217], v164 offset:3072
	ds_read_b128 v[228:231], v164 offset:4096
	ds_read_b128 v[232:235], v164 offset:5120
	ds_read_b128 v[236:239], v164 offset:6144
	ds_read_b128 v[240:243], v164 offset:7168
	global_load_lds_dwordx4 v[178:179], off
	v_lshl_add_u64 v[178:179], s[56:57], 0, v[136:137]
	s_mov_b32 m0, s2
	s_nop 0
	global_load_lds_dwordx4 v[178:179], off
	s_waitcnt vmcnt(8)
	s_waitcnt lgkmcnt(0)
	s_barrier
	s_nop 0
	s_waitcnt lgkmcnt(0)
	v_mfma_f32_16x16x32_bf16 v[74:77], v[122:125], v[202:205], v[74:77]
	v_mfma_f32_16x16x32_bf16 v[78:81], v[130:133], v[202:205], v[78:81]
	v_mfma_f32_16x16x32_bf16 v[82:85], v[122:125], v[210:213], v[82:85]
	v_mfma_f32_16x16x32_bf16 v[86:89], v[130:133], v[210:213], v[86:89]
	v_mfma_f32_16x16x32_bf16 v[90:93], v[122:125], v[228:231], v[90:93]
	v_mfma_f32_16x16x32_bf16 v[94:97], v[130:133], v[228:231], v[94:97]
	v_mfma_f32_16x16x32_bf16 v[98:101], v[122:125], v[236:239], v[98:101]
	v_mfma_f32_16x16x32_bf16 v[102:105], v[130:133], v[236:239], v[102:105]
	v_mfma_f32_16x16x32_bf16 v[74:77], v[126:129], v[206:209], v[74:77]
	v_mfma_f32_16x16x32_bf16 v[78:81], v[140:143], v[206:209], v[78:81]
	v_mfma_f32_16x16x32_bf16 v[82:85], v[126:129], v[214:217], v[82:85]
	v_mfma_f32_16x16x32_bf16 v[86:89], v[140:143], v[214:217], v[86:89]
	v_mfma_f32_16x16x32_bf16 v[90:93], v[126:129], v[232:235], v[90:93]
	v_mfma_f32_16x16x32_bf16 v[94:97], v[140:143], v[232:235], v[94:97]
	v_mfma_f32_16x16x32_bf16 v[98:101], v[126:129], v[240:243], v[98:101]
	v_mfma_f32_16x16x32_bf16 v[102:105], v[140:143], v[240:243], v[102:105]
	s_nop 0
	s_nop 0
	v_mfma_f32_16x16x32_bf16 v[106:109], v[144:147], v[202:205], v[106:109]
	v_mfma_f32_16x16x32_bf16 v[110:113], v[194:197], v[202:205], v[110:113]
	v_mfma_f32_16x16x32_bf16 v[114:117], v[144:147], v[210:213], v[114:117]
	v_mfma_f32_16x16x32_bf16 v[50:53], v[194:197], v[210:213], v[50:53]
	v_mfma_f32_16x16x32_bf16 v[54:57], v[144:147], v[228:231], v[54:57]
	v_mfma_f32_16x16x32_bf16 v[58:61], v[194:197], v[228:231], v[58:61]
	v_mfma_f32_16x16x32_bf16 v[62:65], v[144:147], v[236:239], v[62:65]
	v_mfma_f32_16x16x32_bf16 v[66:69], v[194:197], v[236:239], v[66:69]
	v_mfma_f32_16x16x32_bf16 v[106:109], v[148:151], v[206:209], v[106:109]
	v_mfma_f32_16x16x32_bf16 v[110:113], v[198:201], v[206:209], v[110:113]
	v_mfma_f32_16x16x32_bf16 v[114:117], v[148:151], v[214:217], v[114:117]
	v_mfma_f32_16x16x32_bf16 v[50:53], v[198:201], v[214:217], v[50:53]
	v_mfma_f32_16x16x32_bf16 v[54:57], v[148:151], v[232:235], v[54:57]
	v_mfma_f32_16x16x32_bf16 v[58:61], v[198:201], v[232:235], v[58:61]
	v_mfma_f32_16x16x32_bf16 v[62:65], v[148:151], v[240:243], v[62:65]
	v_mfma_f32_16x16x32_bf16 v[66:69], v[198:201], v[240:243], v[66:69]
	s_nop 0
	s_barrier
; #define PG8_STAGE(bufoff, gbase, voff) do { _Pragma("unroll") for (int _i = 0; _i < 2; ++_i) \
;         __builtin_amdgcn_global_load_lds((const unsigned*)((const char*)(gbase) + (voff)[_i]), (PG8_LAS unsigned*)(lds + (bufoff) + ldsw + _i * 8192), 16, 0, 0); } while (0)
; #define PG8_LDA(dst, b, h) do { _Pragma("unroll") for (int m = 0; m < 4; ++m) _Pragma("unroll") for (int k = 0; k < 2; ++k) dst[m][k] = *(const PG8_LAS bf16x8*)(lds + PG8_SA(b, h) + aoff + m * 2048 + k * 1024); } while (0)
; #define PG8_LDB(dst, b, h) do { _Pragma("unroll") for (int n = 0; n < 2; ++n) _Pragma("unroll") for (int k = 0; k < 2; ++k) dst[n][k] = *(const PG8_LAS bf16x8*)(lds + PG8_SB(b, h) + boff + n * 2048 + k * 1024); } while (0)
; #define PG8_MMA(ai, bj, At, Bt) do { __builtin_amdgcn_s_setprio(1); _Pragma("unroll") for (int m = 0; m < 4; ++m) _Pragma("unroll") for (int n = 0; n < 2; ++n) _Pragma("unroll") for (int k = 0; k < 2; ++k) \
;         acc[ai][bj][m][n] = __builtin_amdgcn_mfma_f32_16x16x32_bf16(Bt[n][k], At[m][k], acc[ai][bj][m][n], 0, 0, 0); __builtin_amdgcn_s_setprio(0); } while (0)
; #define PG8_BAR __builtin_amdgcn_s_barrier()
; template <class Epi, class Sched, bool ALIGN_EPI = false, bool SP2 = false>
; __device__ __forceinline__ void gemm_phase(PG8_LAS unsigned char* lds, const Gemm g, const Sched& S, const Epi& E, const int wave_s) {
;     ...
;             PG8_LDB(B0, 0, 0); PG8_LDB(B1, 0, 1); PG8_SCHED; PG8_LDA(At, 0, 0); PG8_STAGE(PG8_SA(1, 1), a1 + hstepA, voffA);
;             PG8_WAIT_V(8); PG8_WAIT_L(0); PG8_BAR; PG8_MMA(0, 0, At, B0); PG8_MMA(0, 1, At, B1); PG8_BAR; PG8_SCHED;
;             PG8_LDA(At, 0, 1); PG8_STAGE(PG8_SB(0, 0), b2, voffB); PG8_STAGE(PG8_SB(0, 1), b2 + hstepB, voffB); PG8_STAGE(PG8_SA(0, 0), a2, voffA);
;             PG8_WAIT_V(8); PG8_WAIT_L(0); PG8_BAR; PG8_MMA(1, 0, At, B0); PG8_MMA(1, 1, At, B1); PG8_BAR; PG8_SCHED;
;             PG8_LDB(B0, 1, 0); PG8_LDB(B1, 1, 1); PG8_SCHED; PG8_LDA(At, 1, 0); PG8_STAGE(PG8_SA(0, 1), a2 + hstepA, voffA);
;             PG8_WAIT_V(8); PG8_WAIT_L(0); PG8_BAR; PG8_MMA(0, 0, At, B0); PG8_MMA(0, 1, At, B1); PG8_BAR; PG8_SCHED;
;             PG8_LDA(At, 1, 1); PG8_STAGE(PG8_SB(1, 0), b3, voffB); PG8_STAGE(PG8_SB(1, 1), b3 + hstepB, voffB); PG8_STAGE(PG8_SA(1, 0), a3, voffA);
;             PG8_WAIT_V(8); PG8_WAIT_L(0); PG8_BAR; PG8_MMA(1, 0, At, B0); PG8_MMA(1, 1, At, B1); PG8_BAR; PG8_SCHED;
	s_mov_b64 s[66:67], 0x200
	s_mov_b32 m0, s49
	v_lshl_add_u64 v[178:179], v[2:3], 0, s[66:67]
	s_add_u32 s56, s12, 0x18200
	ds_read_b128 v[202:205], v164 offset:16384
	ds_read_b128 v[206:209], v164 offset:17408
	ds_read_b128 v[210:213], v164 offset:18432
	ds_read_b128 v[214:217], v164 offset:19456
	ds_read_b128 v[228:231], v164 offset:20480
	ds_read_b128 v[232:235], v164 offset:21504
	ds_read_b128 v[236:239], v164 offset:22528
	ds_read_b128 v[240:243], v164 offset:23552
	global_load_lds_dwordx4 v[178:179], off
	v_lshl_add_u64 v[178:179], v[4:5], 0, s[66:67]
	s_mov_b32 m0, s3
	s_addc_u32 s57, s13, 0
	global_load_lds_dwordx4 v[178:179], off
	v_lshl_add_u64 v[178:179], s[56:57], 0, v[134:135]
	s_mov_b32 m0, s8
	s_nop 0
	global_load_lds_dwordx4 v[178:179], off
	v_lshl_add_u64 v[178:179], s[56:57], 0, v[138:139]
	s_mov_b32 m0, s9
	s_nop 0
	global_load_lds_dwordx4 v[178:179], off
	v_lshl_add_u64 v[178:179], v[6:7], 0, s[66:67]
	s_mov_b32 m0, s41
	s_nop 0
	global_load_lds_dwordx4 v[178:179], off
	v_lshl_add_u64 v[178:179], v[8:9], 0, s[66:67]
	s_mov_b32 m0, s42
	s_nop 0
	global_load_lds_dwordx4 v[178:179], off
	s_waitcnt vmcnt(8)
	s_waitcnt lgkmcnt(0)
	s_barrier
	s_nop 0
	s_waitcnt lgkmcnt(0)
	v_mfma_f32_16x16x32_bf16 v[18:21], v[122:125], v[236:239], v[18:21]
	v_mfma_f32_16x16x32_bf16 v[22:25], v[130:133], v[236:239], v[22:25]
	v_mfma_f32_16x16x32_bf16 v[152:155], v[122:125], v[202:205], v[152:155]
	v_mfma_f32_16x16x32_bf16 v[156:159], v[130:133], v[202:205], v[156:159]
	v_mfma_f32_16x16x32_bf16 v[160:163], v[122:125], v[210:213], v[160:163]
	v_mfma_f32_16x16x32_bf16 v[166:169], v[130:133], v[210:213], v[166:169]
	v_mfma_f32_16x16x32_bf16 v[170:173], v[122:125], v[228:231], v[170:173]
	v_mfma_f32_16x16x32_bf16 v[174:177], v[130:133], v[228:231], v[174:177]
	v_mfma_f32_16x16x32_bf16 v[18:21], v[126:129], v[240:243], v[18:21]
	v_mfma_f32_16x16x32_bf16 v[22:25], v[140:143], v[240:243], v[22:25]
	v_mfma_f32_16x16x32_bf16 v[152:155], v[126:129], v[206:209], v[152:155]
	v_mfma_f32_16x16x32_bf16 v[156:159], v[140:143], v[206:209], v[156:159]
	v_mfma_f32_16x16x32_bf16 v[160:163], v[126:129], v[214:217], v[160:163]
	v_mfma_f32_16x16x32_bf16 v[166:169], v[140:143], v[214:217], v[166:169]
	v_mfma_f32_16x16x32_bf16 v[170:173], v[126:129], v[232:235], v[170:173]
	v_mfma_f32_16x16x32_bf16 v[174:177], v[140:143], v[232:235], v[174:177]
	s_nop 0
	s_nop 0
	v_mfma_f32_16x16x32_bf16 v[26:29], v[144:147], v[202:205], v[26:29]
	v_mfma_f32_16x16x32_bf16 v[30:33], v[194:197], v[202:205], v[30:33]
	v_mfma_f32_16x16x32_bf16 v[42:45], v[144:147], v[210:213], v[42:45]
	v_mfma_f32_16x16x32_bf16 v[46:49], v[194:197], v[210:213], v[46:49]
	v_mfma_f32_16x16x32_bf16 v[70:73], v[144:147], v[228:231], v[70:73]
	v_mfma_f32_16x16x32_bf16 v[118:121], v[194:197], v[228:231], v[118:121]
	v_mfma_f32_16x16x32_bf16 v[34:37], v[144:147], v[236:239], v[34:37]
	v_mfma_f32_16x16x32_bf16 v[38:41], v[194:197], v[236:239], v[38:41]
	v_mfma_f32_16x16x32_bf16 v[26:29], v[148:151], v[206:209], v[26:29]
	v_mfma_f32_16x16x32_bf16 v[30:33], v[198:201], v[206:209], v[30:33]
	v_mfma_f32_16x16x32_bf16 v[42:45], v[148:151], v[214:217], v[42:45]
	v_mfma_f32_16x16x32_bf16 v[46:49], v[198:201], v[214:217], v[46:49]
	v_mfma_f32_16x16x32_bf16 v[70:73], v[148:151], v[232:235], v[70:73]
	v_mfma_f32_16x16x32_bf16 v[118:121], v[198:201], v[232:235], v[118:121]
	v_mfma_f32_16x16x32_bf16 v[34:37], v[148:151], v[240:243], v[34:37]
	v_mfma_f32_16x16x32_bf16 v[38:41], v[198:201], v[240:243], v[38:41]
	s_nop 0
	s_barrier
	ds_read_b128 v[122:125], v11
	ds_read_b128 v[126:129], v11 offset:1024
	ds_read_b128 v[130:133], v11 offset:2048
	ds_read_b128 v[140:143], v11 offset:3072
	ds_read_b128 v[144:147], v12
	ds_read_b128 v[148:151], v12 offset:1024
	ds_read_b128 v[194:197], v12 offset:2048
	ds_read_b128 v[198:201], v12 offset:3072
	s_add_u32 s56, s10, 0x84200
	s_addc_u32 s57, s11, 0
	s_mov_b32 m0, s43
	v_lshl_add_u64 v[178:179], s[56:57], 0, v[14:15]
	ds_read_b128 v[202:205], v164 offset:32768
	ds_read_b128 v[206:209], v164 offset:33792
	ds_read_b128 v[210:213], v164 offset:34816
	ds_read_b128 v[214:217], v164 offset:35840
	ds_read_b128 v[228:231], v164 offset:36864
	ds_read_b128 v[232:235], v164 offset:37888
	ds_read_b128 v[236:239], v164 offset:38912
	ds_read_b128 v[240:243], v164 offset:39936
	global_load_lds_dwordx4 v[178:179], off
	v_lshl_add_u64 v[178:179], s[56:57], 0, v[136:137]
	s_mov_b32 m0, s44
	s_nop 0
	global_load_lds_dwordx4 v[178:179], off
	s_waitcnt vmcnt(8)
	s_waitcnt lgkmcnt(0)
	s_barrier
; #define PG8_STAGE(bufoff, gbase, voff) do { _Pragma("unroll") for (int _i = 0; _i < 2; ++_i) \
;         __builtin_amdgcn_global_load_lds((const unsigned*)((const char*)(gbase) + (voff)[_i]), (PG8_LAS unsigned*)(lds + (bufoff) + ldsw + _i * 8192), 16, 0, 0); } while (0)
; #define PG8_LDA(dst, b, h) do { _Pragma("unroll") for (int m = 0; m < 4; ++m) _Pragma("unroll") for (int k = 0; k < 2; ++k) dst[m][k] = *(const PG8_LAS bf16x8*)(lds + PG8_SA(b, h) + aoff + m * 2048 + k * 1024); } while (0)
; #define PG8_LDB(dst, b, h) do { _Pragma("unroll") for (int n = 0; n < 2; ++n) _Pragma("unroll") for (int k = 0; k < 2; ++k) dst[n][k] = *(const PG8_LAS bf16x8*)(lds + PG8_SB(b, h) + boff + n * 2048 + k * 1024); } while (0)
; #define PG8_MMA(ai, bj, At, Bt) do { __builtin_amdgcn_s_setprio(1); _Pragma("unroll") for (int m = 0; m < 4; ++m) _Pragma("unroll") for (int n = 0; n < 2; ++n) _Pragma("unroll") for (int k = 0; k < 2; ++k) \
;         acc[ai][bj][m][n] = __builtin_amdgcn_mfma_f32_16x16x32_bf16(Bt[n][k], At[m][k], acc[ai][bj][m][n], 0, 0, 0); __builtin_amdgcn_s_setprio(0); } while (0)
; #define PG8_BAR __builtin_amdgcn_s_barrier()
; template <class Epi, class Sched, bool ALIGN_EPI = false, bool SP2 = false>
; __device__ __forceinline__ void gemm_phase(PG8_LAS unsigned char* lds, const Gemm g, const Sched& S, const Epi& E, const int wave_s) {
;     ...
;             PG8_LDB(B0, 0, 0); PG8_LDB(B1, 0, 1); PG8_SCHED; PG8_LDA(At, 0, 0); PG8_STAGE(PG8_SA(1, 1), a1 + hstepA, voffA);
;             PG8_WAIT_V(8); PG8_WAIT_L(0); PG8_BAR; PG8_MMA(0, 0, At, B0); PG8_MMA(0, 1, At, B1); PG8_BAR; PG8_SCHED;
;             PG8_LDA(At, 0, 1); PG8_STAGE(PG8_SB(0, 0), b2, voffB); PG8_STAGE(PG8_SB(0, 1), b2 + hstepB, voffB); PG8_STAGE(PG8_SA(0, 0), a2, voffA);
;             PG8_WAIT_V(8); PG8_WAIT_L(0); PG8_BAR; PG8_MMA(1, 0, At, B0); PG8_MMA(1, 1, At, B1); PG8_BAR; PG8_SCHED;
;             PG8_LDB(B0, 1, 0); PG8_LDB(B1, 1, 1); PG8_SCHED; PG8_LDA(At, 1, 0); PG8_STAGE(PG8_SA(0, 1), a2 + hstepA, voffA);
;             PG8_WAIT_V(8); PG8_WAIT_L(0); PG8_BAR; PG8_MMA(0, 0, At, B0); PG8_MMA(0, 1, At, B1); PG8_BAR; PG8_SCHED;
;             PG8_LDA(At, 1, 1); PG8_STAGE(PG8_SB(1, 0), b3, voffB); PG8_STAGE(PG8_SB(1, 1), b3 + hstepB, voffB); PG8_STAGE(PG8_SA(1, 0), a3, voffA);
;             PG8_WAIT_V(8); PG8_WAIT_L(0); PG8_BAR; PG8_MMA(1, 0, At, B0); PG8_MMA(1, 1, At, B1); PG8_BAR; PG8_SCHED;
	s_nop 0
	s_waitcnt lgkmcnt(0)
	v_mfma_f32_16x16x32_bf16 v[74:77], v[122:125], v[202:205], v[74:77]
	v_mfma_f32_16x16x32_bf16 v[78:81], v[130:133], v[202:205], v[78:81]
	v_mfma_f32_16x16x32_bf16 v[82:85], v[122:125], v[210:213], v[82:85]
	v_mfma_f32_16x16x32_bf16 v[86:89], v[130:133], v[210:213], v[86:89]
	v_mfma_f32_16x16x32_bf16 v[90:93], v[122:125], v[228:231], v[90:93]
	v_mfma_f32_16x16x32_bf16 v[94:97], v[130:133], v[228:231], v[94:97]
	v_mfma_f32_16x16x32_bf16 v[98:101], v[122:125], v[236:239], v[98:101]
	v_mfma_f32_16x16x32_bf16 v[102:105], v[130:133], v[236:239], v[102:105]
	v_mfma_f32_16x16x32_bf16 v[74:77], v[126:129], v[206:209], v[74:77]
	v_mfma_f32_16x16x32_bf16 v[78:81], v[140:143], v[206:209], v[78:81]
	v_mfma_f32_16x16x32_bf16 v[82:85], v[126:129], v[214:217], v[82:85]
	v_mfma_f32_16x16x32_bf16 v[86:89], v[140:143], v[214:217], v[86:89]
	v_mfma_f32_16x16x32_bf16 v[90:93], v[126:129], v[232:235], v[90:93]
	v_mfma_f32_16x16x32_bf16 v[94:97], v[140:143], v[232:235], v[94:97]
	v_mfma_f32_16x16x32_bf16 v[98:101], v[126:129], v[240:243], v[98:101]
	v_mfma_f32_16x16x32_bf16 v[102:105], v[140:143], v[240:243], v[102:105]
	s_nop 0
	s_nop 0
	v_mfma_f32_16x16x32_bf16 v[106:109], v[144:147], v[202:205], v[106:109]
	v_mfma_f32_16x16x32_bf16 v[110:113], v[194:197], v[202:205], v[110:113]
	v_mfma_f32_16x16x32_bf16 v[114:117], v[144:147], v[210:213], v[114:117]
	v_mfma_f32_16x16x32_bf16 v[50:53], v[194:197], v[210:213], v[50:53]
	v_mfma_f32_16x16x32_bf16 v[54:57], v[144:147], v[228:231], v[54:57]
	v_mfma_f32_16x16x32_bf16 v[58:61], v[194:197], v[228:231], v[58:61]
	v_mfma_f32_16x16x32_bf16 v[62:65], v[144:147], v[236:239], v[62:65]
	v_mfma_f32_16x16x32_bf16 v[66:69], v[194:197], v[236:239], v[66:69]
	v_mfma_f32_16x16x32_bf16 v[106:109], v[148:151], v[206:209], v[106:109]
	v_mfma_f32_16x16x32_bf16 v[110:113], v[198:201], v[206:209], v[110:113]
	v_mfma_f32_16x16x32_bf16 v[114:117], v[148:151], v[214:217], v[114:117]
	v_mfma_f32_16x16x32_bf16 v[50:53], v[198:201], v[214:217], v[50:53]
	v_mfma_f32_16x16x32_bf16 v[54:57], v[148:151], v[232:235], v[54:57]
	v_mfma_f32_16x16x32_bf16 v[58:61], v[198:201], v[232:235], v[58:61]
	v_mfma_f32_16x16x32_bf16 v[62:65], v[148:151], v[240:243], v[62:65]
	v_mfma_f32_16x16x32_bf16 v[66:69], v[198:201], v[240:243], v[66:69]
	s_nop 0
	s_barrier
	s_mov_b64 s[56:57], 0x280
	s_mov_b32 m0, s55
	v_lshl_add_u64 v[2:3], v[2:3], 0, s[56:57]
	s_add_u32 s12, s12, 0x18280
	ds_read_b128 v[202:205], v164 offset:49152
	ds_read_b128 v[206:209], v164 offset:50176
	ds_read_b128 v[210:213], v164 offset:51200
	ds_read_b128 v[214:217], v164 offset:52224
	ds_read_b128 v[228:231], v164 offset:53248
	ds_read_b128 v[232:235], v164 offset:54272
	ds_read_b128 v[236:239], v164 offset:55296
	ds_read_b128 v[240:243], v164 offset:56320
	global_load_lds_dwordx4 v[2:3], off
	v_lshl_add_u64 v[2:3], v[4:5], 0, s[56:57]
	s_mov_b32 m0, s50
	s_addc_u32 s13, s13, 0
	global_load_lds_dwordx4 v[2:3], off
	v_lshl_add_u64 v[2:3], s[12:13], 0, v[134:135]
	s_mov_b32 m0, s51
	s_nop 0
	global_load_lds_dwordx4 v[2:3], off
	v_lshl_add_u64 v[2:3], s[12:13], 0, v[138:139]
	s_mov_b32 m0, s54
	s_nop 0
	global_load_lds_dwordx4 v[2:3], off
	v_lshl_add_u64 v[2:3], v[6:7], 0, s[56:57]
	s_mov_b32 m0, s45
	s_nop 0
	global_load_lds_dwordx4 v[2:3], off
	v_lshl_add_u64 v[2:3], v[8:9], 0, s[56:57]
	s_mov_b32 m0, s46
	s_nop 0
	global_load_lds_dwordx4 v[2:3], off
	s_waitcnt vmcnt(8)
	s_waitcnt lgkmcnt(0)
	s_barrier
	s_nop 0
	s_waitcnt lgkmcnt(0)
	v_mfma_f32_16x16x32_bf16 v[2:5], v[122:125], v[202:205], v[152:155]
	v_mfma_f32_16x16x32_bf16 v[6:9], v[130:133], v[202:205], v[156:159]
	v_mfma_f32_16x16x32_bf16 v[18:21], v[122:125], v[236:239], v[18:21]
	v_mfma_f32_16x16x32_bf16 v[22:25], v[130:133], v[236:239], v[22:25]
	v_mfma_f32_16x16x32_bf16 v[2:5], v[126:129], v[206:209], v[2:5]
	v_mfma_f32_16x16x32_bf16 v[6:9], v[140:143], v[206:209], v[6:9]
	v_mfma_f32_16x16x32_bf16 v[152:155], v[122:125], v[210:213], v[160:163]
	v_mfma_f32_16x16x32_bf16 v[156:159], v[130:133], v[210:213], v[166:169]
	v_mfma_f32_16x16x32_bf16 v[160:163], v[122:125], v[228:231], v[170:173]
	v_mfma_f32_16x16x32_bf16 v[166:169], v[130:133], v[228:231], v[174:177]
	v_mfma_f32_16x16x32_bf16 v[18:21], v[126:129], v[240:243], v[18:21]
	v_mfma_f32_16x16x32_bf16 v[22:25], v[140:143], v[240:243], v[22:25]
	v_mfma_f32_16x16x32_bf16 v[152:155], v[126:129], v[214:217], v[152:155]
	v_mfma_f32_16x16x32_bf16 v[156:159], v[140:143], v[214:217], v[156:159]
	v_mfma_f32_16x16x32_bf16 v[160:163], v[126:129], v[232:235], v[160:163]
	v_mfma_f32_16x16x32_bf16 v[166:169], v[140:143], v[232:235], v[166:169]
	s_nop 0
	s_nop 0
	v_mfma_f32_16x16x32_bf16 v[26:29], v[144:147], v[202:205], v[26:29]
	v_mfma_f32_16x16x32_bf16 v[30:33], v[194:197], v[202:205], v[30:33]
	v_mfma_f32_16x16x32_bf16 v[42:45], v[144:147], v[210:213], v[42:45]
	v_mfma_f32_16x16x32_bf16 v[46:49], v[194:197], v[210:213], v[46:49]
	v_mfma_f32_16x16x32_bf16 v[70:73], v[144:147], v[228:231], v[70:73]
	v_mfma_f32_16x16x32_bf16 v[118:121], v[194:197], v[228:231], v[118:121]
	v_mfma_f32_16x16x32_bf16 v[34:37], v[144:147], v[236:239], v[34:37]
	v_mfma_f32_16x16x32_bf16 v[38:41], v[194:197], v[236:239], v[38:41]
	v_mfma_f32_16x16x32_bf16 v[26:29], v[148:151], v[206:209], v[26:29]
	v_mfma_f32_16x16x32_bf16 v[30:33], v[198:201], v[206:209], v[30:33]
	v_mfma_f32_16x16x32_bf16 v[42:45], v[148:151], v[214:217], v[42:45]
	v_mfma_f32_16x16x32_bf16 v[46:49], v[198:201], v[214:217], v[46:49]
	v_mfma_f32_16x16x32_bf16 v[70:73], v[148:151], v[232:235], v[70:73]
	v_mfma_f32_16x16x32_bf16 v[118:121], v[198:201], v[232:235], v[118:121]
	v_mfma_f32_16x16x32_bf16 v[34:37], v[148:151], v[240:243], v[34:37]
	v_mfma_f32_16x16x32_bf16 v[38:41], v[198:201], v[240:243], v[38:41]
	s_nop 0
	s_barrier
; #define PG8_STAGE(bufoff, gbase, voff) do { _Pragma("unroll") for (int _i = 0; _i < 2; ++_i) \
;         __builtin_amdgcn_global_load_lds((const unsigned*)((const char*)(gbase) + (voff)[_i]), (PG8_LAS unsigned*)(lds + (bufoff) + ldsw + _i * 8192), 16, 0, 0); } while (0)
; #define PG8_LDA(dst, b, h) do { _Pragma("unroll") for (int m = 0; m < 4; ++m) _Pragma("unroll") for (int k = 0; k < 2; ++k) dst[m][k] = *(const PG8_LAS bf16x8*)(lds + PG8_SA(b, h) + aoff + m * 2048 + k * 1024); } while (0)
; #define PG8_LDB(dst, b, h) do { _Pragma("unroll") for (int n = 0; n < 2; ++n) _Pragma("unroll") for (int k = 0; k < 2; ++k) dst[n][k] = *(const PG8_LAS bf16x8*)(lds + PG8_SB(b, h) + boff + n * 2048 + k * 1024); } while (0)
; #define PG8_MMA(ai, bj, At, Bt) do { __builtin_amdgcn_s_setprio(1); _Pragma("unroll") for (int m = 0; m < 4; ++m) _Pragma("unroll") for (int n = 0; n < 2; ++n) _Pragma("unroll") for (int k = 0; k < 2; ++k) \
;         acc[ai][bj][m][n] = __builtin_amdgcn_mfma_f32_16x16x32_bf16(Bt[n][k], At[m][k], acc[ai][bj][m][n], 0, 0, 0); __builtin_amdgcn_s_setprio(0); } while (0)
; #define PG8_BAR __builtin_amdgcn_s_barrier()
; template <class Epi, class Sched, bool ALIGN_EPI = false, bool SP2 = false>
; __device__ __forceinline__ void gemm_phase(PG8_LAS unsigned char* lds, const Gemm g, const Sched& S, const Epi& E, const int wave_s) {
;     ...
;             PG8_LDB(B0, 0, 0); PG8_LDB(B1, 0, 1); PG8_SCHED; PG8_LDA(At, 0, 0); PG8_STAGE(PG8_SA(1, 1), a1 + hstepA, voffA);
;             PG8_WAIT_V(8); PG8_WAIT_L(0); PG8_BAR; PG8_MMA(0, 0, At, B0); PG8_MMA(0, 1, At, B1); PG8_BAR; PG8_SCHED;
;             PG8_LDA(At, 0, 1); PG8_STAGE(PG8_SB(0, 0), b2, voffB); PG8_STAGE(PG8_SB(0, 1), b2 + hstepB, voffB); PG8_STAGE(PG8_SA(0, 0), a2, voffA);
;             PG8_WAIT_V(8); PG8_WAIT_L(0); PG8_BAR; PG8_MMA(1, 0, At, B0); PG8_MMA(1, 1, At, B1); PG8_BAR; PG8_SCHED;
;             PG8_LDB(B0, 1, 0); PG8_LDB(B1, 1, 1); PG8_SCHED; PG8_LDA(At, 1, 0); PG8_STAGE(PG8_SA(0, 1), a2 + hstepA, voffA);
;             PG8_WAIT_V(8); PG8_WAIT_L(0); PG8_BAR; PG8_MMA(0, 0, At, B0); PG8_MMA(0, 1, At, B1); PG8_BAR; PG8_SCHED;
;             PG8_LDA(At, 1, 1); PG8_STAGE(PG8_SB(1, 0), b3, voffB); PG8_STAGE(PG8_SB(1, 1), b3 + hstepB, voffB); PG8_STAGE(PG8_SA(1, 0), a3, voffA);
;             PG8_WAIT_V(8); PG8_WAIT_L(0); PG8_BAR; PG8_MMA(1, 0, At, B0); PG8_MMA(1, 1, At, B1); PG8_BAR; PG8_SCHED;
	ds_read_b128 v[122:125], v0
	ds_read_b128 v[126:129], v0 offset:1024
	ds_read_b128 v[130:133], v0 offset:2048
	ds_read_b128 v[140:143], v0 offset:3072
	ds_read_b128 v[144:147], v10
	ds_read_b128 v[148:151], v10 offset:1024
	ds_read_b128 v[170:173], v10 offset:2048
	ds_read_b128 v[174:177], v10 offset:3072
	s_add_u32 s10, s10, 0x84280
	s_addc_u32 s11, s11, 0
	s_mov_b32 m0, s52
	v_lshl_add_u64 v[178:179], s[10:11], 0, v[14:15]
	ds_read_b128 v[194:197], v164
	ds_read_b128 v[198:201], v164 offset:1024
	ds_read_b128 v[202:205], v164 offset:2048
	ds_read_b128 v[206:209], v164 offset:3072
	ds_read_b128 v[210:213], v164 offset:4096
	ds_read_b128 v[214:217], v164 offset:5120
	ds_read_b128 v[228:231], v164 offset:6144
	ds_read_b128 v[232:235], v164 offset:7168
	global_load_lds_dwordx4 v[178:179], off
	v_lshl_add_u64 v[178:179], s[10:11], 0, v[136:137]
	s_mov_b32 m0, s2
	s_nop 0
	global_load_lds_dwordx4 v[178:179], off
	s_waitcnt vmcnt(8)
	s_waitcnt lgkmcnt(0)
	s_barrier
	s_nop 0
	s_waitcnt lgkmcnt(0)
	v_mfma_f32_16x16x32_bf16 v[98:101], v[122:125], v[228:231], v[98:101]
	v_mfma_f32_16x16x32_bf16 v[74:77], v[122:125], v[194:197], v[74:77]
	v_mfma_f32_16x16x32_bf16 v[78:81], v[130:133], v[194:197], v[78:81]
	v_mfma_f32_16x16x32_bf16 v[82:85], v[122:125], v[202:205], v[82:85]
	v_mfma_f32_16x16x32_bf16 v[86:89], v[130:133], v[202:205], v[86:89]
	v_mfma_f32_16x16x32_bf16 v[90:93], v[122:125], v[210:213], v[90:93]
	v_mfma_f32_16x16x32_bf16 v[94:97], v[130:133], v[210:213], v[94:97]
	v_mfma_f32_16x16x32_bf16 v[236:239], v[126:129], v[232:235], v[98:101]
	v_mfma_f32_16x16x32_bf16 v[98:101], v[130:133], v[228:231], v[102:105]
	v_mfma_f32_16x16x32_bf16 v[74:77], v[126:129], v[198:201], v[74:77]
	v_mfma_f32_16x16x32_bf16 v[78:81], v[140:143], v[198:201], v[78:81]
	v_mfma_f32_16x16x32_bf16 v[82:85], v[126:129], v[206:209], v[82:85]
	v_mfma_f32_16x16x32_bf16 v[86:89], v[140:143], v[206:209], v[86:89]
	v_mfma_f32_16x16x32_bf16 v[90:93], v[126:129], v[214:217], v[90:93]
	v_mfma_f32_16x16x32_bf16 v[94:97], v[140:143], v[214:217], v[94:97]
	v_mfma_f32_16x16x32_bf16 v[102:105], v[140:143], v[232:235], v[98:101]
	s_nop 0
	s_nop 0
	v_mfma_f32_16x16x32_bf16 v[98:101], v[144:147], v[194:197], v[106:109]
	v_mfma_f32_16x16x32_bf16 v[106:109], v[148:151], v[198:201], v[98:101]
	v_mfma_f32_16x16x32_bf16 v[98:101], v[170:173], v[194:197], v[110:113]
	v_mfma_f32_16x16x32_bf16 v[50:53], v[170:173], v[202:205], v[50:53]
	v_mfma_f32_16x16x32_bf16 v[54:57], v[144:147], v[210:213], v[54:57]
	v_mfma_f32_16x16x32_bf16 v[58:61], v[170:173], v[210:213], v[58:61]
	v_mfma_f32_16x16x32_bf16 v[62:65], v[144:147], v[228:231], v[62:65]
	v_mfma_f32_16x16x32_bf16 v[66:69], v[170:173], v[228:231], v[66:69]
	v_mfma_f32_16x16x32_bf16 v[194:197], v[174:177], v[198:201], v[98:101]
	v_mfma_f32_16x16x32_bf16 v[98:101], v[144:147], v[202:205], v[114:117]
	v_mfma_f32_16x16x32_bf16 v[50:53], v[174:177], v[206:209], v[50:53]
	v_mfma_f32_16x16x32_bf16 v[54:57], v[148:151], v[214:217], v[54:57]
	v_mfma_f32_16x16x32_bf16 v[58:61], v[174:177], v[214:217], v[58:61]
	v_mfma_f32_16x16x32_bf16 v[62:65], v[148:151], v[232:235], v[62:65]
	v_mfma_f32_16x16x32_bf16 v[66:69], v[174:177], v[232:235], v[66:69]
	v_mfma_f32_16x16x32_bf16 v[198:201], v[148:151], v[206:209], v[98:101]
	s_nop 0
	s_barrier
	s_mov_b32 m0, s49
	v_lshl_add_u64 v[186:187], s[28:29], 0, v[134:135]
	s_add_u32 s2, s28, 0x18000
	ds_read_b128 v[98:101], v164 offset:16384
	ds_read_b128 v[110:113], v164 offset:17408
	ds_read_b128 v[114:117], v164 offset:18432
	ds_read_b128 v[202:205], v164 offset:19456
	ds_read_b128 v[206:209], v164 offset:20480
	ds_read_b128 v[210:213], v164 offset:21504
	ds_read_b128 v[214:217], v164 offset:22528
	ds_read_b128 v[228:231], v164 offset:23552
	global_load_lds_dwordx4 v[186:187], off
	v_lshl_add_u64 v[188:189], s[28:29], 0, v[138:139]
	s_mov_b32 m0, s3
	s_addc_u32 s3, s29, 0
	global_load_lds_dwordx4 v[188:189], off
	v_lshl_add_u64 v[178:179], s[2:3], 0, v[134:135]
	s_mov_b32 m0, s8
	v_lshl_add_u64 v[218:219], s[26:27], 0, v[14:15]
	global_load_lds_dwordx4 v[178:179], off
	v_lshl_add_u64 v[178:179], s[2:3], 0, v[138:139]
	s_mov_b32 m0, s9
	v_lshl_add_u64 v[220:221], s[26:27], 0, v[136:137]
	global_load_lds_dwordx4 v[178:179], off
	s_mov_b32 m0, s41
	s_nop 0
	global_load_lds_dwordx4 v[218:219], off
	s_mov_b32 m0, s42
	s_nop 0
	global_load_lds_dwordx4 v[220:221], off
	s_waitcnt vmcnt(8)
	s_waitcnt lgkmcnt(0)
	s_barrier
	s_nop 0
	s_waitcnt lgkmcnt(0)
	v_mfma_f32_16x16x32_bf16 v[2:5], v[122:125], v[98:101], v[2:5]
	v_mfma_f32_16x16x32_bf16 v[6:9], v[130:133], v[98:101], v[6:9]
	v_mfma_f32_16x16x32_bf16 v[18:21], v[122:125], v[214:217], v[18:21]
	v_mfma_f32_16x16x32_bf16 v[22:25], v[130:133], v[214:217], v[22:25]
	v_mfma_f32_16x16x32_bf16 v[2:5], v[126:129], v[110:113], v[2:5]
	v_mfma_f32_16x16x32_bf16 v[6:9], v[140:143], v[110:113], v[6:9]
	v_mfma_f32_16x16x32_bf16 v[152:155], v[122:125], v[114:117], v[152:155]
	v_mfma_f32_16x16x32_bf16 v[156:159], v[130:133], v[114:117], v[156:159]
	v_mfma_f32_16x16x32_bf16 v[160:163], v[122:125], v[206:209], v[160:163]
	v_mfma_f32_16x16x32_bf16 v[166:169], v[130:133], v[206:209], v[166:169]
	v_mfma_f32_16x16x32_bf16 v[18:21], v[126:129], v[228:231], v[18:21]
	v_mfma_f32_16x16x32_bf16 v[22:25], v[140:143], v[228:231], v[22:25]
	v_mfma_f32_16x16x32_bf16 v[152:155], v[126:129], v[202:205], v[152:155]
	v_mfma_f32_16x16x32_bf16 v[156:159], v[140:143], v[202:205], v[156:159]
	v_mfma_f32_16x16x32_bf16 v[160:163], v[126:129], v[210:213], v[160:163]
	v_mfma_f32_16x16x32_bf16 v[166:169], v[140:143], v[210:213], v[166:169]
	s_nop 0
	s_nop 0
	v_mfma_f32_16x16x32_bf16 v[30:33], v[170:173], v[98:101], v[30:33]
	v_mfma_f32_16x16x32_bf16 v[140:143], v[174:177], v[110:113], v[30:33]
	v_mfma_f32_16x16x32_bf16 v[30:33], v[144:147], v[114:117], v[42:45]
	v_mfma_f32_16x16x32_bf16 v[42:45], v[148:151], v[202:205], v[30:33]
	v_mfma_f32_16x16x32_bf16 v[30:33], v[170:173], v[114:117], v[46:49]
	v_mfma_f32_16x16x32_bf16 v[202:205], v[174:177], v[202:205], v[30:33]
	v_mfma_f32_16x16x32_bf16 v[30:33], v[144:147], v[206:209], v[70:73]
	v_mfma_f32_16x16x32_bf16 v[232:235], v[148:151], v[210:213], v[30:33]
	v_mfma_f32_16x16x32_bf16 v[30:33], v[170:173], v[206:209], v[118:121]
	v_mfma_f32_16x16x32_bf16 v[26:29], v[144:147], v[98:101], v[26:29]
	v_mfma_f32_16x16x32_bf16 v[206:209], v[174:177], v[210:213], v[30:33]
	v_mfma_f32_16x16x32_bf16 v[30:33], v[144:147], v[214:217], v[34:37]
	v_mfma_f32_16x16x32_bf16 v[26:29], v[148:151], v[110:113], v[26:29]
	v_mfma_f32_16x16x32_bf16 v[144:147], v[148:151], v[228:231], v[30:33]
	v_mfma_f32_16x16x32_bf16 v[30:33], v[170:173], v[214:217], v[38:41]
	v_mfma_f32_16x16x32_bf16 v[148:151], v[174:177], v[228:231], v[30:33]
	s_nop 0
	s_barrier
; #define PG8_STAGE(bufoff, gbase, voff) do { _Pragma("unroll") for (int _i = 0; _i < 2; ++_i) \
;         __builtin_amdgcn_global_load_lds((const unsigned*)((const char*)(gbase) + (voff)[_i]), (PG8_LAS unsigned*)(lds + (bufoff) + ldsw + _i * 8192), 16, 0, 0); } while (0)
; #define PG8_LDA(dst, b, h) do { _Pragma("unroll") for (int m = 0; m < 4; ++m) _Pragma("unroll") for (int k = 0; k < 2; ++k) dst[m][k] = *(const PG8_LAS bf16x8*)(lds + PG8_SA(b, h) + aoff + m * 2048 + k * 1024); } while (0)
; #define PG8_LDB(dst, b, h) do { _Pragma("unroll") for (int n = 0; n < 2; ++n) _Pragma("unroll") for (int k = 0; k < 2; ++k) dst[n][k] = *(const PG8_LAS bf16x8*)(lds + PG8_SB(b, h) + boff + n * 2048 + k * 1024); } while (0)
; #define PG8_WAIT_V(n) asm volatile("s_waitcnt vmcnt(" #n ")" ::: "memory")
; #define PG8_WAIT_L(n) asm volatile("s_waitcnt lgkmcnt(" #n ")" ::: "memory")
; #define PG8_BAR __builtin_amdgcn_s_barrier()
; #define PG8_SCHED __builtin_amdgcn_sched_barrier(0)
; template <class Epi, class Sched, bool ALIGN_EPI = false, bool SP2 = false>
; __device__ __forceinline__ void gemm_phase(PG8_LAS unsigned char* lds, const Gemm g, const Sched& S, const Epi& E, const int wave_s) {
;     ...
;             PG8_LDB(B0, 0, 0); PG8_LDB(B1, 0, 1); PG8_SCHED; PG8_LDA(At, 0, 0); PG8_STAGE(PG8_SA(1, 1), a1 + hstepA, voffA);
;             PG8_WAIT_V(8); PG8_WAIT_L(0); PG8_BAR; PG8_MMA(0, 0, At, B0); PG8_MMA(0, 1, At, B1); PG8_BAR; PG8_SCHED;
;             PG8_LDA(At, 0, 1); PG8_STAGE(PG8_SB(0, 0), b2, voffB); PG8_STAGE(PG8_SB(0, 1), b2 + hstepB, voffB); PG8_STAGE(PG8_SA(0, 0), a2, voffA);
;             PG8_WAIT_V(8); PG8_WAIT_L(0); PG8_BAR; PG8_MMA(1, 0, At, B0); PG8_MMA(1, 1, At, B1); PG8_BAR; PG8_SCHED;
;             PG8_LDB(B0, 1, 0); PG8_LDB(B1, 1, 1); PG8_SCHED; PG8_LDA(At, 1, 0); PG8_STAGE(PG8_SA(0, 1), a2 + hstepA, voffA);
;             PG8_WAIT_V(8); PG8_WAIT_L(0); PG8_BAR; PG8_MMA(0, 0, At, B0); PG8_MMA(0, 1, At, B1); PG8_BAR; PG8_SCHED;
;             PG8_LDA(At, 1, 1); PG8_STAGE(PG8_SB(1, 0), b3, voffB); PG8_STAGE(PG8_SB(1, 1), b3 + hstepB, voffB); PG8_STAGE(PG8_SA(1, 0), a3, voffA);
;             PG8_WAIT_V(8); PG8_WAIT_L(0); PG8_BAR; PG8_MMA(1, 0, At, B0); PG8_MMA(1, 1, At, B1); PG8_BAR; PG8_SCHED;
;     ...
;         if constexpr (ALIGN_EPI) { if (wr == 0) PG8_BAR; }
	ds_read_b128 v[38:41], v11
	ds_read_b128 v[170:173], v11 offset:1024
	ds_read_b128 v[174:177], v11 offset:2048
	ds_read_b128 v[210:213], v11 offset:3072
	ds_read_b128 v[214:217], v12
	ds_read_b128 v[228:231], v12 offset:1024
	ds_read_b128 v[240:243], v12 offset:2048
	ds_read_b128 v[244:247], v12 offset:3072
	s_add_u32 s2, s26, 0x84000
	s_addc_u32 s3, s27, 0
	s_mov_b32 m0, s43
	v_lshl_add_u64 v[98:99], s[2:3], 0, v[14:15]
	ds_read_b128 v[10:13], v164 offset:32768
	ds_read_b128 v[30:33], v164 offset:33792
	ds_read_b128 v[34:37], v164 offset:34816
	ds_read_b128 v[46:49], v164 offset:35840
	ds_read_b128 v[70:73], v164 offset:36864
	ds_read_b128 v[248:251], v164 offset:37888
	ds_read_b128 v[178:181], v164 offset:38912
	ds_read_b128 v[190:193], v164 offset:39936
	global_load_lds_dwordx4 v[98:99], off
	v_lshl_add_u64 v[98:99], s[2:3], 0, v[136:137]
	s_mov_b32 m0, s44
	s_nop 0
	global_load_lds_dwordx4 v[98:99], off
	s_waitcnt vmcnt(8)
	s_waitcnt lgkmcnt(0)
	s_barrier
	s_nop 0
	s_waitcnt lgkmcnt(0)
	v_mfma_f32_16x16x32_bf16 v[74:77], v[38:41], v[10:13], v[74:77]
	v_mfma_f32_16x16x32_bf16 v[126:129], v[170:173], v[30:33], v[74:77]
	v_mfma_f32_16x16x32_bf16 v[74:77], v[174:177], v[10:13], v[78:81]
	v_mfma_f32_16x16x32_bf16 v[130:133], v[210:213], v[30:33], v[74:77]
	v_mfma_f32_16x16x32_bf16 v[74:77], v[38:41], v[34:37], v[82:85]
	v_mfma_f32_16x16x32_bf16 v[114:117], v[170:173], v[46:49], v[74:77]
	v_mfma_f32_16x16x32_bf16 v[74:77], v[174:177], v[34:37], v[86:89]
	v_mfma_f32_16x16x32_bf16 v[110:113], v[210:213], v[46:49], v[74:77]
	v_mfma_f32_16x16x32_bf16 v[74:77], v[38:41], v[70:73], v[90:93]
	v_mfma_f32_16x16x32_bf16 v[98:101], v[170:173], v[248:251], v[74:77]
	v_mfma_f32_16x16x32_bf16 v[74:77], v[174:177], v[70:73], v[94:97]
	v_mfma_f32_16x16x32_bf16 v[94:97], v[210:213], v[248:251], v[74:77]
	v_mfma_f32_16x16x32_bf16 v[74:77], v[38:41], v[178:181], v[236:239]
	v_mfma_f32_16x16x32_bf16 v[82:85], v[170:173], v[190:193], v[74:77]
	v_mfma_f32_16x16x32_bf16 v[74:77], v[174:177], v[178:181], v[102:105]
	v_mfma_f32_16x16x32_bf16 v[78:81], v[210:213], v[190:193], v[74:77]
	s_nop 0
	s_nop 0
	v_mfma_f32_16x16x32_bf16 v[74:77], v[214:217], v[10:13], v[106:109]
	v_mfma_f32_16x16x32_bf16 v[10:13], v[240:243], v[10:13], v[194:197]
	v_mfma_f32_16x16x32_bf16 v[118:121], v[244:247], v[30:33], v[10:13]
	v_mfma_f32_16x16x32_bf16 v[10:13], v[214:217], v[34:37], v[198:201]
	v_mfma_f32_16x16x32_bf16 v[106:109], v[228:231], v[46:49], v[10:13]
	v_mfma_f32_16x16x32_bf16 v[10:13], v[240:243], v[34:37], v[50:53]
	v_mfma_f32_16x16x32_bf16 v[102:105], v[244:247], v[46:49], v[10:13]
	v_mfma_f32_16x16x32_bf16 v[10:13], v[214:217], v[70:73], v[54:57]
	v_mfma_f32_16x16x32_bf16 v[90:93], v[228:231], v[248:251], v[10:13]
	v_mfma_f32_16x16x32_bf16 v[10:13], v[240:243], v[70:73], v[58:61]
	v_mfma_f32_16x16x32_bf16 v[86:89], v[244:247], v[248:251], v[10:13]
	v_mfma_f32_16x16x32_bf16 v[10:13], v[214:217], v[178:181], v[62:65]
	v_mfma_f32_16x16x32_bf16 v[122:125], v[228:231], v[30:33], v[74:77]
	v_mfma_f32_16x16x32_bf16 v[74:77], v[228:231], v[190:193], v[10:13]
	v_mfma_f32_16x16x32_bf16 v[10:13], v[240:243], v[178:181], v[66:69]
	v_mfma_f32_16x16x32_bf16 v[70:73], v[244:247], v[190:193], v[10:13]
	s_nop 0
	s_barrier
	s_mov_b32 m0, s55
	s_nop 3
	v_lshl_add_u64 v[10:11], v[186:187], 0, s[58:59]
	s_add_u32 s2, s28, 0x18080
	ds_read_b128 v[54:57], v164 offset:49152
	ds_read_b128 v[178:181], v164 offset:50176
	ds_read_b128 v[190:193], v164 offset:51200
	ds_read_b128 v[194:197], v164 offset:52224
	ds_read_b128 v[198:201], v164 offset:53248
	ds_read_b128 v[236:239], v164 offset:54272
	ds_read_b128 v[248:251], v164 offset:55296
	ds_read_b128 v[182:185], v164 offset:56320
	global_load_lds_dwordx4 v[10:11], off
	v_lshl_add_u64 v[10:11], v[188:189], 0, s[58:59]
	s_mov_b32 m0, s50
	s_addc_u32 s3, s29, 0
	global_load_lds_dwordx4 v[10:11], off
	v_lshl_add_u64 v[10:11], s[2:3], 0, v[134:135]
	s_mov_b32 m0, s51
	s_nop 0
	global_load_lds_dwordx4 v[10:11], off
	v_lshl_add_u64 v[10:11], s[2:3], 0, v[138:139]
	s_mov_b32 m0, s54
	s_nop 0
	global_load_lds_dwordx4 v[10:11], off
	v_lshl_add_u64 v[10:11], v[218:219], 0, s[58:59]
	s_mov_b32 m0, s45
	s_nop 0
	global_load_lds_dwordx4 v[10:11], off
	v_lshl_add_u64 v[10:11], v[220:221], 0, s[58:59]
	s_mov_b32 m0, s46
	s_nop 0
	global_load_lds_dwordx4 v[10:11], off
	s_waitcnt vmcnt(8)
	s_waitcnt lgkmcnt(0)
	s_barrier
	s_nop 0
	s_waitcnt lgkmcnt(0)
	v_mfma_f32_16x16x32_bf16 v[2:5], v[38:41], v[54:57], v[2:5]
	v_mfma_f32_16x16x32_bf16 v[66:69], v[170:173], v[178:181], v[2:5]
	v_mfma_f32_16x16x32_bf16 v[2:5], v[174:177], v[54:57], v[6:9]
	v_mfma_f32_16x16x32_bf16 v[62:65], v[210:213], v[178:181], v[2:5]
	v_mfma_f32_16x16x32_bf16 v[2:5], v[38:41], v[190:193], v[152:155]
	v_mfma_f32_16x16x32_bf16 v[50:53], v[170:173], v[194:197], v[2:5]
	v_mfma_f32_16x16x32_bf16 v[2:5], v[174:177], v[190:193], v[156:159]
	v_mfma_f32_16x16x32_bf16 v[46:49], v[210:213], v[194:197], v[2:5]
	v_mfma_f32_16x16x32_bf16 v[2:5], v[38:41], v[198:201], v[160:163]
	v_mfma_f32_16x16x32_bf16 v[34:37], v[170:173], v[236:239], v[2:5]
	v_mfma_f32_16x16x32_bf16 v[2:5], v[174:177], v[198:201], v[166:169]
	v_mfma_f32_16x16x32_bf16 v[30:33], v[210:213], v[236:239], v[2:5]
	v_mfma_f32_16x16x32_bf16 v[2:5], v[38:41], v[248:251], v[18:21]
	v_mfma_f32_16x16x32_bf16 v[18:21], v[170:173], v[182:185], v[2:5]
	v_mfma_f32_16x16x32_bf16 v[2:5], v[174:177], v[248:251], v[22:25]
	v_mfma_f32_16x16x32_bf16 v[10:13], v[210:213], v[182:185], v[2:5]
	s_nop 0
	s_nop 0
	v_mfma_f32_16x16x32_bf16 v[2:5], v[214:217], v[54:57], v[26:29]
	v_mfma_f32_16x16x32_bf16 v[58:61], v[228:231], v[178:181], v[2:5]
	v_mfma_f32_16x16x32_bf16 v[2:5], v[240:243], v[54:57], v[140:143]
	v_mfma_f32_16x16x32_bf16 v[54:57], v[244:247], v[178:181], v[2:5]
	v_mfma_f32_16x16x32_bf16 v[2:5], v[214:217], v[190:193], v[42:45]
	v_mfma_f32_16x16x32_bf16 v[42:45], v[228:231], v[194:197], v[2:5]
	v_mfma_f32_16x16x32_bf16 v[2:5], v[240:243], v[190:193], v[202:205]
	v_mfma_f32_16x16x32_bf16 v[38:41], v[244:247], v[194:197], v[2:5]
	v_mfma_f32_16x16x32_bf16 v[2:5], v[214:217], v[198:201], v[232:235]
	v_mfma_f32_16x16x32_bf16 v[26:29], v[228:231], v[236:239], v[2:5]
	v_mfma_f32_16x16x32_bf16 v[2:5], v[240:243], v[198:201], v[206:209]
	v_mfma_f32_16x16x32_bf16 v[22:25], v[244:247], v[236:239], v[2:5]
	v_mfma_f32_16x16x32_bf16 v[2:5], v[214:217], v[248:251], v[144:147]
	v_mfma_f32_16x16x32_bf16 v[6:9], v[228:231], v[182:185], v[2:5]
	v_mfma_f32_16x16x32_bf16 v[2:5], v[240:243], v[248:251], v[148:151]
	v_mfma_f32_16x16x32_bf16 v[2:5], v[244:247], v[182:185], v[2:5]
	s_nop 0
	s_barrier
	s_andn2_b64 vcc, exec, s[22:23]
	s_cbranch_vccnz .LBB0_713
	s_barrier

; __device__ __forceinline__ int opaque_tid(int wave_s) { int l; asm volatile("v_mbcnt_lo_u32_b32 %0, -1, 0\n\tv_mbcnt_hi_u32_b32 %0, -1, %0" : "=v"(l)); return (wave_s << 6) | l; }
; #define PG8_WAIT_V(n) asm volatile("s_waitcnt vmcnt(" #n ")" ::: "memory")
; #define PG8_WAIT_L(n) asm volatile("s_waitcnt lgkmcnt(" #n ")" ::: "memory")
; #define PG8_BAR __builtin_amdgcn_s_barrier()
; template <class Epi, class Sched, bool ALIGN_EPI = false, bool SP2 = false>
; __device__ __forceinline__ void gemm_phase(PG8_LAS unsigned char* lds, const Gemm g, const Sched& S, const Epi& E, const int wave_s) {
;     ...
;         const char* nA = has_next ? (const char*)g.A + (size_t)nxt.pm * tstepA : cA; const char* nB = has_next ? (const char*)g.Bt + (size_t)nxt.pn * tstepB : cB;
;         for (int t = 0; t < nt; t += 2) {
;             if constexpr (Epi::KHOOK) { if (t == 6 || t == 12) { const int l3_ = opaque_tid(wave_s) & 63; E.khook(acc, t, wr, l3_ & 15, ui & 1, lds); } }
;             const bool last = (t == nt - 2);
;             const char* a1 = cA + (size_t)(t + 1) * kstep;
;             const char* a2 = last ? nA : cA + (size_t)(t + 2) * kstep; const char* b2 = last ? nB : cB + (size_t)(t + 2) * kstep;
;             const char* a3 = a2 + kstep; const char* b3 = b2 + kstep;
;             if (last && has_next) S.a_ready(nxt);
;             if constexpr (SP2) {
;             PG8_LDB(B0, 0, 0); PG8_LDB(B1, 0, 1); PG8_SCHED; PG8_LDA(At, 0, 0); PG8_STAGE(PG8_SA(1, 1), a1 + hstepA, voffA);
;             PG8_WAIT_V(8); PG8_WAIT_L(0); PG8_BAR; PG8_MMA(0, 0, At, B0); PG8_MMA(0, 1, At, B1); PG8_BAR; PG8_SCHED;
;             PG8_LDA(At, 0, 1); PG8_STAGE(PG8_SB(0, 0), b2, voffB); PG8_STAGE(PG8_SB(0, 1), b2 + hstepB, voffB); PG8_STAGE(PG8_SA(0, 0), a2, voffA);
;             PG8_WAIT_V(8); PG8_WAIT_L(0); PG8_BAR; PG8_MMA(1, 0, At, B0); PG8_MMA(1, 1, At, B1); PG8_BAR; PG8_SCHED;
;             PG8_LDB(B0, 1, 0); PG8_LDB(B1, 1, 1); PG8_SCHED; PG8_LDA(At, 1, 0); PG8_STAGE(PG8_SA(0, 1), a2 + hstepA, voffA);
;             PG8_WAIT_V(8); PG8_WAIT_L(0); PG8_BAR; PG8_MMA(0, 0, At, B0); PG8_MMA(0, 1, At, B1); PG8_BAR; PG8_SCHED;
;             PG8_LDA(At, 1, 1); PG8_STAGE(PG8_SB(1, 0), b3, voffB); PG8_STAGE(PG8_SB(1, 1), b3 + hstepB, voffB); PG8_STAGE(PG8_SA(1, 0), a3, voffA);
;             PG8_WAIT_V(8); PG8_WAIT_L(0); PG8_BAR; PG8_MMA(1, 0, At, B0); PG8_MMA(1, 1, At, B1); PG8_BAR; PG8_SCHED;
.LBB0_759:
	s_ashr_i32 s21, s20, 31
	s_lshl_b64 s[24:25], s[20:21], 17
	s_add_u32 s24, s34, s24
	s_addc_u32 s25, s35, s25
	s_and_b64 s[8:9], s[8:9], exec
	s_cselect_b32 s9, s25, s29
	s_cselect_b32 s8, s24, s28
	s_add_i32 s49, 0, 0x10000
	s_add_i32 s48, 0, 0x14000
	v_add_u32_e32 v140, s49, v17
	v_add_u32_e32 v214, s48, v17
	ds_read_b128 v[2:5], v140
	ds_read_b128 v[6:9], v140 offset:1024
	ds_read_b128 v[10:13], v140 offset:2048
	ds_read_b128 v[18:21], v140 offset:3072
	ds_read_b128 v[22:25], v214
	ds_read_b128 v[26:29], v214 offset:1024
	ds_read_b128 v[30:33], v214 offset:2048
	ds_read_b128 v[34:37], v214 offset:3072
	s_add_u32 s46, s26, 0x84080
	s_addc_u32 s47, s27, 0
	s_add_i32 s51, s37, 0xc000
	v_lshl_add_u64 v[70:71], s[46:47], 0, v[136:137]
	s_mov_b32 m0, s51
	s_add_i32 s21, s37, 0xe000
	ds_read_b128 v[38:41], v141
	ds_read_b128 v[42:45], v141 offset:1024
	ds_read_b128 v[46:49], v141 offset:2048
	ds_read_b128 v[50:53], v141 offset:3072
	ds_read_b128 v[54:57], v141 offset:4096
	ds_read_b128 v[58:61], v141 offset:5120
	ds_read_b128 v[62:65], v141 offset:6144
	ds_read_b128 v[66:69], v141 offset:7168
	global_load_lds_dwordx4 v[70:71], off
	v_lshl_add_u64 v[70:71], s[46:47], 0, v[134:135]
	s_mov_b32 m0, s21
	s_nop 0
	global_load_lds_dwordx4 v[70:71], off
	s_waitcnt vmcnt(8)
	s_waitcnt lgkmcnt(0)
	s_barrier
	s_nop 0
	s_waitcnt lgkmcnt(0)
	v_mfma_f32_16x16x32_bf16 v[70:73], v[2:5], v[38:41], 0
	v_mfma_f32_16x16x32_bf16 v[74:77], v[10:13], v[38:41], 0
	v_mfma_f32_16x16x32_bf16 v[78:81], v[2:5], v[46:49], 0
	v_mfma_f32_16x16x32_bf16 v[82:85], v[10:13], v[46:49], 0
	v_mfma_f32_16x16x32_bf16 v[86:89], v[2:5], v[54:57], 0
	v_mfma_f32_16x16x32_bf16 v[90:93], v[10:13], v[54:57], 0
	v_mfma_f32_16x16x32_bf16 v[94:97], v[2:5], v[62:65], 0
	v_mfma_f32_16x16x32_bf16 v[98:101], v[10:13], v[62:65], 0
	v_mfma_f32_16x16x32_bf16 v[70:73], v[6:9], v[42:45], v[70:73]
	v_mfma_f32_16x16x32_bf16 v[74:77], v[18:21], v[42:45], v[74:77]
	v_mfma_f32_16x16x32_bf16 v[78:81], v[6:9], v[50:53], v[78:81]
	v_mfma_f32_16x16x32_bf16 v[82:85], v[18:21], v[50:53], v[82:85]
	v_mfma_f32_16x16x32_bf16 v[86:89], v[6:9], v[58:61], v[86:89]
	v_mfma_f32_16x16x32_bf16 v[90:93], v[18:21], v[58:61], v[90:93]
	v_mfma_f32_16x16x32_bf16 v[94:97], v[6:9], v[66:69], v[94:97]
	v_mfma_f32_16x16x32_bf16 v[98:101], v[18:21], v[66:69], v[98:101]
	s_nop 0
	s_nop 0
	v_mfma_f32_16x16x32_bf16 v[102:105], v[22:25], v[38:41], 0
	v_mfma_f32_16x16x32_bf16 v[38:41], v[30:33], v[38:41], 0
	v_mfma_f32_16x16x32_bf16 v[102:105], v[26:29], v[42:45], v[102:105]
	v_mfma_f32_16x16x32_bf16 v[38:41], v[34:37], v[42:45], v[38:41]
	v_mfma_f32_16x16x32_bf16 v[42:45], v[22:25], v[46:49], 0
	v_mfma_f32_16x16x32_bf16 v[46:49], v[30:33], v[46:49], 0
	v_mfma_f32_16x16x32_bf16 v[42:45], v[26:29], v[50:53], v[42:45]
	v_mfma_f32_16x16x32_bf16 v[46:49], v[34:37], v[50:53], v[46:49]
	v_mfma_f32_16x16x32_bf16 v[50:53], v[22:25], v[54:57], 0
	v_mfma_f32_16x16x32_bf16 v[54:57], v[30:33], v[54:57], 0
	v_mfma_f32_16x16x32_bf16 v[50:53], v[26:29], v[58:61], v[50:53]
	v_mfma_f32_16x16x32_bf16 v[54:57], v[34:37], v[58:61], v[54:57]
	v_mfma_f32_16x16x32_bf16 v[58:61], v[22:25], v[62:65], 0
	v_mfma_f32_16x16x32_bf16 v[62:65], v[30:33], v[62:65], 0
	v_mfma_f32_16x16x32_bf16 v[58:61], v[26:29], v[66:69], v[58:61]
	v_mfma_f32_16x16x32_bf16 v[62:65], v[34:37], v[66:69], v[62:65]
	s_nop 0
	s_barrier
	s_add_i32 s49, s49, s36
	v_lshl_add_u64 v[138:139], s[28:29], 0, v[0:1]
	s_add_i32 s46, s49, 0x2000
	v_lshl_add_u64 v[142:143], v[138:139], 0, s[60:61]
	s_mov_b32 m0, s49
	v_lshl_add_u64 v[186:187], s[28:29], 0, v[14:15]
	s_add_u32 s54, s28, 0x10100
	ds_read_b128 v[66:69], v141 offset:16384
	ds_read_b128 v[106:109], v141 offset:17408
	ds_read_b128 v[110:113], v141 offset:18432
	ds_read_b128 v[114:117], v141 offset:19456
	ds_read_b128 v[118:121], v141 offset:20480
	ds_read_b128 v[122:125], v141 offset:21504
	ds_read_b128 v[126:129], v141 offset:22528
	ds_read_b128 v[130:133], v141 offset:23552
	global_load_lds_dwordx4 v[142:143], off
	v_lshl_add_u64 v[142:143], v[186:187], 0, s[60:61]
	s_mov_b32 m0, s46
	s_addc_u32 s55, s29, 0
	s_add_i32 s47, s48, s36
	global_load_lds_dwordx4 v[142:143], off
	v_lshl_add_u64 v[142:143], s[54:55], 0, v[0:1]
	s_mov_b32 m0, s47
	s_add_i32 s48, s47, 0x2000
	global_load_lds_dwordx4 v[142:143], off
	v_lshl_add_u64 v[142:143], s[54:55], 0, v[14:15]
	s_mov_b32 m0, s48
	v_lshl_add_u64 v[188:189], s[26:27], 0, v[136:137]
	global_load_lds_dwordx4 v[142:143], off
	v_lshl_add_u64 v[142:143], v[188:189], 0, s[60:61]
	s_mov_b32 m0, s37
	v_lshl_add_u64 v[210:211], s[26:27], 0, v[134:135]
	global_load_lds_dwordx4 v[142:143], off
	v_lshl_add_u64 v[142:143], v[210:211], 0, s[60:61]
	s_mov_b32 m0, s40
	s_nop 0
	global_load_lds_dwordx4 v[142:143], off
	s_waitcnt vmcnt(8)
	s_waitcnt lgkmcnt(0)
	s_barrier
; #define PG8_STAGE(bufoff, gbase, voff) do { _Pragma("unroll") for (int _i = 0; _i < 2; ++_i) \
;         __builtin_amdgcn_global_load_lds((const unsigned*)((const char*)(gbase) + (voff)[_i]), (PG8_LAS unsigned*)(lds + (bufoff) + ldsw + _i * 8192), 16, 0, 0); } while (0)
; #define PG8_LDA(dst, b, h) do { _Pragma("unroll") for (int m = 0; m < 4; ++m) _Pragma("unroll") for (int k = 0; k < 2; ++k) dst[m][k] = *(const PG8_LAS bf16x8*)(lds + PG8_SA(b, h) + aoff + m * 2048 + k * 1024); } while (0)
; #define PG8_LDB(dst, b, h) do { _Pragma("unroll") for (int n = 0; n < 2; ++n) _Pragma("unroll") for (int k = 0; k < 2; ++k) dst[n][k] = *(const PG8_LAS bf16x8*)(lds + PG8_SB(b, h) + boff + n * 2048 + k * 1024); } while (0)
; #define PG8_MMA(ai, bj, At, Bt) do { __builtin_amdgcn_s_setprio(1); _Pragma("unroll") for (int m = 0; m < 4; ++m) _Pragma("unroll") for (int n = 0; n < 2; ++n) _Pragma("unroll") for (int k = 0; k < 2; ++k) \
;         acc[ai][bj][m][n] = __builtin_amdgcn_mfma_f32_16x16x32_bf16(Bt[n][k], At[m][k], acc[ai][bj][m][n], 0, 0, 0); __builtin_amdgcn_s_setprio(0); } while (0)
; #define PG8_BAR __builtin_amdgcn_s_barrier()
; template <class Epi, class Sched, bool ALIGN_EPI = false, bool SP2 = false>
; __device__ __forceinline__ void gemm_phase(PG8_LAS unsigned char* lds, const Gemm g, const Sched& S, const Epi& E, const int wave_s) {
;     ...
;             PG8_LDB(B0, 0, 0); PG8_LDB(B1, 0, 1); PG8_SCHED; PG8_LDA(At, 0, 0); PG8_STAGE(PG8_SA(1, 1), a1 + hstepA, voffA);
;             PG8_WAIT_V(8); PG8_WAIT_L(0); PG8_BAR; PG8_MMA(0, 0, At, B0); PG8_MMA(0, 1, At, B1); PG8_BAR; PG8_SCHED;
;             PG8_LDA(At, 0, 1); PG8_STAGE(PG8_SB(0, 0), b2, voffB); PG8_STAGE(PG8_SB(0, 1), b2 + hstepB, voffB); PG8_STAGE(PG8_SA(0, 0), a2, voffA);
;             PG8_WAIT_V(8); PG8_WAIT_L(0); PG8_BAR; PG8_MMA(1, 0, At, B0); PG8_MMA(1, 1, At, B1); PG8_BAR; PG8_SCHED;
;             PG8_LDB(B0, 1, 0); PG8_LDB(B1, 1, 1); PG8_SCHED; PG8_LDA(At, 1, 0); PG8_STAGE(PG8_SA(0, 1), a2 + hstepA, voffA);
;             PG8_WAIT_V(8); PG8_WAIT_L(0); PG8_BAR; PG8_MMA(0, 0, At, B0); PG8_MMA(0, 1, At, B1); PG8_BAR; PG8_SCHED;
;             PG8_LDA(At, 1, 1); PG8_STAGE(PG8_SB(1, 0), b3, voffB); PG8_STAGE(PG8_SB(1, 1), b3 + hstepB, voffB); PG8_STAGE(PG8_SA(1, 0), a3, voffA);
;             PG8_WAIT_V(8); PG8_WAIT_L(0); PG8_BAR; PG8_MMA(1, 0, At, B0); PG8_MMA(1, 1, At, B1); PG8_BAR; PG8_SCHED;
	s_nop 0
	s_waitcnt lgkmcnt(0)
	v_mfma_f32_16x16x32_bf16 v[142:145], v[2:5], v[66:69], 0
	v_mfma_f32_16x16x32_bf16 v[150:153], v[2:5], v[110:113], 0
	v_mfma_f32_16x16x32_bf16 v[158:161], v[2:5], v[118:121], 0
	v_mfma_f32_16x16x32_bf16 v[2:5], v[2:5], v[126:129], 0
	v_mfma_f32_16x16x32_bf16 v[142:145], v[6:9], v[106:109], v[142:145]
	v_mfma_f32_16x16x32_bf16 v[150:153], v[6:9], v[114:117], v[150:153]
	v_mfma_f32_16x16x32_bf16 v[158:161], v[6:9], v[122:125], v[158:161]
	v_mfma_f32_16x16x32_bf16 v[2:5], v[6:9], v[130:133], v[2:5]
	v_mfma_f32_16x16x32_bf16 v[6:9], v[10:13], v[126:129], 0
	v_mfma_f32_16x16x32_bf16 v[146:149], v[10:13], v[66:69], 0
	v_mfma_f32_16x16x32_bf16 v[154:157], v[10:13], v[110:113], 0
	v_mfma_f32_16x16x32_bf16 v[162:165], v[10:13], v[118:121], 0
	v_mfma_f32_16x16x32_bf16 v[6:9], v[18:21], v[130:133], v[6:9]
	v_mfma_f32_16x16x32_bf16 v[146:149], v[18:21], v[106:109], v[146:149]
	v_mfma_f32_16x16x32_bf16 v[154:157], v[18:21], v[114:117], v[154:157]
	v_mfma_f32_16x16x32_bf16 v[162:165], v[18:21], v[122:125], v[162:165]
	s_nop 0
	s_nop 0
	v_mfma_f32_16x16x32_bf16 v[10:13], v[22:25], v[66:69], 0
	v_mfma_f32_16x16x32_bf16 v[18:21], v[30:33], v[66:69], 0
	v_mfma_f32_16x16x32_bf16 v[10:13], v[26:29], v[106:109], v[10:13]
	v_mfma_f32_16x16x32_bf16 v[18:21], v[34:37], v[106:109], v[18:21]
	v_mfma_f32_16x16x32_bf16 v[66:69], v[22:25], v[110:113], 0
	v_mfma_f32_16x16x32_bf16 v[106:109], v[30:33], v[110:113], 0
	v_mfma_f32_16x16x32_bf16 v[110:113], v[22:25], v[118:121], 0
	v_mfma_f32_16x16x32_bf16 v[22:25], v[22:25], v[126:129], 0
	v_mfma_f32_16x16x32_bf16 v[66:69], v[26:29], v[114:117], v[66:69]
	v_mfma_f32_16x16x32_bf16 v[106:109], v[34:37], v[114:117], v[106:109]
	v_mfma_f32_16x16x32_bf16 v[110:113], v[26:29], v[122:125], v[110:113]
	v_mfma_f32_16x16x32_bf16 v[114:117], v[30:33], v[118:121], 0
	v_mfma_f32_16x16x32_bf16 v[22:25], v[26:29], v[130:133], v[22:25]
	v_mfma_f32_16x16x32_bf16 v[26:29], v[30:33], v[126:129], 0
	v_mfma_f32_16x16x32_bf16 v[114:117], v[34:37], v[122:125], v[114:117]
	v_mfma_f32_16x16x32_bf16 v[26:29], v[34:37], v[130:133], v[26:29]
	s_nop 0
	s_barrier
	s_add_i32 s52, 0, 0x18000
	s_add_i32 s56, 0, 0x1c000
	v_add_u32_e32 v218, s52, v17
	v_add_u32_e32 v219, s56, v17
	ds_read_b128 v[30:33], v218
	ds_read_b128 v[34:37], v218 offset:1024
	ds_read_b128 v[118:121], v218 offset:2048
	ds_read_b128 v[122:125], v218 offset:3072
	ds_read_b128 v[126:129], v219
	ds_read_b128 v[130:133], v219 offset:1024
	ds_read_b128 v[166:169], v219 offset:2048
	ds_read_b128 v[170:173], v219 offset:3072
	s_add_u32 s54, s26, 0x84100
	s_addc_u32 s55, s27, 0
	s_mov_b32 m0, s41
	v_lshl_add_u64 v[212:213], s[54:55], 0, v[136:137]
	ds_read_b128 v[174:177], v141 offset:32768
	ds_read_b128 v[178:181], v141 offset:33792
	ds_read_b128 v[182:185], v141 offset:34816
	ds_read_b128 v[190:193], v141 offset:35840
	ds_read_b128 v[194:197], v141 offset:36864
	ds_read_b128 v[198:201], v141 offset:37888
	ds_read_b128 v[202:205], v141 offset:38912
	ds_read_b128 v[206:209], v141 offset:39936
	global_load_lds_dwordx4 v[212:213], off
	v_lshl_add_u64 v[212:213], s[54:55], 0, v[134:135]
	s_mov_b32 m0, s42
	s_nop 0
	global_load_lds_dwordx4 v[212:213], off
	s_waitcnt vmcnt(8)
	s_waitcnt lgkmcnt(0)
	s_barrier
	s_nop 0
	s_waitcnt lgkmcnt(0)
	v_mfma_f32_16x16x32_bf16 v[70:73], v[30:33], v[174:177], v[70:73]
	v_mfma_f32_16x16x32_bf16 v[74:77], v[118:121], v[174:177], v[74:77]
	v_mfma_f32_16x16x32_bf16 v[78:81], v[30:33], v[182:185], v[78:81]
	v_mfma_f32_16x16x32_bf16 v[82:85], v[118:121], v[182:185], v[82:85]
	v_mfma_f32_16x16x32_bf16 v[86:89], v[30:33], v[194:197], v[86:89]
	v_mfma_f32_16x16x32_bf16 v[90:93], v[118:121], v[194:197], v[90:93]
	v_mfma_f32_16x16x32_bf16 v[94:97], v[30:33], v[202:205], v[94:97]
	v_mfma_f32_16x16x32_bf16 v[98:101], v[118:121], v[202:205], v[98:101]
	v_mfma_f32_16x16x32_bf16 v[70:73], v[34:37], v[178:181], v[70:73]
	v_mfma_f32_16x16x32_bf16 v[74:77], v[122:125], v[178:181], v[74:77]
	v_mfma_f32_16x16x32_bf16 v[78:81], v[34:37], v[190:193], v[78:81]
	v_mfma_f32_16x16x32_bf16 v[82:85], v[122:125], v[190:193], v[82:85]
	v_mfma_f32_16x16x32_bf16 v[86:89], v[34:37], v[198:201], v[86:89]
	v_mfma_f32_16x16x32_bf16 v[90:93], v[122:125], v[198:201], v[90:93]
	v_mfma_f32_16x16x32_bf16 v[94:97], v[34:37], v[206:209], v[94:97]
	v_mfma_f32_16x16x32_bf16 v[98:101], v[122:125], v[206:209], v[98:101]
	s_nop 0
	s_nop 0
	v_mfma_f32_16x16x32_bf16 v[102:105], v[126:129], v[174:177], v[102:105]
	v_mfma_f32_16x16x32_bf16 v[38:41], v[166:169], v[174:177], v[38:41]
	v_mfma_f32_16x16x32_bf16 v[42:45], v[126:129], v[182:185], v[42:45]
	v_mfma_f32_16x16x32_bf16 v[46:49], v[166:169], v[182:185], v[46:49]
	v_mfma_f32_16x16x32_bf16 v[50:53], v[126:129], v[194:197], v[50:53]
	v_mfma_f32_16x16x32_bf16 v[54:57], v[166:169], v[194:197], v[54:57]
	v_mfma_f32_16x16x32_bf16 v[58:61], v[126:129], v[202:205], v[58:61]
	v_mfma_f32_16x16x32_bf16 v[62:65], v[166:169], v[202:205], v[62:65]
	v_mfma_f32_16x16x32_bf16 v[102:105], v[130:133], v[178:181], v[102:105]
	v_mfma_f32_16x16x32_bf16 v[38:41], v[170:173], v[178:181], v[38:41]
	v_mfma_f32_16x16x32_bf16 v[42:45], v[130:133], v[190:193], v[42:45]
	v_mfma_f32_16x16x32_bf16 v[46:49], v[170:173], v[190:193], v[46:49]
	v_mfma_f32_16x16x32_bf16 v[50:53], v[130:133], v[198:201], v[50:53]
	v_mfma_f32_16x16x32_bf16 v[54:57], v[170:173], v[198:201], v[54:57]
	v_mfma_f32_16x16x32_bf16 v[58:61], v[130:133], v[206:209], v[58:61]
	v_mfma_f32_16x16x32_bf16 v[62:65], v[170:173], v[206:209], v[62:65]
	s_nop 0
	s_barrier
; #define PG8_STAGE(bufoff, gbase, voff) do { _Pragma("unroll") for (int _i = 0; _i < 2; ++_i) \
;         __builtin_amdgcn_global_load_lds((const unsigned*)((const char*)(gbase) + (voff)[_i]), (PG8_LAS unsigned*)(lds + (bufoff) + ldsw + _i * 8192), 16, 0, 0); } while (0)
; #define PG8_LDA(dst, b, h) do { _Pragma("unroll") for (int m = 0; m < 4; ++m) _Pragma("unroll") for (int k = 0; k < 2; ++k) dst[m][k] = *(const PG8_LAS bf16x8*)(lds + PG8_SA(b, h) + aoff + m * 2048 + k * 1024); } while (0)
; #define PG8_LDB(dst, b, h) do { _Pragma("unroll") for (int n = 0; n < 2; ++n) _Pragma("unroll") for (int k = 0; k < 2; ++k) dst[n][k] = *(const PG8_LAS bf16x8*)(lds + PG8_SB(b, h) + boff + n * 2048 + k * 1024); } while (0)
; #define PG8_MMA(ai, bj, At, Bt) do { __builtin_amdgcn_s_setprio(1); _Pragma("unroll") for (int m = 0; m < 4; ++m) _Pragma("unroll") for (int n = 0; n < 2; ++n) _Pragma("unroll") for (int k = 0; k < 2; ++k) \
;         acc[ai][bj][m][n] = __builtin_amdgcn_mfma_f32_16x16x32_bf16(Bt[n][k], At[m][k], acc[ai][bj][m][n], 0, 0, 0); __builtin_amdgcn_s_setprio(0); } while (0)
; #define PG8_BAR __builtin_amdgcn_s_barrier()
; template <class Epi, class Sched, bool ALIGN_EPI = false, bool SP2 = false>
; __device__ __forceinline__ void gemm_phase(PG8_LAS unsigned char* lds, const Gemm g, const Sched& S, const Epi& E, const int wave_s) {
;     ...
;             PG8_LDB(B0, 0, 0); PG8_LDB(B1, 0, 1); PG8_SCHED; PG8_LDA(At, 0, 0); PG8_STAGE(PG8_SA(1, 1), a1 + hstepA, voffA);
;             PG8_WAIT_V(8); PG8_WAIT_L(0); PG8_BAR; PG8_MMA(0, 0, At, B0); PG8_MMA(0, 1, At, B1); PG8_BAR; PG8_SCHED;
;             PG8_LDA(At, 0, 1); PG8_STAGE(PG8_SB(0, 0), b2, voffB); PG8_STAGE(PG8_SB(0, 1), b2 + hstepB, voffB); PG8_STAGE(PG8_SA(0, 0), a2, voffA);
;             PG8_WAIT_V(8); PG8_WAIT_L(0); PG8_BAR; PG8_MMA(1, 0, At, B0); PG8_MMA(1, 1, At, B1); PG8_BAR; PG8_SCHED;
;             PG8_LDB(B0, 1, 0); PG8_LDB(B1, 1, 1); PG8_SCHED; PG8_LDA(At, 1, 0); PG8_STAGE(PG8_SA(0, 1), a2 + hstepA, voffA);
;             PG8_WAIT_V(8); PG8_WAIT_L(0); PG8_BAR; PG8_MMA(0, 0, At, B0); PG8_MMA(0, 1, At, B1); PG8_BAR; PG8_SCHED;
;             PG8_LDA(At, 1, 1); PG8_STAGE(PG8_SB(1, 0), b3, voffB); PG8_STAGE(PG8_SB(1, 1), b3 + hstepB, voffB); PG8_STAGE(PG8_SA(1, 0), a3, voffA);
;             PG8_WAIT_V(8); PG8_WAIT_L(0); PG8_BAR; PG8_MMA(1, 0, At, B0); PG8_MMA(1, 1, At, B1); PG8_BAR; PG8_SCHED;
	s_add_i32 s52, s52, s36
	s_add_i32 s50, s52, 0x2000
	v_lshl_add_u64 v[138:139], v[138:139], 0, s[78:79]
	s_mov_b32 m0, s52
	s_add_u32 s54, s28, 0x10180
	ds_read_b128 v[174:177], v141 offset:49152
	ds_read_b128 v[178:181], v141 offset:50176
	ds_read_b128 v[182:185], v141 offset:51200
	ds_read_b128 v[190:193], v141 offset:52224
	ds_read_b128 v[194:197], v141 offset:53248
	ds_read_b128 v[198:201], v141 offset:54272
	ds_read_b128 v[202:205], v141 offset:55296
	ds_read_b128 v[206:209], v141 offset:56320
	global_load_lds_dwordx4 v[138:139], off
	v_lshl_add_u64 v[138:139], v[186:187], 0, s[78:79]
	s_mov_b32 m0, s50
	s_addc_u32 s55, s29, 0
	s_add_i32 s28, s56, s36
	global_load_lds_dwordx4 v[138:139], off
	v_lshl_add_u64 v[138:139], s[54:55], 0, v[0:1]
	s_mov_b32 m0, s28
	s_add_i32 s29, s28, 0x2000
	global_load_lds_dwordx4 v[138:139], off
	v_lshl_add_u64 v[138:139], s[54:55], 0, v[14:15]
	s_mov_b32 m0, s29
	s_nop 0
	global_load_lds_dwordx4 v[138:139], off
	v_lshl_add_u64 v[138:139], v[188:189], 0, s[78:79]
	s_mov_b32 m0, s43
	s_nop 0
	global_load_lds_dwordx4 v[138:139], off
	v_lshl_add_u64 v[138:139], v[210:211], 0, s[78:79]
	s_mov_b32 m0, s44
	s_nop 0
	global_load_lds_dwordx4 v[138:139], off
	s_waitcnt vmcnt(8)
	s_waitcnt lgkmcnt(0)
	s_barrier
	s_nop 0
	s_waitcnt lgkmcnt(0)
	v_mfma_f32_16x16x32_bf16 v[2:5], v[30:33], v[202:205], v[2:5]
	v_mfma_f32_16x16x32_bf16 v[6:9], v[118:121], v[202:205], v[6:9]
	v_mfma_f32_16x16x32_bf16 v[142:145], v[30:33], v[174:177], v[142:145]
	v_mfma_f32_16x16x32_bf16 v[146:149], v[118:121], v[174:177], v[146:149]
	v_mfma_f32_16x16x32_bf16 v[150:153], v[30:33], v[182:185], v[150:153]
	v_mfma_f32_16x16x32_bf16 v[154:157], v[118:121], v[182:185], v[154:157]
	v_mfma_f32_16x16x32_bf16 v[158:161], v[30:33], v[194:197], v[158:161]
	v_mfma_f32_16x16x32_bf16 v[162:165], v[118:121], v[194:197], v[162:165]
	v_mfma_f32_16x16x32_bf16 v[2:5], v[34:37], v[206:209], v[2:5]
	v_mfma_f32_16x16x32_bf16 v[6:9], v[122:125], v[206:209], v[6:9]
	v_mfma_f32_16x16x32_bf16 v[142:145], v[34:37], v[178:181], v[142:145]
	v_mfma_f32_16x16x32_bf16 v[146:149], v[122:125], v[178:181], v[146:149]
	v_mfma_f32_16x16x32_bf16 v[150:153], v[34:37], v[190:193], v[150:153]
	v_mfma_f32_16x16x32_bf16 v[154:157], v[122:125], v[190:193], v[154:157]
	v_mfma_f32_16x16x32_bf16 v[158:161], v[34:37], v[198:201], v[158:161]
	v_mfma_f32_16x16x32_bf16 v[162:165], v[122:125], v[198:201], v[162:165]
	s_nop 0
	s_nop 0
	v_mfma_f32_16x16x32_bf16 v[10:13], v[126:129], v[174:177], v[10:13]
	v_mfma_f32_16x16x32_bf16 v[18:21], v[166:169], v[174:177], v[18:21]
	v_mfma_f32_16x16x32_bf16 v[30:33], v[126:129], v[182:185], v[66:69]
	v_mfma_f32_16x16x32_bf16 v[34:37], v[166:169], v[182:185], v[106:109]
	v_mfma_f32_16x16x32_bf16 v[66:69], v[126:129], v[194:197], v[110:113]
	v_mfma_f32_16x16x32_bf16 v[106:109], v[166:169], v[194:197], v[114:117]
	v_mfma_f32_16x16x32_bf16 v[22:25], v[126:129], v[202:205], v[22:25]
	v_mfma_f32_16x16x32_bf16 v[26:29], v[166:169], v[202:205], v[26:29]
	v_mfma_f32_16x16x32_bf16 v[10:13], v[130:133], v[178:181], v[10:13]
	v_mfma_f32_16x16x32_bf16 v[18:21], v[170:173], v[178:181], v[18:21]
	v_mfma_f32_16x16x32_bf16 v[30:33], v[130:133], v[190:193], v[30:33]
	v_mfma_f32_16x16x32_bf16 v[34:37], v[170:173], v[190:193], v[34:37]
	v_mfma_f32_16x16x32_bf16 v[66:69], v[130:133], v[198:201], v[66:69]
	v_mfma_f32_16x16x32_bf16 v[106:109], v[170:173], v[198:201], v[106:109]
	v_mfma_f32_16x16x32_bf16 v[22:25], v[130:133], v[206:209], v[22:25]
	v_mfma_f32_16x16x32_bf16 v[26:29], v[170:173], v[206:209], v[26:29]
	s_nop 0
	s_barrier
	ds_read_b128 v[110:113], v140
	ds_read_b128 v[114:117], v140 offset:1024
	ds_read_b128 v[118:121], v140 offset:2048
	ds_read_b128 v[122:125], v140 offset:3072
	ds_read_b128 v[126:129], v214
	ds_read_b128 v[130:133], v214 offset:1024
	ds_read_b128 v[166:169], v214 offset:2048
	ds_read_b128 v[170:173], v214 offset:3072
	s_add_u32 s26, s26, 0x84180
	s_addc_u32 s27, s27, 0
	s_mov_b32 m0, s51
	v_lshl_add_u64 v[138:139], s[26:27], 0, v[136:137]
	ds_read_b128 v[174:177], v141
	ds_read_b128 v[178:181], v141 offset:1024
	ds_read_b128 v[182:185], v141 offset:2048
	ds_read_b128 v[190:193], v141 offset:3072
	ds_read_b128 v[194:197], v141 offset:4096
	ds_read_b128 v[198:201], v141 offset:5120
	ds_read_b128 v[202:205], v141 offset:6144
	ds_read_b128 v[206:209], v141 offset:7168
	global_load_lds_dwordx4 v[138:139], off
	v_lshl_add_u64 v[138:139], s[26:27], 0, v[134:135]
	s_mov_b32 m0, s21
	s_nop 0
	global_load_lds_dwordx4 v[138:139], off
	s_waitcnt vmcnt(8)
	s_waitcnt lgkmcnt(0)
	s_barrier
; #define PG8_STAGE(bufoff, gbase, voff) do { _Pragma("unroll") for (int _i = 0; _i < 2; ++_i) \
;         __builtin_amdgcn_global_load_lds((const unsigned*)((const char*)(gbase) + (voff)[_i]), (PG8_LAS unsigned*)(lds + (bufoff) + ldsw + _i * 8192), 16, 0, 0); } while (0)
; #define PG8_LDA(dst, b, h) do { _Pragma("unroll") for (int m = 0; m < 4; ++m) _Pragma("unroll") for (int k = 0; k < 2; ++k) dst[m][k] = *(const PG8_LAS bf16x8*)(lds + PG8_SA(b, h) + aoff + m * 2048 + k * 1024); } while (0)
; #define PG8_LDB(dst, b, h) do { _Pragma("unroll") for (int n = 0; n < 2; ++n) _Pragma("unroll") for (int k = 0; k < 2; ++k) dst[n][k] = *(const PG8_LAS bf16x8*)(lds + PG8_SB(b, h) + boff + n * 2048 + k * 1024); } while (0)
; #define PG8_MMA(ai, bj, At, Bt) do { __builtin_amdgcn_s_setprio(1); _Pragma("unroll") for (int m = 0; m < 4; ++m) _Pragma("unroll") for (int n = 0; n < 2; ++n) _Pragma("unroll") for (int k = 0; k < 2; ++k) \
;         acc[ai][bj][m][n] = __builtin_amdgcn_mfma_f32_16x16x32_bf16(Bt[n][k], At[m][k], acc[ai][bj][m][n], 0, 0, 0); __builtin_amdgcn_s_setprio(0); } while (0)
; #define PG8_BAR __builtin_amdgcn_s_barrier()
; template <class Epi, class Sched, bool ALIGN_EPI = false, bool SP2 = false>
; __device__ __forceinline__ void gemm_phase(PG8_LAS unsigned char* lds, const Gemm g, const Sched& S, const Epi& E, const int wave_s) {
;     ...
;             PG8_LDB(B0, 0, 0); PG8_LDB(B1, 0, 1); PG8_SCHED; PG8_LDA(At, 0, 0); PG8_STAGE(PG8_SA(1, 1), a1 + hstepA, voffA);
;             PG8_WAIT_V(8); PG8_WAIT_L(0); PG8_BAR; PG8_MMA(0, 0, At, B0); PG8_MMA(0, 1, At, B1); PG8_BAR; PG8_SCHED;
;             PG8_LDA(At, 0, 1); PG8_STAGE(PG8_SB(0, 0), b2, voffB); PG8_STAGE(PG8_SB(0, 1), b2 + hstepB, voffB); PG8_STAGE(PG8_SA(0, 0), a2, voffA);
;             PG8_WAIT_V(8); PG8_WAIT_L(0); PG8_BAR; PG8_MMA(1, 0, At, B0); PG8_MMA(1, 1, At, B1); PG8_BAR; PG8_SCHED;
;             PG8_LDB(B0, 1, 0); PG8_LDB(B1, 1, 1); PG8_SCHED; PG8_LDA(At, 1, 0); PG8_STAGE(PG8_SA(0, 1), a2 + hstepA, voffA);
;             PG8_WAIT_V(8); PG8_WAIT_L(0); PG8_BAR; PG8_MMA(0, 0, At, B0); PG8_MMA(0, 1, At, B1); PG8_BAR; PG8_SCHED;
;             PG8_LDA(At, 1, 1); PG8_STAGE(PG8_SB(1, 0), b3, voffB); PG8_STAGE(PG8_SB(1, 1), b3 + hstepB, voffB); PG8_STAGE(PG8_SA(1, 0), a3, voffA);
;             PG8_WAIT_V(8); PG8_WAIT_L(0); PG8_BAR; PG8_MMA(1, 0, At, B0); PG8_MMA(1, 1, At, B1); PG8_BAR; PG8_SCHED;
	s_nop 0
	s_waitcnt lgkmcnt(0)
	v_mfma_f32_16x16x32_bf16 v[70:73], v[110:113], v[174:177], v[70:73]
	v_mfma_f32_16x16x32_bf16 v[74:77], v[118:121], v[174:177], v[74:77]
	v_mfma_f32_16x16x32_bf16 v[78:81], v[110:113], v[182:185], v[78:81]
	v_mfma_f32_16x16x32_bf16 v[82:85], v[118:121], v[182:185], v[82:85]
	v_mfma_f32_16x16x32_bf16 v[86:89], v[110:113], v[194:197], v[86:89]
	v_mfma_f32_16x16x32_bf16 v[90:93], v[118:121], v[194:197], v[90:93]
	v_mfma_f32_16x16x32_bf16 v[94:97], v[110:113], v[202:205], v[94:97]
	v_mfma_f32_16x16x32_bf16 v[70:73], v[114:117], v[178:181], v[70:73]
	v_mfma_f32_16x16x32_bf16 v[74:77], v[122:125], v[178:181], v[74:77]
	v_mfma_f32_16x16x32_bf16 v[78:81], v[114:117], v[190:193], v[78:81]
	v_mfma_f32_16x16x32_bf16 v[82:85], v[122:125], v[190:193], v[82:85]
	v_mfma_f32_16x16x32_bf16 v[86:89], v[114:117], v[198:201], v[86:89]
	v_mfma_f32_16x16x32_bf16 v[90:93], v[122:125], v[198:201], v[90:93]
	v_mfma_f32_16x16x32_bf16 v[210:213], v[114:117], v[206:209], v[94:97]
	v_mfma_f32_16x16x32_bf16 v[94:97], v[118:121], v[202:205], v[98:101]
	v_mfma_f32_16x16x32_bf16 v[214:217], v[122:125], v[206:209], v[94:97]
	s_nop 0
	s_nop 0
	v_mfma_f32_16x16x32_bf16 v[94:97], v[126:129], v[174:177], v[102:105]
	v_mfma_f32_16x16x32_bf16 v[38:41], v[166:169], v[174:177], v[38:41]
	v_mfma_f32_16x16x32_bf16 v[42:45], v[126:129], v[182:185], v[42:45]
	v_mfma_f32_16x16x32_bf16 v[46:49], v[166:169], v[182:185], v[46:49]
	v_mfma_f32_16x16x32_bf16 v[50:53], v[126:129], v[194:197], v[50:53]
	v_mfma_f32_16x16x32_bf16 v[54:57], v[166:169], v[194:197], v[54:57]
	v_mfma_f32_16x16x32_bf16 v[58:61], v[126:129], v[202:205], v[58:61]
	v_mfma_f32_16x16x32_bf16 v[62:65], v[166:169], v[202:205], v[62:65]
	v_mfma_f32_16x16x32_bf16 v[102:105], v[130:133], v[178:181], v[94:97]
	v_mfma_f32_16x16x32_bf16 v[38:41], v[170:173], v[178:181], v[38:41]
	v_mfma_f32_16x16x32_bf16 v[42:45], v[130:133], v[190:193], v[42:45]
	v_mfma_f32_16x16x32_bf16 v[46:49], v[170:173], v[190:193], v[46:49]
	v_mfma_f32_16x16x32_bf16 v[50:53], v[130:133], v[198:201], v[50:53]
	v_mfma_f32_16x16x32_bf16 v[54:57], v[170:173], v[198:201], v[54:57]
	v_mfma_f32_16x16x32_bf16 v[58:61], v[130:133], v[206:209], v[58:61]
	v_mfma_f32_16x16x32_bf16 v[62:65], v[170:173], v[206:209], v[62:65]
	s_nop 0
	s_barrier
	s_mov_b32 m0, s49
	v_lshl_add_u64 v[138:139], s[8:9], 0, v[0:1]
	s_add_u32 s26, s8, 0x10000
	ds_read_b128 v[94:97], v141 offset:16384
	ds_read_b128 v[98:101], v141 offset:17408
	ds_read_b128 v[174:177], v141 offset:18432
	ds_read_b128 v[178:181], v141 offset:19456
	ds_read_b128 v[182:185], v141 offset:20480
	ds_read_b128 v[190:193], v141 offset:21504
	ds_read_b128 v[194:197], v141 offset:22528
	ds_read_b128 v[198:201], v141 offset:23552
	global_load_lds_dwordx4 v[138:139], off
	v_lshl_add_u64 v[252:253], s[8:9], 0, v[14:15]
	s_mov_b32 m0, s46
	s_addc_u32 s27, s9, 0
	global_load_lds_dwordx4 v[252:253], off
	v_lshl_add_u64 v[186:187], s[26:27], 0, v[0:1]
	s_mov_b32 m0, s47
	v_lshl_add_u64 v[222:223], s[22:23], 0, v[136:137]
	global_load_lds_dwordx4 v[186:187], off
	v_lshl_add_u64 v[186:187], s[26:27], 0, v[14:15]
	s_mov_b32 m0, s48
	v_lshl_add_u64 v[226:227], s[22:23], 0, v[134:135]
	global_load_lds_dwordx4 v[186:187], off
	s_mov_b32 m0, s37
	s_nop 0
	global_load_lds_dwordx4 v[222:223], off
	s_mov_b32 m0, s40
	s_nop 0
	global_load_lds_dwordx4 v[226:227], off
	s_waitcnt vmcnt(8)
	s_waitcnt lgkmcnt(0)
	s_barrier
	s_nop 0
	s_waitcnt lgkmcnt(0)
	v_mfma_f32_16x16x32_bf16 v[2:5], v[110:113], v[194:197], v[2:5]
	v_mfma_f32_16x16x32_bf16 v[6:9], v[118:121], v[194:197], v[6:9]
	v_mfma_f32_16x16x32_bf16 v[142:145], v[110:113], v[94:97], v[142:145]
	v_mfma_f32_16x16x32_bf16 v[146:149], v[118:121], v[94:97], v[146:149]
	v_mfma_f32_16x16x32_bf16 v[150:153], v[110:113], v[174:177], v[150:153]
	v_mfma_f32_16x16x32_bf16 v[154:157], v[118:121], v[174:177], v[154:157]
	v_mfma_f32_16x16x32_bf16 v[158:161], v[110:113], v[182:185], v[158:161]
	v_mfma_f32_16x16x32_bf16 v[162:165], v[118:121], v[182:185], v[162:165]
	v_mfma_f32_16x16x32_bf16 v[2:5], v[114:117], v[198:201], v[2:5]
	v_mfma_f32_16x16x32_bf16 v[6:9], v[122:125], v[198:201], v[6:9]
	v_mfma_f32_16x16x32_bf16 v[142:145], v[114:117], v[98:101], v[142:145]
	v_mfma_f32_16x16x32_bf16 v[146:149], v[122:125], v[98:101], v[146:149]
	v_mfma_f32_16x16x32_bf16 v[150:153], v[114:117], v[178:181], v[150:153]
	v_mfma_f32_16x16x32_bf16 v[154:157], v[122:125], v[178:181], v[154:157]
	v_mfma_f32_16x16x32_bf16 v[158:161], v[114:117], v[190:193], v[158:161]
	v_mfma_f32_16x16x32_bf16 v[162:165], v[122:125], v[190:193], v[162:165]
	s_nop 0
	s_nop 0
	v_mfma_f32_16x16x32_bf16 v[10:13], v[126:129], v[94:97], v[10:13]
	v_mfma_f32_16x16x32_bf16 v[202:205], v[130:133], v[98:101], v[10:13]
	v_mfma_f32_16x16x32_bf16 v[10:13], v[166:169], v[94:97], v[18:21]
	v_mfma_f32_16x16x32_bf16 v[206:209], v[170:173], v[98:101], v[10:13]
	v_mfma_f32_16x16x32_bf16 v[10:13], v[126:129], v[174:177], v[30:33]
	v_mfma_f32_16x16x32_bf16 v[228:231], v[130:133], v[178:181], v[10:13]
	v_mfma_f32_16x16x32_bf16 v[10:13], v[166:169], v[174:177], v[34:37]
	v_mfma_f32_16x16x32_bf16 v[174:177], v[170:173], v[178:181], v[10:13]
	v_mfma_f32_16x16x32_bf16 v[10:13], v[126:129], v[182:185], v[66:69]
	v_mfma_f32_16x16x32_bf16 v[178:181], v[130:133], v[190:193], v[10:13]
	v_mfma_f32_16x16x32_bf16 v[10:13], v[166:169], v[182:185], v[106:109]
	v_mfma_f32_16x16x32_bf16 v[182:185], v[170:173], v[190:193], v[10:13]
	v_mfma_f32_16x16x32_bf16 v[10:13], v[126:129], v[194:197], v[22:25]
	v_mfma_f32_16x16x32_bf16 v[190:193], v[130:133], v[198:201], v[10:13]
	v_mfma_f32_16x16x32_bf16 v[10:13], v[166:169], v[194:197], v[26:29]
	v_mfma_f32_16x16x32_bf16 v[166:169], v[170:173], v[198:201], v[10:13]
	s_nop 0
	s_barrier
; #define PG8_STAGE(bufoff, gbase, voff) do { _Pragma("unroll") for (int _i = 0; _i < 2; ++_i) \
;         __builtin_amdgcn_global_load_lds((const unsigned*)((const char*)(gbase) + (voff)[_i]), (PG8_LAS unsigned*)(lds + (bufoff) + ldsw + _i * 8192), 16, 0, 0); } while (0)
; #define PG8_LDA(dst, b, h) do { _Pragma("unroll") for (int m = 0; m < 4; ++m) _Pragma("unroll") for (int k = 0; k < 2; ++k) dst[m][k] = *(const PG8_LAS bf16x8*)(lds + PG8_SA(b, h) + aoff + m * 2048 + k * 1024); } while (0)
; #define PG8_LDB(dst, b, h) do { _Pragma("unroll") for (int n = 0; n < 2; ++n) _Pragma("unroll") for (int k = 0; k < 2; ++k) dst[n][k] = *(const PG8_LAS bf16x8*)(lds + PG8_SB(b, h) + boff + n * 2048 + k * 1024); } while (0)
; #define PG8_WAIT_V(n) asm volatile("s_waitcnt vmcnt(" #n ")" ::: "memory")
; #define PG8_WAIT_L(n) asm volatile("s_waitcnt lgkmcnt(" #n ")" ::: "memory")
; #define PG8_BAR __builtin_amdgcn_s_barrier()
; #define PG8_SCHED __builtin_amdgcn_sched_barrier(0)
; template <class Epi, class Sched, bool ALIGN_EPI = false, bool SP2 = false>
; __device__ __forceinline__ void gemm_phase(PG8_LAS unsigned char* lds, const Gemm g, const Sched& S, const Epi& E, const int wave_s) {
;     ...
;             PG8_LDB(B0, 0, 0); PG8_LDB(B1, 0, 1); PG8_SCHED; PG8_LDA(At, 0, 0); PG8_STAGE(PG8_SA(1, 1), a1 + hstepA, voffA);
;             PG8_WAIT_V(8); PG8_WAIT_L(0); PG8_BAR; PG8_MMA(0, 0, At, B0); PG8_MMA(0, 1, At, B1); PG8_BAR; PG8_SCHED;
;             PG8_LDA(At, 0, 1); PG8_STAGE(PG8_SB(0, 0), b2, voffB); PG8_STAGE(PG8_SB(0, 1), b2 + hstepB, voffB); PG8_STAGE(PG8_SA(0, 0), a2, voffA);
;             PG8_WAIT_V(8); PG8_WAIT_L(0); PG8_BAR; PG8_MMA(1, 0, At, B0); PG8_MMA(1, 1, At, B1); PG8_BAR; PG8_SCHED;
;             PG8_LDB(B0, 1, 0); PG8_LDB(B1, 1, 1); PG8_SCHED; PG8_LDA(At, 1, 0); PG8_STAGE(PG8_SA(0, 1), a2 + hstepA, voffA);
;             PG8_WAIT_V(8); PG8_WAIT_L(0); PG8_BAR; PG8_MMA(0, 0, At, B0); PG8_MMA(0, 1, At, B1); PG8_BAR; PG8_SCHED;
;             PG8_LDA(At, 1, 1); PG8_STAGE(PG8_SB(1, 0), b3, voffB); PG8_STAGE(PG8_SB(1, 1), b3 + hstepB, voffB); PG8_STAGE(PG8_SA(1, 0), a3, voffA);
;             PG8_WAIT_V(8); PG8_WAIT_L(0); PG8_BAR; PG8_MMA(1, 0, At, B0); PG8_MMA(1, 1, At, B1); PG8_BAR; PG8_SCHED;
;     ...
;         if constexpr (ALIGN_EPI) { if (wr == 0) PG8_BAR; }
	s_nop 4
	ds_read_b128 v[10:13], v218
	ds_read_b128 v[18:21], v218 offset:1024
	ds_read_b128 v[22:25], v218 offset:2048
	ds_read_b128 v[26:29], v218 offset:3072
	ds_read_b128 v[170:173], v219
	ds_read_b128 v[194:197], v219 offset:1024
	ds_read_b128 v[198:201], v219 offset:2048
	ds_read_b128 v[232:235], v219 offset:3072
	s_add_u32 s26, s22, 0x84000
	s_addc_u32 s27, s23, 0
	s_mov_b32 m0, s41
	v_lshl_add_u64 v[66:67], s[26:27], 0, v[136:137]
	ds_read_b128 v[30:33], v141 offset:32768
	ds_read_b128 v[34:37], v141 offset:33792
	ds_read_b128 v[236:239], v141 offset:34816
	ds_read_b128 v[240:243], v141 offset:35840
	ds_read_b128 v[244:247], v141 offset:36864
	ds_read_b128 v[248:251], v141 offset:37888
	ds_read_b128 v[186:189], v141 offset:38912
	ds_read_b128 v[218:221], v141 offset:39936
	global_load_lds_dwordx4 v[66:67], off
	v_lshl_add_u64 v[66:67], s[26:27], 0, v[134:135]
	s_mov_b32 m0, s42
	s_nop 0
	global_load_lds_dwordx4 v[66:67], off
	s_waitcnt vmcnt(8)
	s_waitcnt lgkmcnt(0)
	s_barrier
	s_nop 0
	s_waitcnt lgkmcnt(0)
	v_mfma_f32_16x16x32_bf16 v[66:69], v[10:13], v[30:33], v[70:73]
	v_mfma_f32_16x16x32_bf16 v[130:133], v[18:21], v[34:37], v[66:69]
	v_mfma_f32_16x16x32_bf16 v[66:69], v[22:25], v[30:33], v[74:77]
	v_mfma_f32_16x16x32_bf16 v[126:129], v[26:29], v[34:37], v[66:69]
	v_mfma_f32_16x16x32_bf16 v[66:69], v[10:13], v[236:239], v[78:81]
	v_mfma_f32_16x16x32_bf16 v[114:117], v[18:21], v[240:243], v[66:69]
	v_mfma_f32_16x16x32_bf16 v[66:69], v[22:25], v[236:239], v[82:85]
	v_mfma_f32_16x16x32_bf16 v[110:113], v[26:29], v[240:243], v[66:69]
	v_mfma_f32_16x16x32_bf16 v[66:69], v[10:13], v[244:247], v[86:89]
	v_mfma_f32_16x16x32_bf16 v[98:101], v[18:21], v[248:251], v[66:69]
	v_mfma_f32_16x16x32_bf16 v[66:69], v[22:25], v[244:247], v[90:93]
	v_mfma_f32_16x16x32_bf16 v[94:97], v[26:29], v[248:251], v[66:69]
	v_mfma_f32_16x16x32_bf16 v[66:69], v[10:13], v[186:189], v[210:213]
	v_mfma_f32_16x16x32_bf16 v[74:77], v[18:21], v[218:221], v[66:69]
	v_mfma_f32_16x16x32_bf16 v[66:69], v[22:25], v[186:189], v[214:217]
	v_mfma_f32_16x16x32_bf16 v[66:69], v[26:29], v[218:221], v[66:69]
	s_nop 0
	s_nop 0
	v_mfma_f32_16x16x32_bf16 v[70:73], v[170:173], v[30:33], v[102:105]
	v_mfma_f32_16x16x32_bf16 v[30:33], v[198:201], v[30:33], v[38:41]
	v_mfma_f32_16x16x32_bf16 v[118:121], v[232:235], v[34:37], v[30:33]
	v_mfma_f32_16x16x32_bf16 v[30:33], v[170:173], v[236:239], v[42:45]
	v_mfma_f32_16x16x32_bf16 v[106:109], v[194:197], v[240:243], v[30:33]
	v_mfma_f32_16x16x32_bf16 v[30:33], v[198:201], v[236:239], v[46:49]
	v_mfma_f32_16x16x32_bf16 v[102:105], v[232:235], v[240:243], v[30:33]
	v_mfma_f32_16x16x32_bf16 v[30:33], v[170:173], v[244:247], v[50:53]
	v_mfma_f32_16x16x32_bf16 v[90:93], v[194:197], v[248:251], v[30:33]
	v_mfma_f32_16x16x32_bf16 v[30:33], v[198:201], v[244:247], v[54:57]
	v_mfma_f32_16x16x32_bf16 v[86:89], v[232:235], v[248:251], v[30:33]
	v_mfma_f32_16x16x32_bf16 v[30:33], v[170:173], v[186:189], v[58:61]
	v_mfma_f32_16x16x32_bf16 v[58:61], v[194:197], v[218:221], v[30:33]
	v_mfma_f32_16x16x32_bf16 v[30:33], v[198:201], v[186:189], v[62:65]
	v_mfma_f32_16x16x32_bf16 v[122:125], v[194:197], v[34:37], v[70:73]
	v_mfma_f32_16x16x32_bf16 v[54:57], v[232:235], v[218:221], v[30:33]
	s_nop 0
	s_barrier
	s_mov_b32 m0, s52
	s_nop 2
	v_lshl_add_u64 v[30:31], v[138:139], 0, s[58:59]
	s_add_u32 s8, s8, 0x10080
	ds_read_b128 v[38:41], v141 offset:49152
	ds_read_b128 v[42:45], v141 offset:50176
	ds_read_b128 v[186:189], v141 offset:51200
	ds_read_b128 v[210:213], v141 offset:52224
	ds_read_b128 v[214:217], v141 offset:53248
	ds_read_b128 v[218:221], v141 offset:54272
	ds_read_b128 v[236:239], v141 offset:55296
	ds_read_b128 v[240:243], v141 offset:56320
	global_load_lds_dwordx4 v[30:31], off
	v_lshl_add_u64 v[30:31], v[252:253], 0, s[58:59]
	s_mov_b32 m0, s50
	s_addc_u32 s9, s9, 0
	global_load_lds_dwordx4 v[30:31], off
	v_lshl_add_u64 v[30:31], s[8:9], 0, v[0:1]
	s_mov_b32 m0, s28
	s_nop 0
	global_load_lds_dwordx4 v[30:31], off
	v_lshl_add_u64 v[30:31], s[8:9], 0, v[14:15]
	s_mov_b32 m0, s29
	s_nop 0
	global_load_lds_dwordx4 v[30:31], off
	v_lshl_add_u64 v[30:31], v[222:223], 0, s[58:59]
	s_mov_b32 m0, s43
	s_nop 0
	global_load_lds_dwordx4 v[30:31], off
	v_lshl_add_u64 v[30:31], v[226:227], 0, s[58:59]
	s_mov_b32 m0, s44
	s_nop 0
	global_load_lds_dwordx4 v[30:31], off
	s_waitcnt vmcnt(8)
	s_waitcnt lgkmcnt(0)
	s_barrier
	s_nop 0
	s_waitcnt lgkmcnt(0)
	v_mfma_f32_16x16x32_bf16 v[30:33], v[10:13], v[38:41], v[142:145]
	v_mfma_f32_16x16x32_bf16 v[82:85], v[18:21], v[42:45], v[30:33]
	v_mfma_f32_16x16x32_bf16 v[30:33], v[22:25], v[38:41], v[146:149]
	v_mfma_f32_16x16x32_bf16 v[78:81], v[26:29], v[42:45], v[30:33]
	v_mfma_f32_16x16x32_bf16 v[30:33], v[10:13], v[186:189], v[150:153]
	v_mfma_f32_16x16x32_bf16 v[50:53], v[18:21], v[210:213], v[30:33]
	v_mfma_f32_16x16x32_bf16 v[30:33], v[22:25], v[186:189], v[154:157]
	v_mfma_f32_16x16x32_bf16 v[46:49], v[26:29], v[210:213], v[30:33]
	v_mfma_f32_16x16x32_bf16 v[30:33], v[10:13], v[214:217], v[158:161]
	v_mfma_f32_16x16x32_bf16 v[2:5], v[10:13], v[236:239], v[2:5]
	v_mfma_f32_16x16x32_bf16 v[34:37], v[18:21], v[218:221], v[30:33]
	v_mfma_f32_16x16x32_bf16 v[30:33], v[22:25], v[214:217], v[162:165]
	v_mfma_f32_16x16x32_bf16 v[18:21], v[18:21], v[240:243], v[2:5]
	v_mfma_f32_16x16x32_bf16 v[2:5], v[22:25], v[236:239], v[6:9]
	v_mfma_f32_16x16x32_bf16 v[30:33], v[26:29], v[218:221], v[30:33]
	v_mfma_f32_16x16x32_bf16 v[10:13], v[26:29], v[240:243], v[2:5]
	s_nop 0
	s_nop 0
	v_mfma_f32_16x16x32_bf16 v[2:5], v[170:173], v[38:41], v[202:205]
	v_mfma_f32_16x16x32_bf16 v[70:73], v[194:197], v[42:45], v[2:5]
	v_mfma_f32_16x16x32_bf16 v[2:5], v[198:201], v[38:41], v[206:209]
	v_mfma_f32_16x16x32_bf16 v[62:65], v[232:235], v[42:45], v[2:5]
	v_mfma_f32_16x16x32_bf16 v[2:5], v[170:173], v[186:189], v[228:231]
	v_mfma_f32_16x16x32_bf16 v[42:45], v[194:197], v[210:213], v[2:5]
	v_mfma_f32_16x16x32_bf16 v[2:5], v[198:201], v[186:189], v[174:177]
	v_mfma_f32_16x16x32_bf16 v[38:41], v[232:235], v[210:213], v[2:5]
	v_mfma_f32_16x16x32_bf16 v[2:5], v[170:173], v[214:217], v[178:181]
	v_mfma_f32_16x16x32_bf16 v[26:29], v[194:197], v[218:221], v[2:5]
	v_mfma_f32_16x16x32_bf16 v[2:5], v[198:201], v[214:217], v[182:185]
	v_mfma_f32_16x16x32_bf16 v[22:25], v[232:235], v[218:221], v[2:5]
	v_mfma_f32_16x16x32_bf16 v[2:5], v[170:173], v[236:239], v[190:193]
	v_mfma_f32_16x16x32_bf16 v[6:9], v[194:197], v[240:243], v[2:5]
	v_mfma_f32_16x16x32_bf16 v[2:5], v[198:201], v[236:239], v[166:169]
	v_mfma_f32_16x16x32_bf16 v[2:5], v[232:235], v[240:243], v[2:5]
	s_nop 0
	s_barrier
	s_andn2_b64 vcc, exec, s[16:17]
	s_cbranch_vccnz .LBB0_761
	s_barrier

; __device__ __forceinline__ int opaque_tid(int wave_s) { int l; asm volatile("v_mbcnt_lo_u32_b32 %0, -1, 0\n\tv_mbcnt_hi_u32_b32 %0, -1, %0" : "=v"(l)); return (wave_s << 6) | l; }
; #define PG8_STAGE(bufoff, gbase, voff) do { _Pragma("unroll") for (int _i = 0; _i < 2; ++_i) \
;         __builtin_amdgcn_global_load_lds((const unsigned*)((const char*)(gbase) + (voff)[_i]), (PG8_LAS unsigned*)(lds + (bufoff) + ldsw + _i * 8192), 16, 0, 0); } while (0)
; #define PG8_WAIT_V(n) asm volatile("s_waitcnt vmcnt(" #n ")" ::: "memory")
; template <class Epi, class Sched, bool ALIGN_EPI = false, bool SP2 = false>
; __device__ __forceinline__ void gemm_phase(PG8_LAS unsigned char* lds, const Gemm g, const Sched& S, const Epi& E, const int wave_s) {
;     ...
;         for (int t = 0; t < nt; t += 2) {
;             if constexpr (Epi::KHOOK) { if (t == 6 || t == 12) { const int l3_ = opaque_tid(wave_s) & 63; E.khook(acc, t, wr, l3_ & 15, ui & 1, lds); } }
;             const bool last = (t == nt - 2);
;             const char* a1 = cA + (size_t)(t + 1) * kstep;
;             const char* a2 = last ? nA : cA + (size_t)(t + 2) * kstep; const char* b2 = last ? nB : cB + (size_t)(t + 2) * kstep;
;             const char* a3 = a2 + kstep; const char* b3 = b2 + kstep;
;             if (last && has_next) S.a_ready(nxt);
;             if constexpr (SP2) {
;             PG8_LDB(B0, 0, 0); PG8_LDB(B1, 0, 1); PG8_SCHED; PG8_LDA(At, 0, 0); PG8_STAGE(PG8_SA(1, 1), a1 + hstepA, voffA);
;             PG8_WAIT_V(8); PG8_WAIT_L(0); PG8_BAR; PG8_MMA(0, 0, At, B0); PG8_MMA(0, 1, At, B1); PG8_BAR; PG8_SCHED;
;             PG8_LDA(At, 0, 1); PG8_STAGE(PG8_SB(0, 0), b2, voffB); PG8_STAGE(PG8_SB(0, 1), b2 + hstepB, voffB); PG8_STAGE(PG8_SA(0, 0), a2, voffA);
;             PG8_WAIT_V(8); PG8_WAIT_L(0); PG8_BAR; PG8_MMA(1, 0, At, B0); PG8_MMA(1, 1, At, B1); PG8_BAR; PG8_SCHED;
;             PG8_LDB(B0, 1, 0); PG8_LDB(B1, 1, 1); PG8_SCHED; PG8_LDA(At, 1, 0); PG8_STAGE(PG8_SA(0, 1), a2 + hstepA, voffA);
;             PG8_WAIT_V(8); PG8_WAIT_L(0); PG8_BAR; PG8_MMA(0, 0, At, B0); PG8_MMA(0, 1, At, B1); PG8_BAR; PG8_SCHED;
;             PG8_LDA(At, 1, 1); PG8_STAGE(PG8_SB(1, 0), b3, voffB); PG8_STAGE(PG8_SB(1, 1), b3 + hstepB, voffB); PG8_STAGE(PG8_SA(1, 0), a3, voffA);
;             PG8_WAIT_V(8); PG8_WAIT_L(0); PG8_BAR; PG8_MMA(1, 0, At, B0); PG8_MMA(1, 1, At, B1); PG8_BAR; PG8_SCHED;
.LBB0_1078:
	s_add_u32 s2, s6, s86
	s_addc_u32 s3, s7, s87
	s_add_u32 s2, s2, 0x100
	s_addc_u32 s3, s3, 0
	s_add_u32 s4, s56, s86
	s_addc_u32 s5, s57, s87
	s_add_i32 s13, 0, 0x10000
	s_cmpk_eq_i32 s86, 0x700
	s_cselect_b32 s41, s11, s3
	s_cselect_b32 s40, s35, s2
	v_add_u32_e32 v0, s13, v17
	s_cselect_b32 s5, s37, s5
	s_cselect_b32 s4, s54, s4
	s_add_i32 vcc_lo, 0, 0x14000
	ds_read_b128 v[74:77], v0
	ds_read_b128 v[78:81], v0 offset:1024
	ds_read_b128 v[82:85], v0 offset:2048
	ds_read_b128 v[150:153], v0 offset:3072
	v_add_u32_e32 v0, vcc_lo, v17
	ds_read_b128 v[154:157], v0
	ds_read_b128 v[158:161], v0 offset:1024
	ds_read_b128 v[174:177], v0 offset:2048
	ds_read_b128 v[178:181], v0 offset:3072
	v_lshl_add_u64 v[2:3], v[72:73], 0, s[86:87]
	s_add_i32 m0, s51, 0xc000
	ds_read_b128 v[182:185], v227
	ds_read_b128 v[186:189], v227 offset:1024
	ds_read_b128 v[190:193], v227 offset:2048
	ds_read_b128 v[194:197], v227 offset:3072
	ds_read_b128 v[198:201], v227 offset:4096
	ds_read_b128 v[202:205], v227 offset:5120
	ds_read_b128 v[206:209], v227 offset:6144
	ds_read_b128 v[210:213], v227 offset:7168
	global_load_lds_dwordx4 v[2:3], off
	v_lshl_add_u64 v[2:3], v[70:71], 0, s[86:87]
	s_add_i32 m0, s51, 0xe000
	s_nop 0
	global_load_lds_dwordx4 v[2:3], off
	s_waitcnt vmcnt(8)
	s_waitcnt lgkmcnt(0)
	s_barrier
	s_nop 0
	s_waitcnt lgkmcnt(0)
	v_mfma_f32_16x16x32_bf16 v[146:149], v[74:77], v[182:185], v[146:149]
	v_mfma_f32_16x16x32_bf16 v[142:145], v[82:85], v[182:185], v[142:145]
	v_mfma_f32_16x16x32_bf16 v[130:133], v[74:77], v[190:193], v[130:133]
	v_mfma_f32_16x16x32_bf16 v[126:129], v[82:85], v[190:193], v[126:129]
	v_mfma_f32_16x16x32_bf16 v[114:117], v[74:77], v[198:201], v[114:117]
	v_mfma_f32_16x16x32_bf16 v[110:113], v[82:85], v[198:201], v[110:113]
	v_mfma_f32_16x16x32_bf16 v[98:101], v[74:77], v[206:209], v[98:101]
	v_mfma_f32_16x16x32_bf16 v[94:97], v[82:85], v[206:209], v[94:97]
	v_mfma_f32_16x16x32_bf16 v[146:149], v[78:81], v[186:189], v[146:149]
	v_mfma_f32_16x16x32_bf16 v[142:145], v[150:153], v[186:189], v[142:145]
	v_mfma_f32_16x16x32_bf16 v[130:133], v[78:81], v[194:197], v[130:133]
	v_mfma_f32_16x16x32_bf16 v[126:129], v[150:153], v[194:197], v[126:129]
	v_mfma_f32_16x16x32_bf16 v[114:117], v[78:81], v[202:205], v[114:117]
	v_mfma_f32_16x16x32_bf16 v[110:113], v[150:153], v[202:205], v[110:113]
	v_mfma_f32_16x16x32_bf16 v[98:101], v[78:81], v[210:213], v[98:101]
	v_mfma_f32_16x16x32_bf16 v[94:97], v[150:153], v[210:213], v[94:97]
	s_nop 0
	s_nop 0
	v_mfma_f32_16x16x32_bf16 v[138:141], v[154:157], v[182:185], v[138:141]
	v_mfma_f32_16x16x32_bf16 v[134:137], v[174:177], v[182:185], v[134:137]
	v_mfma_f32_16x16x32_bf16 v[122:125], v[154:157], v[190:193], v[122:125]
	v_mfma_f32_16x16x32_bf16 v[118:121], v[174:177], v[190:193], v[118:121]
	v_mfma_f32_16x16x32_bf16 v[106:109], v[154:157], v[198:201], v[106:109]
	v_mfma_f32_16x16x32_bf16 v[102:105], v[174:177], v[198:201], v[102:105]
	v_mfma_f32_16x16x32_bf16 v[90:93], v[154:157], v[206:209], v[90:93]
	v_mfma_f32_16x16x32_bf16 v[86:89], v[174:177], v[206:209], v[86:89]
	v_mfma_f32_16x16x32_bf16 v[138:141], v[158:161], v[186:189], v[138:141]
	v_mfma_f32_16x16x32_bf16 v[134:137], v[178:181], v[186:189], v[134:137]
	v_mfma_f32_16x16x32_bf16 v[122:125], v[158:161], v[194:197], v[122:125]
	v_mfma_f32_16x16x32_bf16 v[118:121], v[178:181], v[194:197], v[118:121]
	v_mfma_f32_16x16x32_bf16 v[106:109], v[158:161], v[202:205], v[106:109]
	v_mfma_f32_16x16x32_bf16 v[102:105], v[178:181], v[202:205], v[102:105]
	v_mfma_f32_16x16x32_bf16 v[90:93], v[158:161], v[210:213], v[90:93]
	v_mfma_f32_16x16x32_bf16 v[86:89], v[178:181], v[210:213], v[86:89]
	s_nop 0
	s_barrier
	s_add_i32 s2, s13, s73
	v_lshl_add_u64 v[214:215], s[4:5], 0, v[164:165]
	s_mov_b32 m0, s2
	ds_read_b128 v[182:185], v227 offset:16384
	ds_read_b128 v[186:189], v227 offset:17408
	ds_read_b128 v[190:193], v227 offset:18432
	ds_read_b128 v[194:197], v227 offset:19456
	ds_read_b128 v[198:201], v227 offset:20480
	ds_read_b128 v[202:205], v227 offset:21504
	ds_read_b128 v[206:209], v227 offset:22528
	ds_read_b128 v[210:213], v227 offset:23552
	global_load_lds_dwordx4 v[214:215], off
	s_add_i32 m0, s2, 0x2000
	s_add_u32 s2, s4, 0x40000
	v_lshl_add_u64 v[216:217], s[4:5], 0, v[168:169]
	s_addc_u32 s3, s5, 0
	s_add_i32 s13, vcc_lo, s73
	global_load_lds_dwordx4 v[216:217], off
	v_lshl_add_u64 v[2:3], s[2:3], 0, v[164:165]
	s_mov_b32 m0, s13
	v_lshl_add_u64 v[218:219], s[40:41], 0, v[162:163]
	global_load_lds_dwordx4 v[2:3], off
	v_lshl_add_u64 v[2:3], s[2:3], 0, v[168:169]
	s_add_i32 m0, s13, 0x2000
	v_lshl_add_u64 v[220:221], s[40:41], 0, v[166:167]
	global_load_lds_dwordx4 v[2:3], off
	s_mov_b32 m0, s51
	s_nop 0
	global_load_lds_dwordx4 v[218:219], off
	s_mov_b32 m0, s80
	s_nop 0
	global_load_lds_dwordx4 v[220:221], off
	s_waitcnt vmcnt(8)
	s_waitcnt lgkmcnt(0)
	s_barrier
; #define PG8_STAGE(bufoff, gbase, voff) do { _Pragma("unroll") for (int _i = 0; _i < 2; ++_i) \
;         __builtin_amdgcn_global_load_lds((const unsigned*)((const char*)(gbase) + (voff)[_i]), (PG8_LAS unsigned*)(lds + (bufoff) + ldsw + _i * 8192), 16, 0, 0); } while (0)
; #define PG8_LDA(dst, b, h) do { _Pragma("unroll") for (int m = 0; m < 4; ++m) _Pragma("unroll") for (int k = 0; k < 2; ++k) dst[m][k] = *(const PG8_LAS bf16x8*)(lds + PG8_SA(b, h) + aoff + m * 2048 + k * 1024); } while (0)
; #define PG8_LDB(dst, b, h) do { _Pragma("unroll") for (int n = 0; n < 2; ++n) _Pragma("unroll") for (int k = 0; k < 2; ++k) dst[n][k] = *(const PG8_LAS bf16x8*)(lds + PG8_SB(b, h) + boff + n * 2048 + k * 1024); } while (0)
; #define PG8_MMA(ai, bj, At, Bt) do { __builtin_amdgcn_s_setprio(1); _Pragma("unroll") for (int m = 0; m < 4; ++m) _Pragma("unroll") for (int n = 0; n < 2; ++n) _Pragma("unroll") for (int k = 0; k < 2; ++k) \
;         acc[ai][bj][m][n] = __builtin_amdgcn_mfma_f32_16x16x32_bf16(Bt[n][k], At[m][k], acc[ai][bj][m][n], 0, 0, 0); __builtin_amdgcn_s_setprio(0); } while (0)
; #define PG8_BAR __builtin_amdgcn_s_barrier()
; template <class Epi, class Sched, bool ALIGN_EPI = false, bool SP2 = false>
; __device__ __forceinline__ void gemm_phase(PG8_LAS unsigned char* lds, const Gemm g, const Sched& S, const Epi& E, const int wave_s) {
;     ...
;             PG8_LDB(B0, 0, 0); PG8_LDB(B1, 0, 1); PG8_SCHED; PG8_LDA(At, 0, 0); PG8_STAGE(PG8_SA(1, 1), a1 + hstepA, voffA);
;             PG8_WAIT_V(8); PG8_WAIT_L(0); PG8_BAR; PG8_MMA(0, 0, At, B0); PG8_MMA(0, 1, At, B1); PG8_BAR; PG8_SCHED;
;             PG8_LDA(At, 0, 1); PG8_STAGE(PG8_SB(0, 0), b2, voffB); PG8_STAGE(PG8_SB(0, 1), b2 + hstepB, voffB); PG8_STAGE(PG8_SA(0, 0), a2, voffA);
;             PG8_WAIT_V(8); PG8_WAIT_L(0); PG8_BAR; PG8_MMA(1, 0, At, B0); PG8_MMA(1, 1, At, B1); PG8_BAR; PG8_SCHED;
;             PG8_LDB(B0, 1, 0); PG8_LDB(B1, 1, 1); PG8_SCHED; PG8_LDA(At, 1, 0); PG8_STAGE(PG8_SA(0, 1), a2 + hstepA, voffA);
;             PG8_WAIT_V(8); PG8_WAIT_L(0); PG8_BAR; PG8_MMA(0, 0, At, B0); PG8_MMA(0, 1, At, B1); PG8_BAR; PG8_SCHED;
;             PG8_LDA(At, 1, 1); PG8_STAGE(PG8_SB(1, 0), b3, voffB); PG8_STAGE(PG8_SB(1, 1), b3 + hstepB, voffB); PG8_STAGE(PG8_SA(1, 0), a3, voffA);
;             PG8_WAIT_V(8); PG8_WAIT_L(0); PG8_BAR; PG8_MMA(1, 0, At, B0); PG8_MMA(1, 1, At, B1); PG8_BAR; PG8_SCHED;
	s_nop 0
	s_waitcnt lgkmcnt(0)
	v_mfma_f32_16x16x32_bf16 v[66:69], v[74:77], v[182:185], v[66:69]
	v_mfma_f32_16x16x32_bf16 v[62:65], v[82:85], v[182:185], v[62:65]
	v_mfma_f32_16x16x32_bf16 v[50:53], v[74:77], v[190:193], v[50:53]
	v_mfma_f32_16x16x32_bf16 v[46:49], v[82:85], v[190:193], v[46:49]
	v_mfma_f32_16x16x32_bf16 v[34:37], v[74:77], v[198:201], v[34:37]
	v_mfma_f32_16x16x32_bf16 v[30:33], v[82:85], v[198:201], v[30:33]
	v_mfma_f32_16x16x32_bf16 v[18:21], v[74:77], v[206:209], v[18:21]
	v_mfma_f32_16x16x32_bf16 v[12:15], v[82:85], v[206:209], v[12:15]
	v_mfma_f32_16x16x32_bf16 v[66:69], v[78:81], v[186:189], v[66:69]
	v_mfma_f32_16x16x32_bf16 v[62:65], v[150:153], v[186:189], v[62:65]
	v_mfma_f32_16x16x32_bf16 v[50:53], v[78:81], v[194:197], v[50:53]
	v_mfma_f32_16x16x32_bf16 v[46:49], v[150:153], v[194:197], v[46:49]
	v_mfma_f32_16x16x32_bf16 v[34:37], v[78:81], v[202:205], v[34:37]
	v_mfma_f32_16x16x32_bf16 v[30:33], v[150:153], v[202:205], v[30:33]
	v_mfma_f32_16x16x32_bf16 v[18:21], v[78:81], v[210:213], v[18:21]
	v_mfma_f32_16x16x32_bf16 v[12:15], v[150:153], v[210:213], v[12:15]
	s_nop 0
	s_nop 0
	v_mfma_f32_16x16x32_bf16 v[58:61], v[154:157], v[182:185], v[58:61]
	v_mfma_f32_16x16x32_bf16 v[54:57], v[174:177], v[182:185], v[54:57]
	v_mfma_f32_16x16x32_bf16 v[42:45], v[154:157], v[190:193], v[42:45]
	v_mfma_f32_16x16x32_bf16 v[38:41], v[174:177], v[190:193], v[38:41]
	v_mfma_f32_16x16x32_bf16 v[26:29], v[154:157], v[198:201], v[26:29]
	v_mfma_f32_16x16x32_bf16 v[22:25], v[174:177], v[198:201], v[22:25]
	v_mfma_f32_16x16x32_bf16 v[8:11], v[154:157], v[206:209], v[8:11]
	v_mfma_f32_16x16x32_bf16 v[2:5], v[174:177], v[206:209], v[4:7]
	v_mfma_f32_16x16x32_bf16 v[58:61], v[158:161], v[186:189], v[58:61]
	v_mfma_f32_16x16x32_bf16 v[54:57], v[178:181], v[186:189], v[54:57]
	v_mfma_f32_16x16x32_bf16 v[42:45], v[158:161], v[194:197], v[42:45]
	v_mfma_f32_16x16x32_bf16 v[38:41], v[178:181], v[194:197], v[38:41]
	v_mfma_f32_16x16x32_bf16 v[26:29], v[158:161], v[202:205], v[26:29]
	v_mfma_f32_16x16x32_bf16 v[22:25], v[178:181], v[202:205], v[22:25]
	v_mfma_f32_16x16x32_bf16 v[8:11], v[158:161], v[210:213], v[8:11]
	v_mfma_f32_16x16x32_bf16 v[2:5], v[178:181], v[210:213], v[2:5]
	s_nop 0
	s_barrier
	s_add_i32 s13, 0, 0x18000
	v_add_u32_e32 v0, s13, v17
	s_add_i32 vcc_lo, 0, 0x1c000
	ds_read_b128 v[74:77], v0
	ds_read_b128 v[78:81], v0 offset:1024
	ds_read_b128 v[82:85], v0 offset:2048
	ds_read_b128 v[150:153], v0 offset:3072
	v_add_u32_e32 v0, vcc_lo, v17
	ds_read_b128 v[154:157], v0
	ds_read_b128 v[158:161], v0 offset:1024
	ds_read_b128 v[174:177], v0 offset:2048
	ds_read_b128 v[178:181], v0 offset:3072
	s_add_u32 s2, s40, 0x40000
	s_addc_u32 s3, s41, 0
	s_mov_b32 m0, s81
	v_lshl_add_u64 v[6:7], s[2:3], 0, v[162:163]
	ds_read_b128 v[182:185], v227 offset:32768
	ds_read_b128 v[186:189], v227 offset:33792
	ds_read_b128 v[190:193], v227 offset:34816
	ds_read_b128 v[194:197], v227 offset:35840
	ds_read_b128 v[198:201], v227 offset:36864
	ds_read_b128 v[202:205], v227 offset:37888
	ds_read_b128 v[206:209], v227 offset:38912
	ds_read_b128 v[210:213], v227 offset:39936
	global_load_lds_dwordx4 v[6:7], off
	v_lshl_add_u64 v[6:7], s[2:3], 0, v[166:167]
	s_mov_b32 m0, s82
	s_nop 0
	global_load_lds_dwordx4 v[6:7], off
	s_waitcnt vmcnt(8)
	s_waitcnt lgkmcnt(0)
	s_barrier
	s_nop 0
	s_waitcnt lgkmcnt(0)
	v_mfma_f32_16x16x32_bf16 v[146:149], v[74:77], v[182:185], v[146:149]
	v_mfma_f32_16x16x32_bf16 v[142:145], v[82:85], v[182:185], v[142:145]
	v_mfma_f32_16x16x32_bf16 v[130:133], v[74:77], v[190:193], v[130:133]
	v_mfma_f32_16x16x32_bf16 v[126:129], v[82:85], v[190:193], v[126:129]
	v_mfma_f32_16x16x32_bf16 v[114:117], v[74:77], v[198:201], v[114:117]
	v_mfma_f32_16x16x32_bf16 v[110:113], v[82:85], v[198:201], v[110:113]
	v_mfma_f32_16x16x32_bf16 v[98:101], v[74:77], v[206:209], v[98:101]
	v_mfma_f32_16x16x32_bf16 v[94:97], v[82:85], v[206:209], v[94:97]
	v_mfma_f32_16x16x32_bf16 v[146:149], v[78:81], v[186:189], v[146:149]
	v_mfma_f32_16x16x32_bf16 v[142:145], v[150:153], v[186:189], v[142:145]
	v_mfma_f32_16x16x32_bf16 v[130:133], v[78:81], v[194:197], v[130:133]
	v_mfma_f32_16x16x32_bf16 v[126:129], v[150:153], v[194:197], v[126:129]
	v_mfma_f32_16x16x32_bf16 v[114:117], v[78:81], v[202:205], v[114:117]
	v_mfma_f32_16x16x32_bf16 v[110:113], v[150:153], v[202:205], v[110:113]
	v_mfma_f32_16x16x32_bf16 v[98:101], v[78:81], v[210:213], v[98:101]
	v_mfma_f32_16x16x32_bf16 v[94:97], v[150:153], v[210:213], v[94:97]
	s_nop 0
	s_nop 0
	v_mfma_f32_16x16x32_bf16 v[138:141], v[154:157], v[182:185], v[138:141]
	v_mfma_f32_16x16x32_bf16 v[134:137], v[174:177], v[182:185], v[134:137]
	v_mfma_f32_16x16x32_bf16 v[122:125], v[154:157], v[190:193], v[122:125]
	v_mfma_f32_16x16x32_bf16 v[118:121], v[174:177], v[190:193], v[118:121]
	v_mfma_f32_16x16x32_bf16 v[106:109], v[154:157], v[198:201], v[106:109]
	v_mfma_f32_16x16x32_bf16 v[102:105], v[174:177], v[198:201], v[102:105]
	v_mfma_f32_16x16x32_bf16 v[90:93], v[154:157], v[206:209], v[90:93]
	v_mfma_f32_16x16x32_bf16 v[86:89], v[174:177], v[206:209], v[86:89]
	v_mfma_f32_16x16x32_bf16 v[138:141], v[158:161], v[186:189], v[138:141]
	v_mfma_f32_16x16x32_bf16 v[134:137], v[178:181], v[186:189], v[134:137]
	v_mfma_f32_16x16x32_bf16 v[122:125], v[158:161], v[194:197], v[122:125]
	v_mfma_f32_16x16x32_bf16 v[118:121], v[178:181], v[194:197], v[118:121]
	v_mfma_f32_16x16x32_bf16 v[106:109], v[158:161], v[202:205], v[106:109]
	v_mfma_f32_16x16x32_bf16 v[102:105], v[178:181], v[202:205], v[102:105]
	v_mfma_f32_16x16x32_bf16 v[90:93], v[158:161], v[210:213], v[90:93]
	v_mfma_f32_16x16x32_bf16 v[86:89], v[178:181], v[210:213], v[86:89]
	s_nop 0
	s_barrier
; __device__ __forceinline__ int opaque_tid(int wave_s) { int l; asm volatile("v_mbcnt_lo_u32_b32 %0, -1, 0\n\tv_mbcnt_hi_u32_b32 %0, -1, %0" : "=v"(l)); return (wave_s << 6) | l; }
; #define PG8_STAGE(bufoff, gbase, voff) do { _Pragma("unroll") for (int _i = 0; _i < 2; ++_i) \
;         __builtin_amdgcn_global_load_lds((const unsigned*)((const char*)(gbase) + (voff)[_i]), (PG8_LAS unsigned*)(lds + (bufoff) + ldsw + _i * 8192), 16, 0, 0); } while (0)
; #define PG8_WAIT_V(n) asm volatile("s_waitcnt vmcnt(" #n ")" ::: "memory")
; template <class Epi, class Sched, bool ALIGN_EPI = false, bool SP2 = false>
; __device__ __forceinline__ void gemm_phase(PG8_LAS unsigned char* lds, const Gemm g, const Sched& S, const Epi& E, const int wave_s) {
;     ...
;         for (int t = 0; t < nt; t += 2) {
;             if constexpr (Epi::KHOOK) { if (t == 6 || t == 12) { const int l3_ = opaque_tid(wave_s) & 63; E.khook(acc, t, wr, l3_ & 15, ui & 1, lds); } }
;             const bool last = (t == nt - 2);
;             const char* a1 = cA + (size_t)(t + 1) * kstep;
;             const char* a2 = last ? nA : cA + (size_t)(t + 2) * kstep; const char* b2 = last ? nB : cB + (size_t)(t + 2) * kstep;
;             const char* a3 = a2 + kstep; const char* b3 = b2 + kstep;
;             if (last && has_next) S.a_ready(nxt);
;             if constexpr (SP2) {
;             PG8_LDB(B0, 0, 0); PG8_LDB(B1, 0, 1); PG8_SCHED; PG8_LDA(At, 0, 0); PG8_STAGE(PG8_SA(1, 1), a1 + hstepA, voffA);
;             PG8_WAIT_V(8); PG8_WAIT_L(0); PG8_BAR; PG8_MMA(0, 0, At, B0); PG8_MMA(0, 1, At, B1); PG8_BAR; PG8_SCHED;
;             PG8_LDA(At, 0, 1); PG8_STAGE(PG8_SB(0, 0), b2, voffB); PG8_STAGE(PG8_SB(0, 1), b2 + hstepB, voffB); PG8_STAGE(PG8_SA(0, 0), a2, voffA);
;             PG8_WAIT_V(8); PG8_WAIT_L(0); PG8_BAR; PG8_MMA(1, 0, At, B0); PG8_MMA(1, 1, At, B1); PG8_BAR; PG8_SCHED;
;             PG8_LDB(B0, 1, 0); PG8_LDB(B1, 1, 1); PG8_SCHED; PG8_LDA(At, 1, 0); PG8_STAGE(PG8_SA(0, 1), a2 + hstepA, voffA);
;             PG8_WAIT_V(8); PG8_WAIT_L(0); PG8_BAR; PG8_MMA(0, 0, At, B0); PG8_MMA(0, 1, At, B1); PG8_BAR; PG8_SCHED;
;             PG8_LDA(At, 1, 1); PG8_STAGE(PG8_SB(1, 0), b3, voffB); PG8_STAGE(PG8_SB(1, 1), b3 + hstepB, voffB); PG8_STAGE(PG8_SA(1, 0), a3, voffA);
;             PG8_WAIT_V(8); PG8_WAIT_L(0); PG8_BAR; PG8_MMA(1, 0, At, B0); PG8_MMA(1, 1, At, B1); PG8_BAR; PG8_SCHED;
	s_add_i32 s2, s13, s73
	v_lshl_add_u64 v[6:7], v[214:215], 0, s[58:59]
	s_mov_b32 m0, s2
	ds_read_b128 v[182:185], v227 offset:49152
	ds_read_b128 v[186:189], v227 offset:50176
	ds_read_b128 v[190:193], v227 offset:51200
	ds_read_b128 v[194:197], v227 offset:52224
	ds_read_b128 v[198:201], v227 offset:53248
	ds_read_b128 v[202:205], v227 offset:54272
	ds_read_b128 v[206:209], v227 offset:55296
	ds_read_b128 v[210:213], v227 offset:56320
	global_load_lds_dwordx4 v[6:7], off
	s_add_i32 m0, s2, 0x2000
	s_add_u32 s2, s4, 0x40080
	v_lshl_add_u64 v[6:7], v[216:217], 0, s[58:59]
	s_addc_u32 s3, s5, 0
	s_add_i32 s4, vcc_lo, s73
	global_load_lds_dwordx4 v[6:7], off
	v_lshl_add_u64 v[6:7], s[2:3], 0, v[164:165]
	s_mov_b32 m0, s4
	s_nop 0
	global_load_lds_dwordx4 v[6:7], off
	v_lshl_add_u64 v[6:7], s[2:3], 0, v[168:169]
	s_add_i32 m0, s4, 0x2000
	s_nop 0
	global_load_lds_dwordx4 v[6:7], off
	v_lshl_add_u64 v[6:7], v[218:219], 0, s[58:59]
	s_mov_b32 m0, s92
	s_nop 0
	global_load_lds_dwordx4 v[6:7], off
	v_lshl_add_u64 v[6:7], v[220:221], 0, s[58:59]
	s_mov_b32 m0, s93
	s_nop 0
	global_load_lds_dwordx4 v[6:7], off
	s_waitcnt vmcnt(8)
	s_waitcnt lgkmcnt(0)
	s_barrier
	s_nop 0
	s_waitcnt lgkmcnt(0)
	v_mfma_f32_16x16x32_bf16 v[66:69], v[74:77], v[182:185], v[66:69]
	v_mfma_f32_16x16x32_bf16 v[62:65], v[82:85], v[182:185], v[62:65]
	v_mfma_f32_16x16x32_bf16 v[50:53], v[74:77], v[190:193], v[50:53]
	v_mfma_f32_16x16x32_bf16 v[46:49], v[82:85], v[190:193], v[46:49]
	v_mfma_f32_16x16x32_bf16 v[34:37], v[74:77], v[198:201], v[34:37]
	v_mfma_f32_16x16x32_bf16 v[30:33], v[82:85], v[198:201], v[30:33]
	v_mfma_f32_16x16x32_bf16 v[18:21], v[74:77], v[206:209], v[18:21]
	v_mfma_f32_16x16x32_bf16 v[12:15], v[82:85], v[206:209], v[12:15]
	v_mfma_f32_16x16x32_bf16 v[66:69], v[78:81], v[186:189], v[66:69]
	v_mfma_f32_16x16x32_bf16 v[62:65], v[150:153], v[186:189], v[62:65]
	v_mfma_f32_16x16x32_bf16 v[50:53], v[78:81], v[194:197], v[50:53]
	v_mfma_f32_16x16x32_bf16 v[46:49], v[150:153], v[194:197], v[46:49]
	v_mfma_f32_16x16x32_bf16 v[34:37], v[78:81], v[202:205], v[34:37]
	v_mfma_f32_16x16x32_bf16 v[30:33], v[150:153], v[202:205], v[30:33]
	v_mfma_f32_16x16x32_bf16 v[18:21], v[78:81], v[210:213], v[18:21]
	v_mfma_f32_16x16x32_bf16 v[12:15], v[150:153], v[210:213], v[12:15]
	s_nop 0
	s_nop 0
	v_mfma_f32_16x16x32_bf16 v[58:61], v[154:157], v[182:185], v[58:61]
	v_mfma_f32_16x16x32_bf16 v[54:57], v[174:177], v[182:185], v[54:57]
	v_mfma_f32_16x16x32_bf16 v[42:45], v[154:157], v[190:193], v[42:45]
	v_mfma_f32_16x16x32_bf16 v[38:41], v[174:177], v[190:193], v[38:41]
	v_mfma_f32_16x16x32_bf16 v[26:29], v[154:157], v[198:201], v[26:29]
	v_mfma_f32_16x16x32_bf16 v[22:25], v[174:177], v[198:201], v[22:25]
	v_mfma_f32_16x16x32_bf16 v[6:9], v[154:157], v[206:209], v[8:11]
	v_mfma_f32_16x16x32_bf16 v[2:5], v[174:177], v[206:209], v[2:5]
	v_mfma_f32_16x16x32_bf16 v[58:61], v[158:161], v[186:189], v[58:61]
	v_mfma_f32_16x16x32_bf16 v[54:57], v[178:181], v[186:189], v[54:57]
	v_mfma_f32_16x16x32_bf16 v[42:45], v[158:161], v[194:197], v[42:45]
	v_mfma_f32_16x16x32_bf16 v[38:41], v[178:181], v[194:197], v[38:41]
	v_mfma_f32_16x16x32_bf16 v[26:29], v[158:161], v[202:205], v[26:29]
	v_mfma_f32_16x16x32_bf16 v[22:25], v[178:181], v[202:205], v[22:25]
	v_mfma_f32_16x16x32_bf16 v[8:11], v[158:161], v[210:213], v[6:9]
	v_mfma_f32_16x16x32_bf16 v[4:7], v[178:181], v[210:213], v[2:5]
	s_nop 0
	s_barrier
	s_add_i32 s2, s12, 2
	s_add_u32 s86, s86, 0x100
	s_addc_u32 s87, s87, 0
	s_cmp_gt_u32 s12, 13
	s_cbranch_scc1 .LBB0_1081
	s_mov_b32 s12, s2
	s_cmp_lt_i32 s12, 12
	s_cbranch_scc1 .LBB0_1072

; __device__ __forceinline__ int opaque_tid(int wave_s) { int l; asm volatile("v_mbcnt_lo_u32_b32 %0, -1, 0\n\tv_mbcnt_hi_u32_b32 %0, -1, %0" : "=v"(l)); return (wave_s << 6) | l; }
; #define PG8_STAGE(bufoff, gbase, voff) do { _Pragma("unroll") for (int _i = 0; _i < 2; ++_i) \
;         __builtin_amdgcn_global_load_lds((const unsigned*)((const char*)(gbase) + (voff)[_i]), (PG8_LAS unsigned*)(lds + (bufoff) + ldsw + _i * 8192), 16, 0, 0); } while (0)
; #define PG8_WAIT_V(n) asm volatile("s_waitcnt vmcnt(" #n ")" ::: "memory")
; template <class Epi, class Sched, bool ALIGN_EPI = false, bool SP2 = false>
; __device__ __forceinline__ void gemm_phase(PG8_LAS unsigned char* lds, const Gemm g, const Sched& S, const Epi& E, const int wave_s) {
;     ...
;         for (int t = 0; t < nt; t += 2) {
;             if constexpr (Epi::KHOOK) { if (t == 6 || t == 12) { const int l3_ = opaque_tid(wave_s) & 63; E.khook(acc, t, wr, l3_ & 15, ui & 1, lds); } }
;             const bool last = (t == nt - 2);
;             const char* a1 = cA + (size_t)(t + 1) * kstep;
;             const char* a2 = last ? nA : cA + (size_t)(t + 2) * kstep; const char* b2 = last ? nB : cB + (size_t)(t + 2) * kstep;
;             const char* a3 = a2 + kstep; const char* b3 = b2 + kstep;
;             if (last && has_next) S.a_ready(nxt);
;             if constexpr (SP2) {
;             PG8_LDB(B0, 0, 0); PG8_LDB(B1, 0, 1); PG8_SCHED; PG8_LDA(At, 0, 0); PG8_STAGE(PG8_SA(1, 1), a1 + hstepA, voffA);
;             PG8_WAIT_V(8); PG8_WAIT_L(0); PG8_BAR; PG8_MMA(0, 0, At, B0); PG8_MMA(0, 1, At, B1); PG8_BAR; PG8_SCHED;
;             PG8_LDA(At, 0, 1); PG8_STAGE(PG8_SB(0, 0), b2, voffB); PG8_STAGE(PG8_SB(0, 1), b2 + hstepB, voffB); PG8_STAGE(PG8_SA(0, 0), a2, voffA);
;             PG8_WAIT_V(8); PG8_WAIT_L(0); PG8_BAR; PG8_MMA(1, 0, At, B0); PG8_MMA(1, 1, At, B1); PG8_BAR; PG8_SCHED;
;             PG8_LDB(B0, 1, 0); PG8_LDB(B1, 1, 1); PG8_SCHED; PG8_LDA(At, 1, 0); PG8_STAGE(PG8_SA(0, 1), a2 + hstepA, voffA);
;             PG8_WAIT_V(8); PG8_WAIT_L(0); PG8_BAR; PG8_MMA(0, 0, At, B0); PG8_MMA(0, 1, At, B1); PG8_BAR; PG8_SCHED;
;             PG8_LDA(At, 1, 1); PG8_STAGE(PG8_SB(1, 0), b3, voffB); PG8_STAGE(PG8_SB(1, 1), b3 + hstepB, voffB); PG8_STAGE(PG8_SA(1, 0), a3, voffA);
;             PG8_WAIT_V(8); PG8_WAIT_L(0); PG8_BAR; PG8_MMA(1, 0, At, B0); PG8_MMA(1, 1, At, B1); PG8_BAR; PG8_SCHED;
.LBB0_1165:
	s_add_u32 s4, s6, 0xfffc0800
	s_addc_u32 s5, s7, -1
	s_add_i32 s57, 0, 0x10000
	s_cmp_eq_u32 s56, 12
	s_cselect_b32 s31, s2, s5
	s_cselect_b32 s30, s3, s4
	v_add_u32_e32 v0, s57, v17
	s_cselect_b32 s5, s19, s55
	s_cselect_b32 s4, s21, s54
	s_add_i32 s73, 0, 0x14000
	ds_read_b128 v[90:93], v0
	ds_read_b128 v[98:101], v0 offset:1024
	ds_read_b128 v[102:105], v0 offset:2048
	ds_read_b128 v[106:109], v0 offset:3072
	v_add_u32_e32 v0, s73, v17
	ds_read_b128 v[160:163], v0
	ds_read_b128 v[168:171], v0 offset:1024
	ds_read_b128 v[172:175], v0 offset:2048
	ds_read_b128 v[176:179], v0 offset:3072
	v_lshl_add_u64 v[164:165], s[6:7], 0, v[158:159]
	s_add_i32 m0, s27, 0xc000
	ds_read_b128 v[180:183], v166
	ds_read_b128 v[184:187], v166 offset:1024
	ds_read_b128 v[188:191], v166 offset:2048
	ds_read_b128 v[192:195], v166 offset:3072
	ds_read_b128 v[196:199], v166 offset:4096
	ds_read_b128 v[200:203], v166 offset:5120
	ds_read_b128 v[204:207], v166 offset:6144
	ds_read_b128 v[208:211], v166 offset:7168
	global_load_lds_dwordx4 v[164:165], off
	v_lshl_add_u64 v[164:165], s[6:7], 0, v[156:157]
	s_add_i32 m0, s27, 0xe000
	s_nop 0
	global_load_lds_dwordx4 v[164:165], off
	s_waitcnt vmcnt(8)
	s_waitcnt lgkmcnt(0)
	s_barrier
	s_nop 0
	s_waitcnt lgkmcnt(0)
	v_mfma_f32_16x16x32_bf16 v[146:149], v[90:93], v[180:183], v[146:149]
	v_mfma_f32_16x16x32_bf16 v[142:145], v[102:105], v[180:183], v[142:145]
	v_mfma_f32_16x16x32_bf16 v[130:133], v[90:93], v[188:191], v[130:133]
	v_mfma_f32_16x16x32_bf16 v[126:129], v[102:105], v[188:191], v[126:129]
	v_mfma_f32_16x16x32_bf16 v[114:117], v[90:93], v[196:199], v[114:117]
	v_mfma_f32_16x16x32_bf16 v[110:113], v[102:105], v[196:199], v[110:113]
	v_mfma_f32_16x16x32_bf16 v[82:85], v[90:93], v[204:207], v[82:85]
	v_mfma_f32_16x16x32_bf16 v[78:81], v[102:105], v[204:207], v[78:81]
	v_mfma_f32_16x16x32_bf16 v[146:149], v[98:101], v[184:187], v[146:149]
	v_mfma_f32_16x16x32_bf16 v[142:145], v[106:109], v[184:187], v[142:145]
	v_mfma_f32_16x16x32_bf16 v[130:133], v[98:101], v[192:195], v[130:133]
	v_mfma_f32_16x16x32_bf16 v[126:129], v[106:109], v[192:195], v[126:129]
	v_mfma_f32_16x16x32_bf16 v[114:117], v[98:101], v[200:203], v[114:117]
	v_mfma_f32_16x16x32_bf16 v[110:113], v[106:109], v[200:203], v[110:113]
	v_mfma_f32_16x16x32_bf16 v[82:85], v[98:101], v[208:211], v[82:85]
	v_mfma_f32_16x16x32_bf16 v[78:81], v[106:109], v[208:211], v[78:81]
	s_nop 0
	s_nop 0
	v_mfma_f32_16x16x32_bf16 v[138:141], v[160:163], v[180:183], v[138:141]
	v_mfma_f32_16x16x32_bf16 v[134:137], v[172:175], v[180:183], v[134:137]
	v_mfma_f32_16x16x32_bf16 v[122:125], v[160:163], v[188:191], v[122:125]
	v_mfma_f32_16x16x32_bf16 v[118:121], v[172:175], v[188:191], v[118:121]
	v_mfma_f32_16x16x32_bf16 v[94:97], v[160:163], v[196:199], v[94:97]
	v_mfma_f32_16x16x32_bf16 v[86:89], v[172:175], v[196:199], v[86:89]
	v_mfma_f32_16x16x32_bf16 v[74:77], v[160:163], v[204:207], v[74:77]
	v_mfma_f32_16x16x32_bf16 v[70:73], v[172:175], v[204:207], v[70:73]
	v_mfma_f32_16x16x32_bf16 v[138:141], v[168:171], v[184:187], v[138:141]
	v_mfma_f32_16x16x32_bf16 v[134:137], v[176:179], v[184:187], v[134:137]
	v_mfma_f32_16x16x32_bf16 v[122:125], v[168:171], v[192:195], v[122:125]
	v_mfma_f32_16x16x32_bf16 v[118:121], v[176:179], v[192:195], v[118:121]
	v_mfma_f32_16x16x32_bf16 v[94:97], v[168:171], v[200:203], v[94:97]
	v_mfma_f32_16x16x32_bf16 v[86:89], v[176:179], v[200:203], v[86:89]
	v_mfma_f32_16x16x32_bf16 v[74:77], v[168:171], v[208:211], v[74:77]
	v_mfma_f32_16x16x32_bf16 v[70:73], v[176:179], v[208:211], v[70:73]
	s_nop 0
	s_barrier
	s_add_i32 s57, s57, s44
	v_lshl_add_u64 v[164:165], s[4:5], 0, v[150:151]
	s_mov_b32 m0, s57
	ds_read_b128 v[180:183], v166 offset:16384
	ds_read_b128 v[184:187], v166 offset:17408
	ds_read_b128 v[188:191], v166 offset:18432
	ds_read_b128 v[192:195], v166 offset:19456
	ds_read_b128 v[196:199], v166 offset:20480
	ds_read_b128 v[200:203], v166 offset:21504
	ds_read_b128 v[204:207], v166 offset:22528
	ds_read_b128 v[208:211], v166 offset:23552
	global_load_lds_dwordx4 v[164:165], off
	s_add_i32 m0, s57, 0x2000
	s_add_u32 s66, s4, 0x40000
	v_lshl_add_u64 v[212:213], s[4:5], 0, v[154:155]
	s_addc_u32 s67, s5, 0
	s_add_i32 s57, s73, s44
	global_load_lds_dwordx4 v[212:213], off
	v_lshl_add_u64 v[214:215], s[66:67], 0, v[150:151]
	s_mov_b32 m0, s57
	v_lshl_add_u64 v[216:217], s[30:31], 0, v[152:153]
	global_load_lds_dwordx4 v[214:215], off
	v_lshl_add_u64 v[214:215], s[66:67], 0, v[154:155]
	s_add_i32 m0, s57, 0x2000
	s_nop 0
	global_load_lds_dwordx4 v[214:215], off
	v_lshl_add_u64 v[214:215], s[30:31], 0, v[14:15]
	s_mov_b32 m0, s27
	s_nop 0
	global_load_lds_dwordx4 v[214:215], off
	s_mov_b32 m0, s29
	s_nop 0
	global_load_lds_dwordx4 v[216:217], off
	s_waitcnt vmcnt(8)
	s_waitcnt lgkmcnt(0)
	s_barrier
; #define PG8_STAGE(bufoff, gbase, voff) do { _Pragma("unroll") for (int _i = 0; _i < 2; ++_i) \
;         __builtin_amdgcn_global_load_lds((const unsigned*)((const char*)(gbase) + (voff)[_i]), (PG8_LAS unsigned*)(lds + (bufoff) + ldsw + _i * 8192), 16, 0, 0); } while (0)
; #define PG8_LDA(dst, b, h) do { _Pragma("unroll") for (int m = 0; m < 4; ++m) _Pragma("unroll") for (int k = 0; k < 2; ++k) dst[m][k] = *(const PG8_LAS bf16x8*)(lds + PG8_SA(b, h) + aoff + m * 2048 + k * 1024); } while (0)
; #define PG8_LDB(dst, b, h) do { _Pragma("unroll") for (int n = 0; n < 2; ++n) _Pragma("unroll") for (int k = 0; k < 2; ++k) dst[n][k] = *(const PG8_LAS bf16x8*)(lds + PG8_SB(b, h) + boff + n * 2048 + k * 1024); } while (0)
; #define PG8_MMA(ai, bj, At, Bt) do { __builtin_amdgcn_s_setprio(1); _Pragma("unroll") for (int m = 0; m < 4; ++m) _Pragma("unroll") for (int n = 0; n < 2; ++n) _Pragma("unroll") for (int k = 0; k < 2; ++k) \
;         acc[ai][bj][m][n] = __builtin_amdgcn_mfma_f32_16x16x32_bf16(Bt[n][k], At[m][k], acc[ai][bj][m][n], 0, 0, 0); __builtin_amdgcn_s_setprio(0); } while (0)
; #define PG8_BAR __builtin_amdgcn_s_barrier()
; template <class Epi, class Sched, bool ALIGN_EPI = false, bool SP2 = false>
; __device__ __forceinline__ void gemm_phase(PG8_LAS unsigned char* lds, const Gemm g, const Sched& S, const Epi& E, const int wave_s) {
;     ...
;             PG8_LDB(B0, 0, 0); PG8_LDB(B1, 0, 1); PG8_SCHED; PG8_LDA(At, 0, 0); PG8_STAGE(PG8_SA(1, 1), a1 + hstepA, voffA);
;             PG8_WAIT_V(8); PG8_WAIT_L(0); PG8_BAR; PG8_MMA(0, 0, At, B0); PG8_MMA(0, 1, At, B1); PG8_BAR; PG8_SCHED;
;             PG8_LDA(At, 0, 1); PG8_STAGE(PG8_SB(0, 0), b2, voffB); PG8_STAGE(PG8_SB(0, 1), b2 + hstepB, voffB); PG8_STAGE(PG8_SA(0, 0), a2, voffA);
;             PG8_WAIT_V(8); PG8_WAIT_L(0); PG8_BAR; PG8_MMA(1, 0, At, B0); PG8_MMA(1, 1, At, B1); PG8_BAR; PG8_SCHED;
;             PG8_LDB(B0, 1, 0); PG8_LDB(B1, 1, 1); PG8_SCHED; PG8_LDA(At, 1, 0); PG8_STAGE(PG8_SA(0, 1), a2 + hstepA, voffA);
;             PG8_WAIT_V(8); PG8_WAIT_L(0); PG8_BAR; PG8_MMA(0, 0, At, B0); PG8_MMA(0, 1, At, B1); PG8_BAR; PG8_SCHED;
;             PG8_LDA(At, 1, 1); PG8_STAGE(PG8_SB(1, 0), b3, voffB); PG8_STAGE(PG8_SB(1, 1), b3 + hstepB, voffB); PG8_STAGE(PG8_SA(1, 0), a3, voffA);
;             PG8_WAIT_V(8); PG8_WAIT_L(0); PG8_BAR; PG8_MMA(1, 0, At, B0); PG8_MMA(1, 1, At, B1); PG8_BAR; PG8_SCHED;
	s_nop 0
	s_waitcnt lgkmcnt(0)
	v_mfma_f32_16x16x32_bf16 v[66:69], v[90:93], v[180:183], v[66:69]
	v_mfma_f32_16x16x32_bf16 v[62:65], v[102:105], v[180:183], v[62:65]
	v_mfma_f32_16x16x32_bf16 v[50:53], v[90:93], v[188:191], v[50:53]
	v_mfma_f32_16x16x32_bf16 v[46:49], v[102:105], v[188:191], v[46:49]
	v_mfma_f32_16x16x32_bf16 v[34:37], v[90:93], v[196:199], v[34:37]
	v_mfma_f32_16x16x32_bf16 v[30:33], v[102:105], v[196:199], v[30:33]
	v_mfma_f32_16x16x32_bf16 v[18:21], v[90:93], v[204:207], v[18:21]
	v_mfma_f32_16x16x32_bf16 v[10:13], v[102:105], v[204:207], v[10:13]
	v_mfma_f32_16x16x32_bf16 v[66:69], v[98:101], v[184:187], v[66:69]
	v_mfma_f32_16x16x32_bf16 v[62:65], v[106:109], v[184:187], v[62:65]
	v_mfma_f32_16x16x32_bf16 v[50:53], v[98:101], v[192:195], v[50:53]
	v_mfma_f32_16x16x32_bf16 v[46:49], v[106:109], v[192:195], v[46:49]
	v_mfma_f32_16x16x32_bf16 v[34:37], v[98:101], v[200:203], v[34:37]
	v_mfma_f32_16x16x32_bf16 v[30:33], v[106:109], v[200:203], v[30:33]
	v_mfma_f32_16x16x32_bf16 v[18:21], v[98:101], v[208:211], v[18:21]
	v_mfma_f32_16x16x32_bf16 v[10:13], v[106:109], v[208:211], v[10:13]
	s_nop 0
	s_nop 0
	v_mfma_f32_16x16x32_bf16 v[58:61], v[160:163], v[180:183], v[58:61]
	v_mfma_f32_16x16x32_bf16 v[54:57], v[172:175], v[180:183], v[54:57]
	v_mfma_f32_16x16x32_bf16 v[42:45], v[160:163], v[188:191], v[42:45]
	v_mfma_f32_16x16x32_bf16 v[38:41], v[172:175], v[188:191], v[38:41]
	v_mfma_f32_16x16x32_bf16 v[26:29], v[160:163], v[196:199], v[26:29]
	v_mfma_f32_16x16x32_bf16 v[22:25], v[172:175], v[196:199], v[22:25]
	v_mfma_f32_16x16x32_bf16 v[6:9], v[160:163], v[204:207], v[6:9]
	v_mfma_f32_16x16x32_bf16 v[2:5], v[172:175], v[204:207], v[2:5]
	v_mfma_f32_16x16x32_bf16 v[58:61], v[168:171], v[184:187], v[58:61]
	v_mfma_f32_16x16x32_bf16 v[54:57], v[176:179], v[184:187], v[54:57]
	v_mfma_f32_16x16x32_bf16 v[42:45], v[168:171], v[192:195], v[42:45]
	v_mfma_f32_16x16x32_bf16 v[38:41], v[176:179], v[192:195], v[38:41]
	v_mfma_f32_16x16x32_bf16 v[26:29], v[168:171], v[200:203], v[26:29]
	v_mfma_f32_16x16x32_bf16 v[22:25], v[176:179], v[200:203], v[22:25]
	v_mfma_f32_16x16x32_bf16 v[6:9], v[168:171], v[208:211], v[6:9]
	v_mfma_f32_16x16x32_bf16 v[2:5], v[176:179], v[208:211], v[2:5]
	s_nop 0
	s_barrier
	s_add_i32 s57, 0, 0x18000
	v_add_u32_e32 v0, s57, v17
	s_add_i32 s66, 0, 0x1c000
	ds_read_b128 v[90:93], v0
	ds_read_b128 v[98:101], v0 offset:1024
	ds_read_b128 v[102:105], v0 offset:2048
	ds_read_b128 v[106:109], v0 offset:3072
	v_add_u32_e32 v0, s66, v17
	ds_read_b128 v[160:163], v0
	ds_read_b128 v[168:171], v0 offset:1024
	ds_read_b128 v[172:175], v0 offset:2048
	ds_read_b128 v[176:179], v0 offset:3072
	s_add_u32 s30, s30, 0x40000
	s_addc_u32 s31, s31, 0
	s_mov_b32 m0, s45
	v_lshl_add_u64 v[218:219], s[30:31], 0, v[14:15]
	ds_read_b128 v[180:183], v166 offset:32768
	ds_read_b128 v[184:187], v166 offset:33792
	ds_read_b128 v[188:191], v166 offset:34816
	ds_read_b128 v[192:195], v166 offset:35840
	ds_read_b128 v[196:199], v166 offset:36864
	ds_read_b128 v[200:203], v166 offset:37888
	ds_read_b128 v[204:207], v166 offset:38912
	ds_read_b128 v[208:211], v166 offset:39936
	global_load_lds_dwordx4 v[218:219], off
	v_lshl_add_u64 v[218:219], s[30:31], 0, v[152:153]
	s_mov_b32 m0, s46
	s_nop 0
	global_load_lds_dwordx4 v[218:219], off
	s_waitcnt vmcnt(8)
	s_waitcnt lgkmcnt(0)
	s_barrier
	s_nop 0
	s_waitcnt lgkmcnt(0)
	v_mfma_f32_16x16x32_bf16 v[146:149], v[90:93], v[180:183], v[146:149]
	v_mfma_f32_16x16x32_bf16 v[142:145], v[102:105], v[180:183], v[142:145]
	v_mfma_f32_16x16x32_bf16 v[130:133], v[90:93], v[188:191], v[130:133]
	v_mfma_f32_16x16x32_bf16 v[126:129], v[102:105], v[188:191], v[126:129]
	v_mfma_f32_16x16x32_bf16 v[114:117], v[90:93], v[196:199], v[114:117]
	v_mfma_f32_16x16x32_bf16 v[110:113], v[102:105], v[196:199], v[110:113]
	v_mfma_f32_16x16x32_bf16 v[82:85], v[90:93], v[204:207], v[82:85]
	v_mfma_f32_16x16x32_bf16 v[78:81], v[102:105], v[204:207], v[78:81]
	v_mfma_f32_16x16x32_bf16 v[146:149], v[98:101], v[184:187], v[146:149]
	v_mfma_f32_16x16x32_bf16 v[142:145], v[106:109], v[184:187], v[142:145]
	v_mfma_f32_16x16x32_bf16 v[130:133], v[98:101], v[192:195], v[130:133]
	v_mfma_f32_16x16x32_bf16 v[126:129], v[106:109], v[192:195], v[126:129]
	v_mfma_f32_16x16x32_bf16 v[114:117], v[98:101], v[200:203], v[114:117]
	v_mfma_f32_16x16x32_bf16 v[110:113], v[106:109], v[200:203], v[110:113]
	v_mfma_f32_16x16x32_bf16 v[82:85], v[98:101], v[208:211], v[82:85]
	v_mfma_f32_16x16x32_bf16 v[78:81], v[106:109], v[208:211], v[78:81]
	s_nop 0
	s_nop 0
	v_mfma_f32_16x16x32_bf16 v[138:141], v[160:163], v[180:183], v[138:141]
	v_mfma_f32_16x16x32_bf16 v[134:137], v[172:175], v[180:183], v[134:137]
	v_mfma_f32_16x16x32_bf16 v[122:125], v[160:163], v[188:191], v[122:125]
	v_mfma_f32_16x16x32_bf16 v[118:121], v[172:175], v[188:191], v[118:121]
	v_mfma_f32_16x16x32_bf16 v[94:97], v[160:163], v[196:199], v[94:97]
	v_mfma_f32_16x16x32_bf16 v[86:89], v[172:175], v[196:199], v[86:89]
	v_mfma_f32_16x16x32_bf16 v[74:77], v[160:163], v[204:207], v[74:77]
	v_mfma_f32_16x16x32_bf16 v[70:73], v[172:175], v[204:207], v[70:73]
	v_mfma_f32_16x16x32_bf16 v[138:141], v[168:171], v[184:187], v[138:141]
	v_mfma_f32_16x16x32_bf16 v[134:137], v[176:179], v[184:187], v[134:137]
	v_mfma_f32_16x16x32_bf16 v[122:125], v[168:171], v[192:195], v[122:125]
	v_mfma_f32_16x16x32_bf16 v[118:121], v[176:179], v[192:195], v[118:121]
	v_mfma_f32_16x16x32_bf16 v[94:97], v[168:171], v[200:203], v[94:97]
	v_mfma_f32_16x16x32_bf16 v[86:89], v[176:179], v[200:203], v[86:89]
	v_mfma_f32_16x16x32_bf16 v[74:77], v[168:171], v[208:211], v[74:77]
	v_mfma_f32_16x16x32_bf16 v[70:73], v[176:179], v[208:211], v[70:73]
	s_nop 0
	s_barrier
; __device__ __forceinline__ int opaque_tid(int wave_s) { int l; asm volatile("v_mbcnt_lo_u32_b32 %0, -1, 0\n\tv_mbcnt_hi_u32_b32 %0, -1, %0" : "=v"(l)); return (wave_s << 6) | l; }
; #define PG8_STAGE(bufoff, gbase, voff) do { _Pragma("unroll") for (int _i = 0; _i < 2; ++_i) \
;         __builtin_amdgcn_global_load_lds((const unsigned*)((const char*)(gbase) + (voff)[_i]), (PG8_LAS unsigned*)(lds + (bufoff) + ldsw + _i * 8192), 16, 0, 0); } while (0)
; #define PG8_WAIT_V(n) asm volatile("s_waitcnt vmcnt(" #n ")" ::: "memory")
; template <class Epi, class Sched, bool ALIGN_EPI = false, bool SP2 = false>
; __device__ __forceinline__ void gemm_phase(PG8_LAS unsigned char* lds, const Gemm g, const Sched& S, const Epi& E, const int wave_s) {
;     ...
;         for (int t = 0; t < nt; t += 2) {
;             if constexpr (Epi::KHOOK) { if (t == 6 || t == 12) { const int l3_ = opaque_tid(wave_s) & 63; E.khook(acc, t, wr, l3_ & 15, ui & 1, lds); } }
;             const bool last = (t == nt - 2);
;             const char* a1 = cA + (size_t)(t + 1) * kstep;
;             const char* a2 = last ? nA : cA + (size_t)(t + 2) * kstep; const char* b2 = last ? nB : cB + (size_t)(t + 2) * kstep;
;             const char* a3 = a2 + kstep; const char* b3 = b2 + kstep;
;             if (last && has_next) S.a_ready(nxt);
;             if constexpr (SP2) {
;             PG8_LDB(B0, 0, 0); PG8_LDB(B1, 0, 1); PG8_SCHED; PG8_LDA(At, 0, 0); PG8_STAGE(PG8_SA(1, 1), a1 + hstepA, voffA);
;             PG8_WAIT_V(8); PG8_WAIT_L(0); PG8_BAR; PG8_MMA(0, 0, At, B0); PG8_MMA(0, 1, At, B1); PG8_BAR; PG8_SCHED;
;             PG8_LDA(At, 0, 1); PG8_STAGE(PG8_SB(0, 0), b2, voffB); PG8_STAGE(PG8_SB(0, 1), b2 + hstepB, voffB); PG8_STAGE(PG8_SA(0, 0), a2, voffA);
;             PG8_WAIT_V(8); PG8_WAIT_L(0); PG8_BAR; PG8_MMA(1, 0, At, B0); PG8_MMA(1, 1, At, B1); PG8_BAR; PG8_SCHED;
;             PG8_LDB(B0, 1, 0); PG8_LDB(B1, 1, 1); PG8_SCHED; PG8_LDA(At, 1, 0); PG8_STAGE(PG8_SA(0, 1), a2 + hstepA, voffA);
;             PG8_WAIT_V(8); PG8_WAIT_L(0); PG8_BAR; PG8_MMA(0, 0, At, B0); PG8_MMA(0, 1, At, B1); PG8_BAR; PG8_SCHED;
;             PG8_LDA(At, 1, 1); PG8_STAGE(PG8_SB(1, 0), b3, voffB); PG8_STAGE(PG8_SB(1, 1), b3 + hstepB, voffB); PG8_STAGE(PG8_SA(1, 0), a3, voffA);
;             PG8_WAIT_V(8); PG8_WAIT_L(0); PG8_BAR; PG8_MMA(1, 0, At, B0); PG8_MMA(1, 1, At, B1); PG8_BAR; PG8_SCHED;
	s_add_i32 s30, s57, s44
	v_lshl_add_u64 v[164:165], v[164:165], 0, s[58:59]
	s_mov_b32 m0, s30
	ds_read_b128 v[180:183], v166 offset:49152
	ds_read_b128 v[184:187], v166 offset:50176
	ds_read_b128 v[188:191], v166 offset:51200
	ds_read_b128 v[192:195], v166 offset:52224
	ds_read_b128 v[196:199], v166 offset:53248
	ds_read_b128 v[200:203], v166 offset:54272
	ds_read_b128 v[204:207], v166 offset:55296
	ds_read_b128 v[208:211], v166 offset:56320
	global_load_lds_dwordx4 v[164:165], off
	s_add_i32 m0, s30, 0x2000
	s_add_u32 s4, s4, 0x40080
	v_lshl_add_u64 v[164:165], v[212:213], 0, s[58:59]
	s_addc_u32 s5, s5, 0
	s_add_i32 s30, s66, s44
	global_load_lds_dwordx4 v[164:165], off
	v_lshl_add_u64 v[164:165], s[4:5], 0, v[150:151]
	s_mov_b32 m0, s30
	s_nop 0
	global_load_lds_dwordx4 v[164:165], off
	v_lshl_add_u64 v[164:165], s[4:5], 0, v[154:155]
	s_add_i32 m0, s30, 0x2000
	s_nop 0
	global_load_lds_dwordx4 v[164:165], off
	v_lshl_add_u64 v[164:165], v[214:215], 0, v[248:249]
	s_mov_b32 m0, s49
	s_nop 0
	global_load_lds_dwordx4 v[164:165], off
	v_lshl_add_u64 v[164:165], v[216:217], 0, v[248:249]
	s_mov_b32 m0, s50
	s_nop 0
	global_load_lds_dwordx4 v[164:165], off
	s_waitcnt vmcnt(8)
	s_waitcnt lgkmcnt(0)
	s_barrier
	s_nop 0
	s_waitcnt lgkmcnt(0)
	v_mfma_f32_16x16x32_bf16 v[66:69], v[90:93], v[180:183], v[66:69]
	v_mfma_f32_16x16x32_bf16 v[62:65], v[102:105], v[180:183], v[62:65]
	v_mfma_f32_16x16x32_bf16 v[50:53], v[90:93], v[188:191], v[50:53]
	v_mfma_f32_16x16x32_bf16 v[46:49], v[102:105], v[188:191], v[46:49]
	v_mfma_f32_16x16x32_bf16 v[34:37], v[90:93], v[196:199], v[34:37]
	v_mfma_f32_16x16x32_bf16 v[30:33], v[102:105], v[196:199], v[30:33]
	v_mfma_f32_16x16x32_bf16 v[18:21], v[90:93], v[204:207], v[18:21]
	v_mfma_f32_16x16x32_bf16 v[10:13], v[102:105], v[204:207], v[10:13]
	v_mfma_f32_16x16x32_bf16 v[66:69], v[98:101], v[184:187], v[66:69]
	v_mfma_f32_16x16x32_bf16 v[62:65], v[106:109], v[184:187], v[62:65]
	v_mfma_f32_16x16x32_bf16 v[50:53], v[98:101], v[192:195], v[50:53]
	v_mfma_f32_16x16x32_bf16 v[46:49], v[106:109], v[192:195], v[46:49]
	v_mfma_f32_16x16x32_bf16 v[34:37], v[98:101], v[200:203], v[34:37]
	v_mfma_f32_16x16x32_bf16 v[30:33], v[106:109], v[200:203], v[30:33]
	v_mfma_f32_16x16x32_bf16 v[18:21], v[98:101], v[208:211], v[18:21]
	v_mfma_f32_16x16x32_bf16 v[10:13], v[106:109], v[208:211], v[10:13]
	s_nop 0
	s_nop 0
	v_mfma_f32_16x16x32_bf16 v[58:61], v[160:163], v[180:183], v[58:61]
	v_mfma_f32_16x16x32_bf16 v[54:57], v[172:175], v[180:183], v[54:57]
	v_mfma_f32_16x16x32_bf16 v[42:45], v[160:163], v[188:191], v[42:45]
	v_mfma_f32_16x16x32_bf16 v[38:41], v[172:175], v[188:191], v[38:41]
	v_mfma_f32_16x16x32_bf16 v[26:29], v[160:163], v[196:199], v[26:29]
	v_mfma_f32_16x16x32_bf16 v[22:25], v[172:175], v[196:199], v[22:25]
	v_mfma_f32_16x16x32_bf16 v[6:9], v[160:163], v[204:207], v[6:9]
	v_mfma_f32_16x16x32_bf16 v[2:5], v[172:175], v[204:207], v[2:5]
	v_mfma_f32_16x16x32_bf16 v[58:61], v[168:171], v[184:187], v[58:61]
	v_mfma_f32_16x16x32_bf16 v[54:57], v[176:179], v[184:187], v[54:57]
	v_mfma_f32_16x16x32_bf16 v[42:45], v[168:171], v[192:195], v[42:45]
	v_mfma_f32_16x16x32_bf16 v[38:41], v[176:179], v[192:195], v[38:41]
	v_mfma_f32_16x16x32_bf16 v[26:29], v[168:171], v[200:203], v[26:29]
	v_mfma_f32_16x16x32_bf16 v[22:25], v[176:179], v[200:203], v[22:25]
	v_mfma_f32_16x16x32_bf16 v[6:9], v[168:171], v[208:211], v[6:9]
	v_mfma_f32_16x16x32_bf16 v[2:5], v[176:179], v[208:211], v[2:5]
	s_nop 0
	s_barrier
	s_add_i32 s56, s56, 2
	s_add_u32 s54, s54, 0x100
	s_addc_u32 s55, s55, 0
	s_add_u32 s6, s6, 0x1000
	s_addc_u32 s7, s7, 0
	s_cmp_gt_u32 s56, 13
	s_cbranch_scc0 .LBB0_1165
	s_and_b64 vcc, exec, s[16:17]
	s_cbranch_vccz .LBB0_1168
	s_barrier

; __device__ __forceinline__ int opaque_tid(int wave_s) { int l; asm volatile("v_mbcnt_lo_u32_b32 %0, -1, 0\n\tv_mbcnt_hi_u32_b32 %0, -1, %0" : "=v"(l)); return (wave_s << 6) | l; }
; #define PG8_STAGE(bufoff, gbase, voff) do { _Pragma("unroll") for (int _i = 0; _i < 2; ++_i) \
;         __builtin_amdgcn_global_load_lds((const unsigned*)((const char*)(gbase) + (voff)[_i]), (PG8_LAS unsigned*)(lds + (bufoff) + ldsw + _i * 8192), 16, 0, 0); } while (0)
; #define PG8_WAIT_V(n) asm volatile("s_waitcnt vmcnt(" #n ")" ::: "memory")
; template <class Epi, class Sched, bool ALIGN_EPI = false, bool SP2 = false>
; __device__ __forceinline__ void gemm_phase(PG8_LAS unsigned char* lds, const Gemm g, const Sched& S, const Epi& E, const int wave_s) {
;     ...
;         for (int t = 0; t < nt; t += 2) {
;             if constexpr (Epi::KHOOK) { if (t == 6 || t == 12) { const int l3_ = opaque_tid(wave_s) & 63; E.khook(acc, t, wr, l3_ & 15, ui & 1, lds); } }
;             const bool last = (t == nt - 2);
;             const char* a1 = cA + (size_t)(t + 1) * kstep;
;             const char* a2 = last ? nA : cA + (size_t)(t + 2) * kstep; const char* b2 = last ? nB : cB + (size_t)(t + 2) * kstep;
;             const char* a3 = a2 + kstep; const char* b3 = b2 + kstep;
;             if (last && has_next) S.a_ready(nxt);
;             if constexpr (SP2) {
;             PG8_LDB(B0, 0, 0); PG8_LDB(B1, 0, 1); PG8_SCHED; PG8_LDA(At, 0, 0); PG8_STAGE(PG8_SA(1, 1), a1 + hstepA, voffA);
;             PG8_WAIT_V(8); PG8_WAIT_L(0); PG8_BAR; PG8_MMA(0, 0, At, B0); PG8_MMA(0, 1, At, B1); PG8_BAR; PG8_SCHED;
;             PG8_LDA(At, 0, 1); PG8_STAGE(PG8_SB(0, 0), b2, voffB); PG8_STAGE(PG8_SB(0, 1), b2 + hstepB, voffB); PG8_STAGE(PG8_SA(0, 0), a2, voffA);
;             PG8_WAIT_V(8); PG8_WAIT_L(0); PG8_BAR; PG8_MMA(1, 0, At, B0); PG8_MMA(1, 1, At, B1); PG8_BAR; PG8_SCHED;
;             PG8_LDB(B0, 1, 0); PG8_LDB(B1, 1, 1); PG8_SCHED; PG8_LDA(At, 1, 0); PG8_STAGE(PG8_SA(0, 1), a2 + hstepA, voffA);
;             PG8_WAIT_V(8); PG8_WAIT_L(0); PG8_BAR; PG8_MMA(0, 0, At, B0); PG8_MMA(0, 1, At, B1); PG8_BAR; PG8_SCHED;
;             PG8_LDA(At, 1, 1); PG8_STAGE(PG8_SB(1, 0), b3, voffB); PG8_STAGE(PG8_SB(1, 1), b3 + hstepB, voffB); PG8_STAGE(PG8_SA(1, 0), a3, voffA);
;             PG8_WAIT_V(8); PG8_WAIT_L(0); PG8_BAR; PG8_MMA(1, 0, At, B0); PG8_MMA(1, 1, At, B1); PG8_BAR; PG8_SCHED;
.LBB0_1243:
	s_add_u32 s8, s10, 0x1000
	s_addc_u32 s9, s11, 0
	s_add_i32 s55, 0, 0x10000
	s_cmp_eq_u32 s54, 40
	s_cselect_b32 s35, s29, s9
	s_cselect_b32 s34, s28, s8
	v_add_u32_e32 v0, s55, v17
	s_cselect_b32 s5, s31, s3
	s_cselect_b32 s4, s30, s2
	s_add_i32 s56, 0, 0x14000
	ds_read_b128 v[62:65], v0
	ds_read_b128 v[66:69], v0 offset:1024
	ds_read_b128 v[70:73], v0 offset:2048
	ds_read_b128 v[74:77], v0 offset:3072
	v_add_u32_e32 v0, s56, v17
	ds_read_b128 v[150:153], v0
	ds_read_b128 v[154:157], v0 offset:1024
	ds_read_b128 v[158:161], v0 offset:2048
	ds_read_b128 v[162:165], v0 offset:3072
	v_lshl_add_u64 v[208:209], s[10:11], 0, v[202:203]
	s_add_i32 m0, s44, 0xc000
	ds_read_b128 v[166:169], v216
	ds_read_b128 v[170:173], v216 offset:1024
	ds_read_b128 v[174:177], v216 offset:2048
	ds_read_b128 v[178:181], v216 offset:3072
	ds_read_b128 v[182:185], v216 offset:4096
	ds_read_b128 v[186:189], v216 offset:5120
	ds_read_b128 v[190:193], v216 offset:6144
	ds_read_b128 v[204:207], v216 offset:7168
	global_load_lds_dwordx4 v[208:209], off
	v_lshl_add_u64 v[208:209], s[10:11], 0, v[200:201]
	s_add_i32 m0, s44, 0xe000
	s_nop 0
	global_load_lds_dwordx4 v[208:209], off
	s_waitcnt vmcnt(8)
	s_waitcnt lgkmcnt(0)
	s_barrier
	s_nop 0
	s_waitcnt lgkmcnt(0)
	v_mfma_f32_16x16x32_bf16 v[146:149], v[62:65], v[166:169], v[146:149]
	v_mfma_f32_16x16x32_bf16 v[142:145], v[70:73], v[166:169], v[142:145]
	v_mfma_f32_16x16x32_bf16 v[130:133], v[62:65], v[174:177], v[130:133]
	v_mfma_f32_16x16x32_bf16 v[126:129], v[70:73], v[174:177], v[126:129]
	v_mfma_f32_16x16x32_bf16 v[114:117], v[62:65], v[182:185], v[114:117]
	v_mfma_f32_16x16x32_bf16 v[110:113], v[70:73], v[182:185], v[110:113]
	v_mfma_f32_16x16x32_bf16 v[98:101], v[62:65], v[190:193], v[98:101]
	v_mfma_f32_16x16x32_bf16 v[94:97], v[70:73], v[190:193], v[94:97]
	v_mfma_f32_16x16x32_bf16 v[146:149], v[66:69], v[170:173], v[146:149]
	v_mfma_f32_16x16x32_bf16 v[142:145], v[74:77], v[170:173], v[142:145]
	v_mfma_f32_16x16x32_bf16 v[130:133], v[66:69], v[178:181], v[130:133]
	v_mfma_f32_16x16x32_bf16 v[126:129], v[74:77], v[178:181], v[126:129]
	v_mfma_f32_16x16x32_bf16 v[114:117], v[66:69], v[186:189], v[114:117]
	v_mfma_f32_16x16x32_bf16 v[110:113], v[74:77], v[186:189], v[110:113]
	v_mfma_f32_16x16x32_bf16 v[98:101], v[66:69], v[204:207], v[98:101]
	v_mfma_f32_16x16x32_bf16 v[94:97], v[74:77], v[204:207], v[94:97]
	s_nop 0
	s_nop 0
	v_mfma_f32_16x16x32_bf16 v[138:141], v[150:153], v[166:169], v[138:141]
	v_mfma_f32_16x16x32_bf16 v[134:137], v[158:161], v[166:169], v[134:137]
	v_mfma_f32_16x16x32_bf16 v[122:125], v[150:153], v[174:177], v[122:125]
	v_mfma_f32_16x16x32_bf16 v[118:121], v[158:161], v[174:177], v[118:121]
	v_mfma_f32_16x16x32_bf16 v[106:109], v[150:153], v[182:185], v[106:109]
	v_mfma_f32_16x16x32_bf16 v[102:105], v[158:161], v[182:185], v[102:105]
	v_mfma_f32_16x16x32_bf16 v[90:93], v[150:153], v[190:193], v[90:93]
	v_mfma_f32_16x16x32_bf16 v[86:89], v[158:161], v[190:193], v[86:89]
	v_mfma_f32_16x16x32_bf16 v[138:141], v[154:157], v[170:173], v[138:141]
	v_mfma_f32_16x16x32_bf16 v[134:137], v[162:165], v[170:173], v[134:137]
	v_mfma_f32_16x16x32_bf16 v[122:125], v[154:157], v[178:181], v[122:125]
	v_mfma_f32_16x16x32_bf16 v[118:121], v[162:165], v[178:181], v[118:121]
	v_mfma_f32_16x16x32_bf16 v[106:109], v[154:157], v[186:189], v[106:109]
	v_mfma_f32_16x16x32_bf16 v[102:105], v[162:165], v[186:189], v[102:105]
	v_mfma_f32_16x16x32_bf16 v[90:93], v[154:157], v[204:207], v[90:93]
	v_mfma_f32_16x16x32_bf16 v[86:89], v[162:165], v[204:207], v[86:89]
	s_nop 0
	s_barrier
	s_add_i32 s10, s55, s37
	v_lshl_add_u64 v[208:209], s[4:5], 0, v[194:195]
	s_mov_b32 m0, s10
	ds_read_b128 v[166:169], v216 offset:16384
	ds_read_b128 v[170:173], v216 offset:17408
	ds_read_b128 v[174:177], v216 offset:18432
	ds_read_b128 v[178:181], v216 offset:19456
	ds_read_b128 v[182:185], v216 offset:20480
	ds_read_b128 v[186:189], v216 offset:21504
	ds_read_b128 v[190:193], v216 offset:22528
	ds_read_b128 v[204:207], v216 offset:23552
	global_load_lds_dwordx4 v[208:209], off
	s_add_i32 m0, s10, 0x2000
	s_add_u32 s10, s4, 0xb0000
	v_lshl_add_u64 v[210:211], s[4:5], 0, v[198:199]
	s_addc_u32 s11, s5, 0
	s_add_i32 s55, s56, s37
	global_load_lds_dwordx4 v[210:211], off
	v_lshl_add_u64 v[212:213], s[10:11], 0, v[194:195]
	s_mov_b32 m0, s55
	v_lshl_add_u64 v[214:215], s[34:35], 0, v[196:197]
	global_load_lds_dwordx4 v[212:213], off
	v_lshl_add_u64 v[212:213], s[10:11], 0, v[198:199]
	s_add_i32 m0, s55, 0x2000
	s_nop 0
	global_load_lds_dwordx4 v[212:213], off
	v_lshl_add_u64 v[212:213], s[34:35], 0, v[14:15]
	s_mov_b32 m0, s44
	s_nop 0
	global_load_lds_dwordx4 v[212:213], off
	s_mov_b32 m0, s45
	s_nop 0
	global_load_lds_dwordx4 v[214:215], off
	s_waitcnt vmcnt(8)
	s_waitcnt lgkmcnt(0)
	s_barrier
; #define PG8_STAGE(bufoff, gbase, voff) do { _Pragma("unroll") for (int _i = 0; _i < 2; ++_i) \
;         __builtin_amdgcn_global_load_lds((const unsigned*)((const char*)(gbase) + (voff)[_i]), (PG8_LAS unsigned*)(lds + (bufoff) + ldsw + _i * 8192), 16, 0, 0); } while (0)
; #define PG8_LDA(dst, b, h) do { _Pragma("unroll") for (int m = 0; m < 4; ++m) _Pragma("unroll") for (int k = 0; k < 2; ++k) dst[m][k] = *(const PG8_LAS bf16x8*)(lds + PG8_SA(b, h) + aoff + m * 2048 + k * 1024); } while (0)
; #define PG8_LDB(dst, b, h) do { _Pragma("unroll") for (int n = 0; n < 2; ++n) _Pragma("unroll") for (int k = 0; k < 2; ++k) dst[n][k] = *(const PG8_LAS bf16x8*)(lds + PG8_SB(b, h) + boff + n * 2048 + k * 1024); } while (0)
; #define PG8_MMA(ai, bj, At, Bt) do { __builtin_amdgcn_s_setprio(1); _Pragma("unroll") for (int m = 0; m < 4; ++m) _Pragma("unroll") for (int n = 0; n < 2; ++n) _Pragma("unroll") for (int k = 0; k < 2; ++k) \
;         acc[ai][bj][m][n] = __builtin_amdgcn_mfma_f32_16x16x32_bf16(Bt[n][k], At[m][k], acc[ai][bj][m][n], 0, 0, 0); __builtin_amdgcn_s_setprio(0); } while (0)
; #define PG8_BAR __builtin_amdgcn_s_barrier()
; template <class Epi, class Sched, bool ALIGN_EPI = false, bool SP2 = false>
; __device__ __forceinline__ void gemm_phase(PG8_LAS unsigned char* lds, const Gemm g, const Sched& S, const Epi& E, const int wave_s) {
;     ...
;             PG8_LDB(B0, 0, 0); PG8_LDB(B1, 0, 1); PG8_SCHED; PG8_LDA(At, 0, 0); PG8_STAGE(PG8_SA(1, 1), a1 + hstepA, voffA);
;             PG8_WAIT_V(8); PG8_WAIT_L(0); PG8_BAR; PG8_MMA(0, 0, At, B0); PG8_MMA(0, 1, At, B1); PG8_BAR; PG8_SCHED;
;             PG8_LDA(At, 0, 1); PG8_STAGE(PG8_SB(0, 0), b2, voffB); PG8_STAGE(PG8_SB(0, 1), b2 + hstepB, voffB); PG8_STAGE(PG8_SA(0, 0), a2, voffA);
;             PG8_WAIT_V(8); PG8_WAIT_L(0); PG8_BAR; PG8_MMA(1, 0, At, B0); PG8_MMA(1, 1, At, B1); PG8_BAR; PG8_SCHED;
;             PG8_LDB(B0, 1, 0); PG8_LDB(B1, 1, 1); PG8_SCHED; PG8_LDA(At, 1, 0); PG8_STAGE(PG8_SA(0, 1), a2 + hstepA, voffA);
;             PG8_WAIT_V(8); PG8_WAIT_L(0); PG8_BAR; PG8_MMA(0, 0, At, B0); PG8_MMA(0, 1, At, B1); PG8_BAR; PG8_SCHED;
;             PG8_LDA(At, 1, 1); PG8_STAGE(PG8_SB(1, 0), b3, voffB); PG8_STAGE(PG8_SB(1, 1), b3 + hstepB, voffB); PG8_STAGE(PG8_SA(1, 0), a3, voffA);
;             PG8_WAIT_V(8); PG8_WAIT_L(0); PG8_BAR; PG8_MMA(1, 0, At, B0); PG8_MMA(1, 1, At, B1); PG8_BAR; PG8_SCHED;
	s_nop 0
	s_waitcnt lgkmcnt(0)
	v_mfma_f32_16x16x32_bf16 v[82:85], v[62:65], v[166:169], v[82:85]
	v_mfma_f32_16x16x32_bf16 v[78:81], v[70:73], v[166:169], v[78:81]
	v_mfma_f32_16x16x32_bf16 v[50:53], v[62:65], v[174:177], v[50:53]
	v_mfma_f32_16x16x32_bf16 v[46:49], v[70:73], v[174:177], v[46:49]
	v_mfma_f32_16x16x32_bf16 v[34:37], v[62:65], v[182:185], v[34:37]
	v_mfma_f32_16x16x32_bf16 v[30:33], v[70:73], v[182:185], v[30:33]
	v_mfma_f32_16x16x32_bf16 v[18:21], v[62:65], v[190:193], v[18:21]
	v_mfma_f32_16x16x32_bf16 v[10:13], v[70:73], v[190:193], v[10:13]
	v_mfma_f32_16x16x32_bf16 v[82:85], v[66:69], v[170:173], v[82:85]
	v_mfma_f32_16x16x32_bf16 v[78:81], v[74:77], v[170:173], v[78:81]
	v_mfma_f32_16x16x32_bf16 v[50:53], v[66:69], v[178:181], v[50:53]
	v_mfma_f32_16x16x32_bf16 v[46:49], v[74:77], v[178:181], v[46:49]
	v_mfma_f32_16x16x32_bf16 v[34:37], v[66:69], v[186:189], v[34:37]
	v_mfma_f32_16x16x32_bf16 v[30:33], v[74:77], v[186:189], v[30:33]
	v_mfma_f32_16x16x32_bf16 v[18:21], v[66:69], v[204:207], v[18:21]
	v_mfma_f32_16x16x32_bf16 v[10:13], v[74:77], v[204:207], v[10:13]
	s_nop 0
	s_nop 0
	v_mfma_f32_16x16x32_bf16 v[58:61], v[150:153], v[166:169], v[58:61]
	v_mfma_f32_16x16x32_bf16 v[54:57], v[158:161], v[166:169], v[54:57]
	v_mfma_f32_16x16x32_bf16 v[42:45], v[150:153], v[174:177], v[42:45]
	v_mfma_f32_16x16x32_bf16 v[38:41], v[158:161], v[174:177], v[38:41]
	v_mfma_f32_16x16x32_bf16 v[26:29], v[150:153], v[182:185], v[26:29]
	v_mfma_f32_16x16x32_bf16 v[22:25], v[158:161], v[182:185], v[22:25]
	v_mfma_f32_16x16x32_bf16 v[6:9], v[150:153], v[190:193], v[6:9]
	v_mfma_f32_16x16x32_bf16 v[2:5], v[158:161], v[190:193], v[2:5]
	v_mfma_f32_16x16x32_bf16 v[58:61], v[154:157], v[170:173], v[58:61]
	v_mfma_f32_16x16x32_bf16 v[54:57], v[162:165], v[170:173], v[54:57]
	v_mfma_f32_16x16x32_bf16 v[42:45], v[154:157], v[178:181], v[42:45]
	v_mfma_f32_16x16x32_bf16 v[38:41], v[162:165], v[178:181], v[38:41]
	v_mfma_f32_16x16x32_bf16 v[26:29], v[154:157], v[186:189], v[26:29]
	v_mfma_f32_16x16x32_bf16 v[22:25], v[162:165], v[186:189], v[22:25]
	v_mfma_f32_16x16x32_bf16 v[6:9], v[154:157], v[204:207], v[6:9]
	v_mfma_f32_16x16x32_bf16 v[2:5], v[162:165], v[204:207], v[2:5]
	s_nop 0
	s_barrier
	s_add_i32 s55, 0, 0x18000
	v_add_u32_e32 v0, s55, v17
	s_add_i32 s56, 0, 0x1c000
	ds_read_b128 v[62:65], v0
	ds_read_b128 v[66:69], v0 offset:1024
	ds_read_b128 v[70:73], v0 offset:2048
	ds_read_b128 v[74:77], v0 offset:3072
	v_add_u32_e32 v0, s56, v17
	ds_read_b128 v[150:153], v0
	ds_read_b128 v[154:157], v0 offset:1024
	ds_read_b128 v[158:161], v0 offset:2048
	ds_read_b128 v[162:165], v0 offset:3072
	s_add_u32 s10, s34, 0xb0000
	s_addc_u32 s11, s35, 0
	s_mov_b32 m0, s46
	v_lshl_add_u64 v[218:219], s[10:11], 0, v[14:15]
	ds_read_b128 v[166:169], v216 offset:32768
	ds_read_b128 v[170:173], v216 offset:33792
	ds_read_b128 v[174:177], v216 offset:34816
	ds_read_b128 v[178:181], v216 offset:35840
	ds_read_b128 v[182:185], v216 offset:36864
	ds_read_b128 v[186:189], v216 offset:37888
	ds_read_b128 v[190:193], v216 offset:38912
	ds_read_b128 v[204:207], v216 offset:39936
	global_load_lds_dwordx4 v[218:219], off
	v_lshl_add_u64 v[218:219], s[10:11], 0, v[196:197]
	s_mov_b32 m0, s47
	s_nop 0
	global_load_lds_dwordx4 v[218:219], off
	s_waitcnt vmcnt(8)
	s_waitcnt lgkmcnt(0)
	s_barrier
	s_nop 0
	s_waitcnt lgkmcnt(0)
	v_mfma_f32_16x16x32_bf16 v[146:149], v[62:65], v[166:169], v[146:149]
	v_mfma_f32_16x16x32_bf16 v[142:145], v[70:73], v[166:169], v[142:145]
	v_mfma_f32_16x16x32_bf16 v[130:133], v[62:65], v[174:177], v[130:133]
	v_mfma_f32_16x16x32_bf16 v[126:129], v[70:73], v[174:177], v[126:129]
	v_mfma_f32_16x16x32_bf16 v[114:117], v[62:65], v[182:185], v[114:117]
	v_mfma_f32_16x16x32_bf16 v[110:113], v[70:73], v[182:185], v[110:113]
	v_mfma_f32_16x16x32_bf16 v[98:101], v[62:65], v[190:193], v[98:101]
	v_mfma_f32_16x16x32_bf16 v[94:97], v[70:73], v[190:193], v[94:97]
	v_mfma_f32_16x16x32_bf16 v[146:149], v[66:69], v[170:173], v[146:149]
	v_mfma_f32_16x16x32_bf16 v[142:145], v[74:77], v[170:173], v[142:145]
	v_mfma_f32_16x16x32_bf16 v[130:133], v[66:69], v[178:181], v[130:133]
	v_mfma_f32_16x16x32_bf16 v[126:129], v[74:77], v[178:181], v[126:129]
	v_mfma_f32_16x16x32_bf16 v[114:117], v[66:69], v[186:189], v[114:117]
	v_mfma_f32_16x16x32_bf16 v[110:113], v[74:77], v[186:189], v[110:113]
	v_mfma_f32_16x16x32_bf16 v[98:101], v[66:69], v[204:207], v[98:101]
	v_mfma_f32_16x16x32_bf16 v[94:97], v[74:77], v[204:207], v[94:97]
	s_nop 0
	s_nop 0
	v_mfma_f32_16x16x32_bf16 v[138:141], v[150:153], v[166:169], v[138:141]
	v_mfma_f32_16x16x32_bf16 v[134:137], v[158:161], v[166:169], v[134:137]
	v_mfma_f32_16x16x32_bf16 v[122:125], v[150:153], v[174:177], v[122:125]
	v_mfma_f32_16x16x32_bf16 v[118:121], v[158:161], v[174:177], v[118:121]
	v_mfma_f32_16x16x32_bf16 v[106:109], v[150:153], v[182:185], v[106:109]
	v_mfma_f32_16x16x32_bf16 v[102:105], v[158:161], v[182:185], v[102:105]
	v_mfma_f32_16x16x32_bf16 v[90:93], v[150:153], v[190:193], v[90:93]
	v_mfma_f32_16x16x32_bf16 v[86:89], v[158:161], v[190:193], v[86:89]
	v_mfma_f32_16x16x32_bf16 v[138:141], v[154:157], v[170:173], v[138:141]
	v_mfma_f32_16x16x32_bf16 v[134:137], v[162:165], v[170:173], v[134:137]
	v_mfma_f32_16x16x32_bf16 v[122:125], v[154:157], v[178:181], v[122:125]
	v_mfma_f32_16x16x32_bf16 v[118:121], v[162:165], v[178:181], v[118:121]
	v_mfma_f32_16x16x32_bf16 v[106:109], v[154:157], v[186:189], v[106:109]
	v_mfma_f32_16x16x32_bf16 v[102:105], v[162:165], v[186:189], v[102:105]
	v_mfma_f32_16x16x32_bf16 v[90:93], v[154:157], v[204:207], v[90:93]
	v_mfma_f32_16x16x32_bf16 v[86:89], v[162:165], v[204:207], v[86:89]
	s_nop 0
	s_barrier
; __device__ __forceinline__ int opaque_tid(int wave_s) { int l; asm volatile("v_mbcnt_lo_u32_b32 %0, -1, 0\n\tv_mbcnt_hi_u32_b32 %0, -1, %0" : "=v"(l)); return (wave_s << 6) | l; }
; #define PG8_STAGE(bufoff, gbase, voff) do { _Pragma("unroll") for (int _i = 0; _i < 2; ++_i) \
;         __builtin_amdgcn_global_load_lds((const unsigned*)((const char*)(gbase) + (voff)[_i]), (PG8_LAS unsigned*)(lds + (bufoff) + ldsw + _i * 8192), 16, 0, 0); } while (0)
; #define PG8_WAIT_V(n) asm volatile("s_waitcnt vmcnt(" #n ")" ::: "memory")
; template <class Epi, class Sched, bool ALIGN_EPI = false, bool SP2 = false>
; __device__ __forceinline__ void gemm_phase(PG8_LAS unsigned char* lds, const Gemm g, const Sched& S, const Epi& E, const int wave_s) {
;     ...
;         for (int t = 0; t < nt; t += 2) {
;             if constexpr (Epi::KHOOK) { if (t == 6 || t == 12) { const int l3_ = opaque_tid(wave_s) & 63; E.khook(acc, t, wr, l3_ & 15, ui & 1, lds); } }
;             const bool last = (t == nt - 2);
;             const char* a1 = cA + (size_t)(t + 1) * kstep;
;             const char* a2 = last ? nA : cA + (size_t)(t + 2) * kstep; const char* b2 = last ? nB : cB + (size_t)(t + 2) * kstep;
;             const char* a3 = a2 + kstep; const char* b3 = b2 + kstep;
;             if (last && has_next) S.a_ready(nxt);
;             if constexpr (SP2) {
;             PG8_LDB(B0, 0, 0); PG8_LDB(B1, 0, 1); PG8_SCHED; PG8_LDA(At, 0, 0); PG8_STAGE(PG8_SA(1, 1), a1 + hstepA, voffA);
;             PG8_WAIT_V(8); PG8_WAIT_L(0); PG8_BAR; PG8_MMA(0, 0, At, B0); PG8_MMA(0, 1, At, B1); PG8_BAR; PG8_SCHED;
;             PG8_LDA(At, 0, 1); PG8_STAGE(PG8_SB(0, 0), b2, voffB); PG8_STAGE(PG8_SB(0, 1), b2 + hstepB, voffB); PG8_STAGE(PG8_SA(0, 0), a2, voffA);
;             PG8_WAIT_V(8); PG8_WAIT_L(0); PG8_BAR; PG8_MMA(1, 0, At, B0); PG8_MMA(1, 1, At, B1); PG8_BAR; PG8_SCHED;
;             PG8_LDB(B0, 1, 0); PG8_LDB(B1, 1, 1); PG8_SCHED; PG8_LDA(At, 1, 0); PG8_STAGE(PG8_SA(0, 1), a2 + hstepA, voffA);
;             PG8_WAIT_V(8); PG8_WAIT_L(0); PG8_BAR; PG8_MMA(0, 0, At, B0); PG8_MMA(0, 1, At, B1); PG8_BAR; PG8_SCHED;
;             PG8_LDA(At, 1, 1); PG8_STAGE(PG8_SB(1, 0), b3, voffB); PG8_STAGE(PG8_SB(1, 1), b3 + hstepB, voffB); PG8_STAGE(PG8_SA(1, 0), a3, voffA);
;             PG8_WAIT_V(8); PG8_WAIT_L(0); PG8_BAR; PG8_MMA(1, 0, At, B0); PG8_MMA(1, 1, At, B1); PG8_BAR; PG8_SCHED;
	s_add_i32 s10, s55, s37
	v_lshl_add_u64 v[208:209], v[208:209], 0, s[58:59]
	s_mov_b32 m0, s10
	ds_read_b128 v[166:169], v216 offset:49152
	ds_read_b128 v[170:173], v216 offset:50176
	ds_read_b128 v[174:177], v216 offset:51200
	ds_read_b128 v[178:181], v216 offset:52224
	ds_read_b128 v[182:185], v216 offset:53248
	ds_read_b128 v[186:189], v216 offset:54272
	ds_read_b128 v[190:193], v216 offset:55296
	ds_read_b128 v[204:207], v216 offset:56320
	global_load_lds_dwordx4 v[208:209], off
	s_add_i32 m0, s10, 0x2000
	s_add_u32 s4, s4, 0xb0080
	v_lshl_add_u64 v[208:209], v[210:211], 0, s[58:59]
	s_addc_u32 s5, s5, 0
	s_add_i32 s10, s56, s37
	global_load_lds_dwordx4 v[208:209], off
	v_lshl_add_u64 v[208:209], s[4:5], 0, v[194:195]
	s_mov_b32 m0, s10
	s_nop 0
	global_load_lds_dwordx4 v[208:209], off
	v_lshl_add_u64 v[208:209], s[4:5], 0, v[198:199]
	s_add_i32 m0, s10, 0x2000
	s_nop 0
	global_load_lds_dwordx4 v[208:209], off
	v_lshl_add_u64 v[208:209], v[212:213], 0, v[248:249]
	s_mov_b32 m0, s80
	s_nop 0
	global_load_lds_dwordx4 v[208:209], off
	v_lshl_add_u64 v[208:209], v[214:215], 0, v[248:249]
	s_mov_b32 m0, s81
	s_nop 0
	global_load_lds_dwordx4 v[208:209], off
	s_waitcnt vmcnt(8)
	s_waitcnt lgkmcnt(0)
	s_barrier
	s_nop 0
	s_waitcnt lgkmcnt(0)
	v_mfma_f32_16x16x32_bf16 v[82:85], v[62:65], v[166:169], v[82:85]
	v_mfma_f32_16x16x32_bf16 v[78:81], v[70:73], v[166:169], v[78:81]
	v_mfma_f32_16x16x32_bf16 v[50:53], v[62:65], v[174:177], v[50:53]
	v_mfma_f32_16x16x32_bf16 v[46:49], v[70:73], v[174:177], v[46:49]
	v_mfma_f32_16x16x32_bf16 v[34:37], v[62:65], v[182:185], v[34:37]
	v_mfma_f32_16x16x32_bf16 v[30:33], v[70:73], v[182:185], v[30:33]
	v_mfma_f32_16x16x32_bf16 v[18:21], v[62:65], v[190:193], v[18:21]
	v_mfma_f32_16x16x32_bf16 v[10:13], v[70:73], v[190:193], v[10:13]
	v_mfma_f32_16x16x32_bf16 v[82:85], v[66:69], v[170:173], v[82:85]
	v_mfma_f32_16x16x32_bf16 v[78:81], v[74:77], v[170:173], v[78:81]
	v_mfma_f32_16x16x32_bf16 v[50:53], v[66:69], v[178:181], v[50:53]
	v_mfma_f32_16x16x32_bf16 v[46:49], v[74:77], v[178:181], v[46:49]
	v_mfma_f32_16x16x32_bf16 v[34:37], v[66:69], v[186:189], v[34:37]
	v_mfma_f32_16x16x32_bf16 v[30:33], v[74:77], v[186:189], v[30:33]
	v_mfma_f32_16x16x32_bf16 v[18:21], v[66:69], v[204:207], v[18:21]
	v_mfma_f32_16x16x32_bf16 v[10:13], v[74:77], v[204:207], v[10:13]
	s_nop 0
	s_nop 0
	v_mfma_f32_16x16x32_bf16 v[58:61], v[150:153], v[166:169], v[58:61]
	v_mfma_f32_16x16x32_bf16 v[54:57], v[158:161], v[166:169], v[54:57]
	v_mfma_f32_16x16x32_bf16 v[42:45], v[150:153], v[174:177], v[42:45]
	v_mfma_f32_16x16x32_bf16 v[38:41], v[158:161], v[174:177], v[38:41]
	v_mfma_f32_16x16x32_bf16 v[26:29], v[150:153], v[182:185], v[26:29]
	v_mfma_f32_16x16x32_bf16 v[22:25], v[158:161], v[182:185], v[22:25]
	v_mfma_f32_16x16x32_bf16 v[6:9], v[150:153], v[190:193], v[6:9]
	v_mfma_f32_16x16x32_bf16 v[2:5], v[158:161], v[190:193], v[2:5]
	v_mfma_f32_16x16x32_bf16 v[58:61], v[154:157], v[170:173], v[58:61]
	v_mfma_f32_16x16x32_bf16 v[54:57], v[162:165], v[170:173], v[54:57]
	v_mfma_f32_16x16x32_bf16 v[42:45], v[154:157], v[178:181], v[42:45]
	v_mfma_f32_16x16x32_bf16 v[38:41], v[162:165], v[178:181], v[38:41]
	v_mfma_f32_16x16x32_bf16 v[26:29], v[154:157], v[186:189], v[26:29]
	v_mfma_f32_16x16x32_bf16 v[22:25], v[162:165], v[186:189], v[22:25]
	v_mfma_f32_16x16x32_bf16 v[6:9], v[154:157], v[204:207], v[6:9]
	v_mfma_f32_16x16x32_bf16 v[2:5], v[162:165], v[204:207], v[2:5]
	s_nop 0
	s_barrier
	s_add_i32 s54, s54, 2
	s_add_u32 s2, s2, 0x100
	s_addc_u32 s3, s3, 0
	s_cmp_gt_u32 s54, 41
	s_mov_b64 s[10:11], s[8:9]
	s_cbranch_scc0 .LBB0_1243
	s_and_b64 vcc, exec, s[24:25]
	s_cbranch_vccz .LBB0_1246
	s_barrier
